# NSA selected/window walks: fp8 V fragments also stored as 16-byte fragment pairs (projection epilogue byte stores re-addressed) and fetched with 4 global_load_dwordx4 per step; 8 loads per fragment se
# speedup vs baseline: 1.0716x; 1.0194x over previous
; #define PG8_STAGE(bufoff, gbase, voff) do { _Pragma("unroll") for (int _i = 0; _i < 2; ++_i) \
;         __builtin_amdgcn_global_load_lds((const unsigned*)((const char*)(gbase) + (voff)[_i]), (LAS unsigned*)(lds + (bufoff) + ldsw + _i * 8192), 16, 0, 0); } while (0)
; #define PG8_WAIT_V(n) asm volatile("s_waitcnt vmcnt(" #n ")" ::: "memory")
; #define PG8_BAR __builtin_amdgcn_s_barrier()
; template <class Epi, bool FP8 = false>
; __device__ __forceinline__ void gemm_phase(LAS unsigned char* lds, const Gemm g, const StaticOrder& S_, const Epi& E, const int tid) {
;     ...
;     PG8_STAGE(PG8_SB(0, 0), cB, voffB); PG8_STAGE(PG8_SB(0, 1), cB + hstepB, voffB); PG8_STAGE(PG8_SA(0, 0), cA, voffA); PG8_STAGE(PG8_SA(0, 1), cA + hstepA, voffA);
;     if (wr == 1) PG8_BAR;
;     PG8_WAIT_V(2); PG8_BAR;
;     PG8_STAGE(PG8_SB(1, 0), cB + kstep, voffB); PG8_STAGE(PG8_SA(1, 0), cA + kstep, voffA); PG8_STAGE(PG8_SB(1, 1), cB + hstepB + kstep, voffB);
;     PG8_WAIT_V(6); PG8_BAR;
;     __device__ __forceinline__ void operator()(const pg8::Acc& acc, const pg8::Unit& u, int wr, int wc, int fr, int fq) const {
;         const int pn = u.pn, row0 = u.pm * 256 + wr * 64 + fr, cw = wc * 32 + 8 * fq;
;         if (pn < 2) {
;             unsigned char* VF = (unsigned char*)kslf + (pn == 0 ? (size_t)8 << 20 : (size_t)24 << 20);
; #pragma unroll
;             for (int ai = 0; ai < 2; ++ai)
; #pragma unroll
;                 for (int m = 0; m < 4; ++m) {
;                     const int row = row0 + ai * 128 + m * 16, kp = row & 31;
;                     const size_t rbase = (size_t)(row >> 5) * 4096 + (size_t)(((kp >> 2) & 3) * 16) * 8 + 4 * (kp >> 4) + (kp & 3);
; #pragma unroll
;                     for (int bj = 0; bj < 2; ++bj) {
;                         const u32x2 w = pack8_fp8(acc[ai][bj][m][0], acc[ai][bj][m][1]);
;                         unsigned char* vb = VF + (size_t)bj * 512 * 4096 + rbase + (size_t)(cw >> 4) * 512 + (size_t)(cw & 15) * 8;
.LBB0_590:
	s_lshl_b32 s10, s10, 5
	s_lshl_b32 s71, s11, 6
	s_lshl_b32 s16, s11, 13
	s_and_b32 s17, s10, 0x60
	s_mov_b64 s[10:11], 0x80
	s_add_i32 m0, s63, 0x18000
	v_lshl_add_u64 v[6:7], v[6:7], 0, s[10:11]
	s_lshl_b32 s18, s17, 7
	s_waitcnt vmcnt(2)
	s_barrier
	global_load_lds_dwordx4 v[6:7], off
	v_lshl_add_u64 v[4:5], v[4:5], 0, s[10:11]
	s_add_i32 m0, s63, 0x1a000
	s_add_i32 s72, s63, 0x8000
	s_add_i32 s73, s63, 0xa000
	global_load_lds_dwordx4 v[4:5], off
	v_lshl_add_u64 v[0:1], v[0:1], 0, s[10:11]
	s_mov_b32 m0, s72
	s_add_u32 s14, s54, 0x40080
	global_load_lds_dwordx4 v[0:1], off
	v_lshl_add_u64 v[0:1], v[2:3], 0, s[10:11]
	s_mov_b32 m0, s73
	s_addc_u32 s15, s55, 0
	global_load_lds_dwordx4 v[0:1], off
	s_add_i32 m0, s63, 0x1c000
	v_lshl_add_u64 v[0:1], s[14:15], 0, v[160:161]
	global_load_lds_dwordx4 v[0:1], off
	v_lshl_add_u64 v[0:1], s[14:15], 0, v[162:163]
	s_add_i32 m0, s63, 0x1e000
	v_and_b32_e32 v194, 15, v9
	global_load_lds_dwordx4 v[0:1], off
	v_bfe_u32 v0, v9, 4, 2
	v_lshlrev_b32_e32 v1, 3, v0
	v_lshlrev_b32_e32 v0, 4, v0
	v_lshlrev_b32_e32 v2, 2, v9
	v_lshl_or_b32 v0, v194, 6, v0
	v_and_b32_e32 v3, 32, v2
	v_bitop3_b32 v4, v0, s16, v3 bitop3:0xde
	v_bitop3_b32 v195, s18, v0, v3 bitop3:0xf6
	v_or_b32_e32 v0, s17, v1
	v_and_b32_e32 v196, 8, v1
	v_lshlrev_b32_e32 v1, 5, v0
	v_and_b32_e32 v170, 0xe00, v1
	v_lshlrev_b32_e32 v1, 5, v9
	v_mov_b32_e32 v169, 0
	v_and_b32_e32 v168, 0x180, v1
	v_lshlrev_b32_e32 v1, 14, v13
	v_and_b32_e32 v174, 64, v2
	v_and_b32_e32 v242, 0xc00, v170
	v_lshrrev_b32_e32 v243, 6, v170
	v_and_b32_e32 v243, 8, v243
	v_or_b32_e32 v242, v242, v243
	v_add_u32_e32 v242, v242, v168
	v_mov_b32_e32 v243, 0
	v_lshlrev_b32_e32 v244, 1, v174
	v_mov_b32_e32 v245, 0
	v_lshl_add_u64 v[2:3], s[4:5], 0, v[168:169]
	s_mov_b64 s[14:15], 0x1a000000
	v_and_b32_e32 v1, 0xffff8000, v1
	v_lshl_add_u64 v[176:177], v[2:3], 0, s[14:15]
	v_lshl_add_u32 v1, v12, 11, v1
	v_and_b32_e32 v2, 1, v13
	v_lshl_or_b32 v1, v2, 6, v1
	v_lshl_add_u32 v178, v14, 1, v1
	v_lshlrev_b32_e32 v1, 14, v8
	s_cmpk_lt_u32 s13, 0x100
	v_and_b32_e32 v1, 0xffff8000, v1
	s_sext_i32_i16 s83, s12
	s_waitcnt vmcnt(6)
	s_cselect_b64 s[12:13], -1, 0
	s_add_u32 s14, s4, 0x15800000
	v_lshl_add_u32 v1, v10, 11, v1
	v_and_b32_e32 v2, 1, v8
	s_addc_u32 s15, s5, 0
	v_lshl_or_b32 v1, v2, 6, v1
	s_add_i32 s74, 0, 0x10000
	s_add_i32 s75, 0, 0x14000
	v_mov_b32_e32 v171, v169
	v_and_b32_e32 v172, 3, v9
	v_mov_b32_e32 v173, v169
	v_mov_b32_e32 v175, v169
	v_mov_b32_e32 v179, v169
	v_lshl_add_u32 v180, v11, 1, v1
	v_mov_b32_e32 v181, v169
	v_mov_b64_e32 v[182:183], 0x600
	v_mov_b64_e32 v[184:185], 0x5ff
	v_add_u32_e32 v197, s74, v195
	v_add_u32_e32 v198, s75, v195
	v_add_u32_e32 v199, 0, v4
	v_lshlrev_b32_e32 v168, 1, v0
	s_mov_b64 s[16:17], 0x100000
	s_mov_b32 s76, 0x100000
	s_mov_b64 s[18:19], 0x120000
	s_mov_b32 s77, 0x120000
	s_mov_b64 s[20:21], 0x140000
	s_mov_b32 s78, 0x140000
	s_mov_b64 s[22:23], 0x160000
	s_mov_b32 s79, 0x160000
	s_mov_b32 s80, 0x800000
	s_mov_b32 s81, 0x200000
	s_mov_b32 s82, 0
	s_barrier
	s_branch .LBB0_593

;     __device__ __forceinline__ void operator()(const pg8::Acc& acc, const pg8::Unit& u, int wr, int wc, int fr, int fq) const {
;     ...
;             unsigned char* VF = (unsigned char*)kslf + (pn == 0 ? (size_t)8 << 20 : (size_t)24 << 20);
; #pragma unroll
;             for (int ai = 0; ai < 2; ++ai)
; #pragma unroll
;                 for (int m = 0; m < 4; ++m) {
;                     const int row = row0 + ai * 128 + m * 16, kp = row & 31;
;                     const size_t rbase = (size_t)(row >> 5) * 4096 + (size_t)(((kp >> 2) & 3) * 16) * 8 + 4 * (kp >> 4) + (kp & 3);
; #pragma unroll
;                     for (int bj = 0; bj < 2; ++bj) {
;                         const u32x2 w = pack8_fp8(acc[ai][bj][m][0], acc[ai][bj][m][1]);
;                         unsigned char* vb = VF + (size_t)bj * 512 * 4096 + rbase + (size_t)(cw >> 4) * 512 + (size_t)(cw & 15) * 8;
;                         vb[0] = (unsigned char)(w.x & 0xffu); vb[8] = (unsigned char)((w.x >> 8) & 0xffu); vb[16] = (unsigned char)((w.x >> 16) & 0xffu); vb[24] = (unsigned char)(w.x >> 24);
;                         vb[32] = (unsigned char)(w.y & 0xffu); vb[40] = (unsigned char)((w.y >> 8) & 0xffu); vb[48] = (unsigned char)((w.y >> 16) & 0xffu); vb[56] = (unsigned char)(w.y >> 24);
;                     }
.LBB0_607:
	s_cmp_eq_u32 s83, 0
	s_cselect_b32 s6, s80, 0x1800000
	s_ashr_i32 s52, s25, 5
	s_ashr_i32 s53, s52, 31
	v_lshl_add_u64 v[128:129], v[176:177], 0, s[6:7]
	s_lshl_b64 s[42:43], s[52:53], 12
	v_mov_b32_e32 v132, 0
	v_lshl_add_u64 v[130:131], v[128:129], 0, s[42:43]
	v_cvt_pk_fp8_f32 v132, v124, v125
	v_lshl_add_u64 v[124:125], v[130:131], 0, v[172:173]
	v_mov_b32_e32 v130, 0
	v_cvt_pk_fp8_f32 v130, v120, v121
	v_cvt_pk_fp8_f32 v132, v126, v127 op_sel:[0,0,1]
	v_lshl_add_u64 v[120:121], v[124:125], 0, v[242:243]
	v_lshl_add_u64 v[120:121], v[120:121], 0, v[244:245]
	v_cvt_pk_fp8_f32 v130, v122, v123 op_sel:[0,0,1]
	v_lshrrev_b32_e32 v122, 8, v132
	global_store_byte v[120:121], v132, off
	global_store_byte v[120:121], v122, off offset:16
	global_store_byte_d16_hi v[120:121], v132, off offset:32
	v_lshrrev_b32_e32 v122, 24, v132
	global_store_byte v[120:121], v122, off offset:48
	global_store_byte v[120:121], v130, off offset:64
	v_lshrrev_b32_e32 v122, 8, v130
	global_store_byte v[120:121], v122, off offset:80
	global_store_byte_d16_hi v[120:121], v130, off offset:96
	v_mov_b32_e32 v122, 0
	v_cvt_pk_fp8_f32 v122, v116, v117
	v_mov_b32_e32 v116, 0
	v_cvt_pk_fp8_f32 v116, v108, v109
	v_lshrrev_b32_e32 v108, 24, v130
	v_cvt_pk_fp8_f32 v122, v118, v119 op_sel:[0,0,1]
	global_store_byte v[120:121], v108, off offset:112
	v_cvt_pk_fp8_f32 v116, v110, v111 op_sel:[0,0,1]
	v_add_co_u32_e32 v108, vcc, s81, v120
	v_lshrrev_b32_e32 v110, 8, v122
	s_nop 0
	v_addc_co_u32_e32 v109, vcc, 0, v121, vcc
	global_store_byte v[108:109], v122, off
	global_store_byte v[108:109], v110, off offset:16
	global_store_byte_d16_hi v[108:109], v122, off offset:32
	v_lshrrev_b32_e32 v110, 24, v122
	global_store_byte v[108:109], v110, off offset:48
	global_store_byte v[108:109], v116, off offset:64
	v_lshrrev_b32_e32 v110, 8, v116
	global_store_byte v[108:109], v110, off offset:80
	v_mov_b32_e32 v110, 0
	v_cvt_pk_fp8_f32 v110, v112, v113
	v_mov_b32_e32 v111, 0
	v_cvt_pk_fp8_f32 v111, v104, v105
	v_lshrrev_b32_e32 v104, 24, v116
	v_cvt_pk_fp8_f32 v110, v114, v115 op_sel:[0,0,1]
	global_store_byte v[108:109], v104, off offset:112
	v_cvt_pk_fp8_f32 v111, v106, v107 op_sel:[0,0,1]
	global_store_byte_d16_hi v[108:109], v116, off offset:96
	v_lshrrev_b32_e32 v104, 8, v110
	global_store_byte v[120:121], v110, off offset:4
	global_store_byte v[120:121], v104, off offset:20
	global_store_byte_d16_hi v[120:121], v110, off offset:36
	v_lshrrev_b32_e32 v104, 24, v110
	global_store_byte v[120:121], v104, off offset:52
	global_store_byte v[120:121], v111, off offset:68
	v_lshrrev_b32_e32 v104, 8, v111
	global_store_byte v[120:121], v104, off offset:84
	v_mov_b32_e32 v104, 0
	v_cvt_pk_fp8_f32 v104, v100, v101
	v_mov_b32_e32 v100, 0
	v_cvt_pk_fp8_f32 v100, v92, v93
	v_lshrrev_b32_e32 v92, 24, v111
	v_cvt_pk_fp8_f32 v104, v102, v103 op_sel:[0,0,1]
	global_store_byte v[120:121], v92, off offset:116
	v_cvt_pk_fp8_f32 v100, v94, v95 op_sel:[0,0,1]
	v_mov_b32_e32 v94, 0
	v_cvt_pk_fp8_f32 v94, v96, v97
	v_lshrrev_b32_e32 v92, 8, v104
	v_mov_b32_e32 v95, 0
	global_store_byte_d16_hi v[120:121], v111, off offset:100
	global_store_byte v[108:109], v104, off offset:4
	global_store_byte v[108:109], v92, off offset:20
	global_store_byte_d16_hi v[108:109], v104, off offset:36
	v_lshrrev_b32_e32 v92, 24, v104
	s_or_b32 s42, s52, 1
	v_cvt_pk_fp8_f32 v95, v88, v89
	global_store_byte v[108:109], v92, off offset:52
	global_store_byte v[108:109], v100, off offset:68
	v_lshrrev_b32_e32 v92, 8, v100
	s_ashr_i32 s43, s42, 31
	global_store_byte v[108:109], v92, off offset:84
	global_store_byte_d16_hi v[108:109], v100, off offset:100
	v_lshrrev_b32_e32 v92, 24, v100
	s_lshl_b64 s[42:43], s[42:43], 12
	v_cvt_pk_fp8_f32 v94, v98, v99 op_sel:[0,0,1]
	global_store_byte v[108:109], v92, off offset:116
	v_lshl_add_u64 v[92:93], v[128:129], 0, s[42:43]
	v_lshl_add_u64 v[92:93], v[92:93], 0, v[172:173]
	v_cvt_pk_fp8_f32 v95, v90, v91 op_sel:[0,0,1]
	v_lshl_add_u64 v[88:89], v[92:93], 0, v[242:243]
	v_lshl_add_u64 v[88:89], v[88:89], 0, v[244:245]
	v_lshrrev_b32_e32 v90, 8, v94
	global_store_byte v[88:89], v94, off
	global_store_byte v[88:89], v90, off offset:16
	global_store_byte_d16_hi v[88:89], v94, off offset:32
	v_lshrrev_b32_e32 v90, 24, v94
	global_store_byte v[88:89], v90, off offset:48
	global_store_byte v[88:89], v95, off offset:64
	v_lshrrev_b32_e32 v90, 8, v95
	global_store_byte v[88:89], v90, off offset:80
	global_store_byte_d16_hi v[88:89], v95, off offset:96
	v_mov_b32_e32 v90, 0
	v_cvt_pk_fp8_f32 v90, v80, v81
	v_mov_b32_e32 v80, 0
	v_cvt_pk_fp8_f32 v80, v76, v77
	v_lshrrev_b32_e32 v76, 24, v95
	v_cvt_pk_fp8_f32 v90, v82, v83 op_sel:[0,0,1]
	global_store_byte v[88:89], v76, off offset:112
	v_cvt_pk_fp8_f32 v80, v78, v79 op_sel:[0,0,1]
	v_add_co_u32_e32 v76, vcc, s81, v88
	v_lshrrev_b32_e32 v78, 8, v90
	s_nop 0
	v_addc_co_u32_e32 v77, vcc, 0, v89, vcc
	global_store_byte v[76:77], v90, off
	global_store_byte v[76:77], v78, off offset:16
	global_store_byte_d16_hi v[76:77], v90, off offset:32
	v_lshrrev_b32_e32 v78, 24, v90
	global_store_byte v[76:77], v78, off offset:48
	global_store_byte v[76:77], v80, off offset:64
	v_lshrrev_b32_e32 v78, 8, v80
	global_store_byte v[76:77], v78, off offset:80
	v_mov_b32_e32 v78, 0
	v_cvt_pk_fp8_f32 v78, v84, v85
	v_mov_b32_e32 v79, 0
	v_cvt_pk_fp8_f32 v79, v72, v73
	v_lshrrev_b32_e32 v72, 24, v80
	v_cvt_pk_fp8_f32 v78, v86, v87 op_sel:[0,0,1]
	global_store_byte v[76:77], v72, off offset:112
	v_cvt_pk_fp8_f32 v79, v74, v75 op_sel:[0,0,1]
	global_store_byte_d16_hi v[76:77], v80, off offset:96
	v_lshrrev_b32_e32 v72, 8, v78
	global_store_byte v[88:89], v78, off offset:4
;     __device__ __forceinline__ void operator()(const pg8::Acc& acc, const pg8::Unit& u, int wr, int wc, int fr, int fq) const {
;     ...
;             unsigned char* VF = (unsigned char*)kslf + (pn == 0 ? (size_t)8 << 20 : (size_t)24 << 20);
; #pragma unroll
;             for (int ai = 0; ai < 2; ++ai)
; #pragma unroll
;                 for (int m = 0; m < 4; ++m) {
;                     const int row = row0 + ai * 128 + m * 16, kp = row & 31;
;                     const size_t rbase = (size_t)(row >> 5) * 4096 + (size_t)(((kp >> 2) & 3) * 16) * 8 + 4 * (kp >> 4) + (kp & 3);
; #pragma unroll
;                     for (int bj = 0; bj < 2; ++bj) {
;                         const u32x2 w = pack8_fp8(acc[ai][bj][m][0], acc[ai][bj][m][1]);
;                         unsigned char* vb = VF + (size_t)bj * 512 * 4096 + rbase + (size_t)(cw >> 4) * 512 + (size_t)(cw & 15) * 8;
;                         vb[0] = (unsigned char)(w.x & 0xffu); vb[8] = (unsigned char)((w.x >> 8) & 0xffu); vb[16] = (unsigned char)((w.x >> 16) & 0xffu); vb[24] = (unsigned char)(w.x >> 24);
;                         vb[32] = (unsigned char)(w.y & 0xffu); vb[40] = (unsigned char)((w.y >> 8) & 0xffu); vb[48] = (unsigned char)((w.y >> 16) & 0xffu); vb[56] = (unsigned char)(w.y >> 24);
;                     }
	global_store_byte v[88:89], v72, off offset:20
	global_store_byte_d16_hi v[88:89], v78, off offset:36
	v_lshrrev_b32_e32 v72, 24, v78
	global_store_byte v[88:89], v72, off offset:52
	global_store_byte v[88:89], v79, off offset:68
	v_lshrrev_b32_e32 v72, 8, v79
	global_store_byte v[88:89], v72, off offset:84
	v_mov_b32_e32 v72, 0
	v_cvt_pk_fp8_f32 v72, v68, v69
	v_mov_b32_e32 v68, 0
	v_cvt_pk_fp8_f32 v68, v64, v65
	v_lshrrev_b32_e32 v64, 24, v79
	v_cvt_pk_fp8_f32 v72, v70, v71 op_sel:[0,0,1]
	global_store_byte v[88:89], v64, off offset:116
	v_cvt_pk_fp8_f32 v68, v66, v67 op_sel:[0,0,1]
	s_add_i32 s6, s25, 0x80
	v_lshrrev_b32_e32 v64, 8, v72
	global_store_byte_d16_hi v[88:89], v79, off offset:100
	global_store_byte v[76:77], v72, off offset:4
	global_store_byte v[76:77], v64, off offset:20
	global_store_byte_d16_hi v[76:77], v72, off offset:36
	v_lshrrev_b32_e32 v64, 24, v72
	s_ashr_i32 s42, s6, 5
	global_store_byte v[76:77], v64, off offset:52
	global_store_byte v[76:77], v68, off offset:68
	v_lshrrev_b32_e32 v64, 8, v68
	s_ashr_i32 s43, s42, 31
	global_store_byte v[76:77], v64, off offset:84
	global_store_byte_d16_hi v[76:77], v68, off offset:100
	v_lshrrev_b32_e32 v64, 24, v68
	s_lshl_b64 s[42:43], s[42:43], 12
	v_mov_b32_e32 v66, 0
	global_store_byte v[76:77], v64, off offset:116
	v_lshl_add_u64 v[64:65], v[128:129], 0, s[42:43]
	v_cvt_pk_fp8_f32 v66, v60, v61
	v_lshl_add_u64 v[60:61], v[64:65], 0, v[172:173]
	v_mov_b32_e32 v64, 0
	v_cvt_pk_fp8_f32 v64, v56, v57
	v_cvt_pk_fp8_f32 v66, v62, v63 op_sel:[0,0,1]
	v_lshl_add_u64 v[56:57], v[60:61], 0, v[242:243]
	v_lshl_add_u64 v[56:57], v[56:57], 0, v[244:245]
	v_cvt_pk_fp8_f32 v64, v58, v59 op_sel:[0,0,1]
	v_lshrrev_b32_e32 v58, 8, v66
	global_store_byte v[56:57], v66, off
	global_store_byte v[56:57], v58, off offset:16
	global_store_byte_d16_hi v[56:57], v66, off offset:32
	v_lshrrev_b32_e32 v58, 24, v66
	global_store_byte v[56:57], v58, off offset:48
	global_store_byte v[56:57], v64, off offset:64
	v_lshrrev_b32_e32 v58, 8, v64
	global_store_byte v[56:57], v58, off offset:80
	global_store_byte_d16_hi v[56:57], v64, off offset:96
	v_mov_b32_e32 v58, 0
	v_cvt_pk_fp8_f32 v58, v52, v53
	v_mov_b32_e32 v52, 0
	v_cvt_pk_fp8_f32 v52, v44, v45
	v_lshrrev_b32_e32 v44, 24, v64
	v_cvt_pk_fp8_f32 v58, v54, v55 op_sel:[0,0,1]
	global_store_byte v[56:57], v44, off offset:112
	v_cvt_pk_fp8_f32 v52, v46, v47 op_sel:[0,0,1]
	v_add_co_u32_e32 v44, vcc, s81, v56
	v_lshrrev_b32_e32 v46, 8, v58
	s_nop 0
	v_addc_co_u32_e32 v45, vcc, 0, v57, vcc
	global_store_byte v[44:45], v58, off
	global_store_byte v[44:45], v46, off offset:16
	global_store_byte_d16_hi v[44:45], v58, off offset:32
	v_lshrrev_b32_e32 v46, 24, v58
	global_store_byte v[44:45], v46, off offset:48
	global_store_byte v[44:45], v52, off offset:64
	v_lshrrev_b32_e32 v46, 8, v52
	global_store_byte v[44:45], v46, off offset:80
	global_store_byte_d16_hi v[44:45], v52, off offset:96
	v_lshrrev_b32_e32 v46, 24, v52
	global_store_byte v[44:45], v46, off offset:112
	v_mov_b32_e32 v46, 0
	v_cvt_pk_fp8_f32 v46, v48, v49
	s_add_i32 s6, s25, 0x90
	v_mov_b32_e32 v47, 0
	s_ashr_i32 s42, s6, 5
	v_cvt_pk_fp8_f32 v47, v40, v41
	s_ashr_i32 s43, s42, 31
	s_lshl_b64 s[42:43], s[42:43], 12
	v_cvt_pk_fp8_f32 v46, v50, v51 op_sel:[0,0,1]
	v_lshl_add_u64 v[44:45], v[128:129], 0, s[42:43]
	v_lshl_add_u64 v[44:45], v[44:45], 0, v[172:173]
	v_cvt_pk_fp8_f32 v47, v42, v43 op_sel:[0,0,1]
	v_lshl_add_u64 v[40:41], v[44:45], 0, v[242:243]
	v_lshl_add_u64 v[40:41], v[40:41], 0, v[244:245]
	v_lshrrev_b32_e32 v42, 8, v46
	global_store_byte v[40:41], v46, off offset:4
	global_store_byte v[40:41], v42, off offset:20
	global_store_byte_d16_hi v[40:41], v46, off offset:36
	v_lshrrev_b32_e32 v42, 24, v46
	global_store_byte v[40:41], v42, off offset:52
	global_store_byte v[40:41], v47, off offset:68
	v_lshrrev_b32_e32 v42, 8, v47
	global_store_byte v[40:41], v42, off offset:84
	global_store_byte_d16_hi v[40:41], v47, off offset:100
	v_mov_b32_e32 v42, 0
	v_cvt_pk_fp8_f32 v42, v36, v37
	v_mov_b32_e32 v36, 0
	v_cvt_pk_fp8_f32 v36, v28, v29
	v_lshrrev_b32_e32 v28, 24, v47
	v_cvt_pk_fp8_f32 v42, v38, v39 op_sel:[0,0,1]
	global_store_byte v[40:41], v28, off offset:116
	v_cvt_pk_fp8_f32 v36, v30, v31 op_sel:[0,0,1]
	v_add_co_u32_e32 v28, vcc, s81, v40
;     __device__ __forceinline__ void operator()(const pg8::Acc& acc, const pg8::Unit& u, int wr, int wc, int fr, int fq) const {
;     ...
;             unsigned char* VF = (unsigned char*)kslf + (pn == 0 ? (size_t)8 << 20 : (size_t)24 << 20);
; #pragma unroll
;             for (int ai = 0; ai < 2; ++ai)
; #pragma unroll
;                 for (int m = 0; m < 4; ++m) {
;                     const int row = row0 + ai * 128 + m * 16, kp = row & 31;
;                     const size_t rbase = (size_t)(row >> 5) * 4096 + (size_t)(((kp >> 2) & 3) * 16) * 8 + 4 * (kp >> 4) + (kp & 3);
; #pragma unroll
;                     for (int bj = 0; bj < 2; ++bj) {
;                         const u32x2 w = pack8_fp8(acc[ai][bj][m][0], acc[ai][bj][m][1]);
;                         unsigned char* vb = VF + (size_t)bj * 512 * 4096 + rbase + (size_t)(cw >> 4) * 512 + (size_t)(cw & 15) * 8;
;                         vb[0] = (unsigned char)(w.x & 0xffu); vb[8] = (unsigned char)((w.x >> 8) & 0xffu); vb[16] = (unsigned char)((w.x >> 16) & 0xffu); vb[24] = (unsigned char)(w.x >> 24);
;                         vb[32] = (unsigned char)(w.y & 0xffu); vb[40] = (unsigned char)((w.y >> 8) & 0xffu); vb[48] = (unsigned char)((w.y >> 16) & 0xffu); vb[56] = (unsigned char)(w.y >> 24);
;                     }
	v_lshrrev_b32_e32 v30, 8, v42
	s_nop 0
	v_addc_co_u32_e32 v29, vcc, 0, v41, vcc
	global_store_byte v[28:29], v42, off offset:4
	global_store_byte v[28:29], v30, off offset:20
	global_store_byte_d16_hi v[28:29], v42, off offset:36
	v_lshrrev_b32_e32 v30, 24, v42
	global_store_byte v[28:29], v30, off offset:52
	global_store_byte v[28:29], v36, off offset:68
	v_lshrrev_b32_e32 v30, 8, v36
	global_store_byte v[28:29], v30, off offset:84
	global_store_byte_d16_hi v[28:29], v36, off offset:100
	v_lshrrev_b32_e32 v30, 24, v36
	global_store_byte v[28:29], v30, off offset:116
	v_mov_b32_e32 v30, 0
	v_cvt_pk_fp8_f32 v30, v32, v33
	s_add_i32 s6, s25, 0xa0
	v_mov_b32_e32 v31, 0
	s_ashr_i32 s42, s6, 5
	v_cvt_pk_fp8_f32 v31, v24, v25
	s_ashr_i32 s43, s42, 31
	s_lshl_b64 s[42:43], s[42:43], 12
	v_cvt_pk_fp8_f32 v30, v34, v35 op_sel:[0,0,1]
	v_lshl_add_u64 v[28:29], v[128:129], 0, s[42:43]
	v_lshl_add_u64 v[28:29], v[28:29], 0, v[172:173]
	v_cvt_pk_fp8_f32 v31, v26, v27 op_sel:[0,0,1]
	v_lshl_add_u64 v[24:25], v[28:29], 0, v[242:243]
	v_lshl_add_u64 v[24:25], v[24:25], 0, v[244:245]
	v_lshrrev_b32_e32 v26, 8, v30
	global_store_byte v[24:25], v30, off
	global_store_byte v[24:25], v26, off offset:16
	global_store_byte_d16_hi v[24:25], v30, off offset:32
	v_lshrrev_b32_e32 v26, 24, v30
	global_store_byte v[24:25], v26, off offset:48
	global_store_byte v[24:25], v31, off offset:64
	v_lshrrev_b32_e32 v26, 8, v31
	global_store_byte v[24:25], v26, off offset:80
	global_store_byte_d16_hi v[24:25], v31, off offset:96
	v_mov_b32_e32 v26, 0
	v_cvt_pk_fp8_f32 v26, v20, v21
	v_mov_b32_e32 v20, 0
	v_cvt_pk_fp8_f32 v20, v12, v13
	v_lshrrev_b32_e32 v12, 24, v31
	v_cvt_pk_fp8_f32 v26, v22, v23 op_sel:[0,0,1]
	global_store_byte v[24:25], v12, off offset:112
	v_cvt_pk_fp8_f32 v20, v14, v15 op_sel:[0,0,1]
	v_add_co_u32_e32 v12, vcc, s81, v24
	v_lshrrev_b32_e32 v14, 8, v26
	s_nop 0
	v_addc_co_u32_e32 v13, vcc, 0, v25, vcc
	global_store_byte v[12:13], v26, off
	global_store_byte v[12:13], v14, off offset:16
	global_store_byte_d16_hi v[12:13], v26, off offset:32
	v_lshrrev_b32_e32 v14, 24, v26
	global_store_byte v[12:13], v14, off offset:48
	global_store_byte v[12:13], v20, off offset:64
	v_lshrrev_b32_e32 v14, 8, v20
	global_store_byte v[12:13], v14, off offset:80
	global_store_byte_d16_hi v[12:13], v20, off offset:96
	v_lshrrev_b32_e32 v14, 24, v20
	global_store_byte v[12:13], v14, off offset:112
	v_mov_b32_e32 v14, 0
	v_cvt_pk_fp8_f32 v14, v16, v17
	s_addk_i32 s25, 0xb0
	v_mov_b32_e32 v15, 0
	s_ashr_i32 s42, s25, 5
	v_cvt_pk_fp8_f32 v15, v8, v9
	s_ashr_i32 s43, s42, 31
	s_lshl_b64 s[42:43], s[42:43], 12
	v_cvt_pk_fp8_f32 v14, v18, v19 op_sel:[0,0,1]
	v_lshl_add_u64 v[12:13], v[128:129], 0, s[42:43]
	v_lshl_add_u64 v[12:13], v[12:13], 0, v[172:173]
	v_cvt_pk_fp8_f32 v15, v10, v11 op_sel:[0,0,1]
	v_lshl_add_u64 v[8:9], v[12:13], 0, v[242:243]
	v_lshl_add_u64 v[8:9], v[8:9], 0, v[244:245]
	v_lshrrev_b32_e32 v10, 8, v14
	global_store_byte v[8:9], v14, off offset:4
	global_store_byte v[8:9], v10, off offset:20
	global_store_byte_d16_hi v[8:9], v14, off offset:36
	v_lshrrev_b32_e32 v10, 24, v14
	global_store_byte v[8:9], v10, off offset:52
	global_store_byte v[8:9], v15, off offset:68
	v_lshrrev_b32_e32 v10, 8, v15
	global_store_byte v[8:9], v10, off offset:84
	global_store_byte_d16_hi v[8:9], v15, off offset:100
	v_mov_b32_e32 v10, 0
	v_cvt_pk_fp8_f32 v10, v4, v5
	v_mov_b32_e32 v4, 0
	v_cvt_pk_fp8_f32 v4, v0, v1
	v_lshrrev_b32_e32 v0, 24, v15
	v_cvt_pk_fp8_f32 v10, v6, v7 op_sel:[0,0,1]
	global_store_byte v[8:9], v0, off offset:116
	v_cvt_pk_fp8_f32 v4, v2, v3 op_sel:[0,0,1]
	v_add_co_u32_e32 v0, vcc, s81, v8
	v_lshrrev_b32_e32 v2, 8, v10
	s_nop 0
	v_addc_co_u32_e32 v1, vcc, 0, v9, vcc
	global_store_byte v[0:1], v10, off offset:4
	global_store_byte v[0:1], v2, off offset:20
	global_store_byte_d16_hi v[0:1], v10, off offset:36
	v_lshrrev_b32_e32 v2, 24, v10
	global_store_byte v[0:1], v2, off offset:52
	global_store_byte v[0:1], v4, off offset:68
	v_lshrrev_b32_e32 v2, 8, v4
	global_store_byte v[0:1], v2, off offset:84
	global_store_byte_d16_hi v[0:1], v4, off offset:100
	v_lshrrev_b32_e32 v2, 24, v4
	global_store_byte v[0:1], v2, off offset:116
	s_andn2_b64 vcc, exec, s[4:5]
	s_mov_b64 s[4:5], -1
	s_cbranch_vccnz .LBB0_592

; __device__ __forceinline__ unsigned cvt_pk_bf16(float lo, float hi) { f32x2 v = {lo, hi}; bf16x2_t b = __builtin_convertvector(v, bf16x2_t); return __builtin_bit_cast(unsigned, b); }
; __device__ __forceinline__ float bf2f(unsigned short b) { return __uint_as_float(((unsigned)b) << 16); }
; __device__ __forceinline__ float bflo(unsigned w) { return __uint_as_float(w << 16); }
; __device__ __forceinline__ float bfhi(unsigned w) { return __uint_as_float(w & 0xffff0000u); }
; __device__ __forceinline__ float quad_total(float v) { v += __shfl_xor(v, 16); v += __shfl_xor(v, 32); return v; }
; __device__ __forceinline__ void nsa_unit(int unit, const bf16_t* proj, const bf16_t* kc, const bf16_t* vc, const bf16_t* gn, const float* cs, const float* sn, ...
;     ...
;     { const float g2 = bf2f(gn[(size_t)tc * 32 + head * 3 + 2]); const float lt = quad_total(st.l), inv = (lt > 0.f ? 1.f / lt : 0.f) * g2;
; #pragma unroll
;         for (int i = 0; i < 8; ++i) { const f32x4 o = st.o[i] * inv; u32x2 w = outl[64 * i]; w.x = cvt_pk_bf16(bflo(w.x) + o[0], bfhi(w.x) + o[1]); w.y = cvt_pk_bf16(bflo(w.y) + o[2], bfhi(w.y) + o[3]); outl[64 * i] = w; } }
;     bf16_t* op = nsaout + (size_t)tc * NOLD + head * 128 + 4 * kq;
; #pragma unroll
;     for (int db = 0; db < 8; ++db) *(u32x2*)(op + 16 * db) = outl[64 * db];
.LBB0_926:
	s_waitcnt vmcnt(8)
	global_load_ushort v0, v[76:77], off offset:4
	ds_bpermute_b32 v35, v225, v34
	ds_read2st64_b64 v[36:39], v226 offset0:27 offset1:28
	ds_read2st64_b64 v[40:43], v226 offset0:29 offset1:30
	ds_read2st64_b64 v[44:47], v226 offset0:31 offset1:32
	ds_read2st64_b64 v[48:51], v226 offset0:33 offset1:34
	s_waitcnt lgkmcnt(3)
	v_lshlrev_b32_e32 v52, 16, v38
	v_and_b32_e32 v53, 0xffff0000, v38
	v_add_f32_e32 v64, v34, v35
	ds_bpermute_b32 v65, v224, v64
	v_lshlrev_b32_e32 v34, 16, v36
	v_and_b32_e32 v35, 0xffff0000, v36
	v_lshlrev_b32_e32 v36, 16, v37
	v_and_b32_e32 v37, 0xffff0000, v37
	s_waitcnt lgkmcnt(0)
	v_add_f32_e32 v64, v64, v65
	v_div_scale_f32 v65, s[10:11], v64, v64, 1.0
	v_rcp_f32_e32 v66, v65
	v_div_scale_f32 v67, vcc, 1.0, v64, 1.0
	v_lshlrev_b32_e32 v38, 16, v39
	v_fma_f32 v68, -v65, v66, 1.0
	v_fmac_f32_e32 v66, v68, v66
	v_mul_f32_e32 v68, v67, v66
	v_fma_f32 v69, -v65, v68, v67
	v_fmac_f32_e32 v68, v69, v66
	v_fma_f32 v65, -v65, v68, v67
	v_div_fmas_f32 v65, v65, v66, v68
	v_div_fixup_f32 v65, v65, v64, 1.0
	v_cmp_lt_f32_e32 vcc, 0, v64
	v_and_b32_e32 v39, 0xffff0000, v39
	v_lshlrev_b32_e32 v56, 16, v42
	v_cndmask_b32_e32 v64, 0, v65, vcc
	v_and_b32_e32 v57, 0xffff0000, v42
	v_lshlrev_b32_e32 v42, 16, v43
	v_and_b32_e32 v43, 0xffff0000, v43
	v_lshlrev_b32_e32 v62, 16, v48
	v_and_b32_e32 v63, 0xffff0000, v48
	v_lshlrev_b32_e32 v48, 16, v49
	v_and_b32_e32 v49, 0xffff0000, v49
	v_lshlrev_b32_e32 v54, 16, v40
	v_and_b32_e32 v55, 0xffff0000, v40
	v_lshlrev_b32_e32 v40, 16, v41
	v_and_b32_e32 v41, 0xffff0000, v41
	v_lshlrev_b32_e32 v58, 16, v44
	v_and_b32_e32 v59, 0xffff0000, v44
	v_lshlrev_b32_e32 v44, 16, v45
	v_and_b32_e32 v45, 0xffff0000, v45
	v_lshlrev_b32_e32 v60, 16, v46
	v_and_b32_e32 v61, 0xffff0000, v46
	v_lshlrev_b32_e32 v46, 16, v47
	v_and_b32_e32 v47, 0xffff0000, v47
	s_waitcnt vmcnt(0)
	v_lshlrev_b32_e32 v0, 16, v0
	v_mul_f32_e32 v0, v64, v0
	v_pk_fma_f32 v[6:7], v[6:7], v[0:1], v[34:35] op_sel_hi:[1,0,1]
	v_pk_fma_f32 v[8:9], v[8:9], v[0:1], v[36:37] op_sel_hi:[1,0,1]
	v_pk_fma_f32 v[12:13], v[12:13], v[0:1], v[38:39] op_sel_hi:[1,0,1]
	v_pk_fma_f32 v[20:21], v[20:21], v[0:1], v[42:43] op_sel_hi:[1,0,1]
	v_cvt_pk_bf16_f32 v6, v6, v7
	v_cvt_pk_bf16_f32 v7, v8, v9
	v_cvt_pk_bf16_f32 v9, v12, v13
	v_cvt_pk_bf16_f32 v13, v20, v21
	v_lshlrev_b32_e32 v20, 16, v50
	v_and_b32_e32 v21, 0xffff0000, v50
	v_pk_fma_f32 v[2:3], v[2:3], v[0:1], v[20:21] op_sel_hi:[1,0,1]
	v_lshlrev_b32_e32 v20, 16, v51
	v_and_b32_e32 v21, 0xffff0000, v51
	v_pk_fma_f32 v[10:11], v[10:11], v[0:1], v[52:53] op_sel_hi:[1,0,1]
	v_pk_fma_f32 v[18:19], v[18:19], v[0:1], v[56:57] op_sel_hi:[1,0,1]
	v_pk_fma_f32 v[30:31], v[30:31], v[0:1], v[62:63] op_sel_hi:[1,0,1]
	v_pk_fma_f32 v[32:33], v[32:33], v[0:1], v[48:49] op_sel_hi:[1,0,1]
	v_pk_fma_f32 v[4:5], v[4:5], v[0:1], v[20:21] op_sel_hi:[1,0,1]
	v_pk_fma_f32 v[14:15], v[14:15], v[0:1], v[54:55] op_sel_hi:[1,0,1]
	v_pk_fma_f32 v[16:17], v[16:17], v[0:1], v[40:41] op_sel_hi:[1,0,1]
	v_pk_fma_f32 v[22:23], v[22:23], v[0:1], v[58:59] op_sel_hi:[1,0,1]
	v_pk_fma_f32 v[24:25], v[24:25], v[0:1], v[44:45] op_sel_hi:[1,0,1]
	v_pk_fma_f32 v[26:27], v[26:27], v[0:1], v[60:61] op_sel_hi:[1,0,1]
	v_pk_fma_f32 v[28:29], v[28:29], v[0:1], v[46:47] op_sel_hi:[1,0,1]
	v_cvt_pk_bf16_f32 v8, v10, v11
	v_cvt_pk_bf16_f32 v12, v18, v19
	v_cvt_pk_bf16_f32 v18, v30, v31
	v_cvt_pk_bf16_f32 v19, v32, v33
	v_cvt_pk_bf16_f32 v2, v2, v3
	v_cvt_pk_bf16_f32 v3, v4, v5
	v_mad_i64_i32 v[4:5], s[10:11], v132, s88, v[126:127]
	v_cvt_pk_bf16_f32 v10, v14, v15
	v_cvt_pk_bf16_f32 v11, v16, v17
	v_cvt_pk_bf16_f32 v14, v22, v23
	v_cvt_pk_bf16_f32 v15, v24, v25
	v_cvt_pk_bf16_f32 v16, v26, v27
	v_cvt_pk_bf16_f32 v17, v28, v29
	ds_write2st64_b64 v226, v[6:7], v[8:9] offset0:27 offset1:28
	ds_write2st64_b64 v226, v[10:11], v[12:13] offset0:29 offset1:30
	ds_write2st64_b64 v226, v[14:15], v[16:17] offset0:31 offset1:32
	ds_write2st64_b64 v226, v[18:19], v[2:3] offset0:33 offset1:34
	global_store_dwordx2 v[4:5], v[6:7], off
	global_store_dwordx2 v[4:5], v[8:9], off offset:32
	global_store_dwordx2 v[4:5], v[10:11], off offset:64
	global_store_dwordx2 v[4:5], v[12:13], off offset:96
	global_store_dwordx2 v[4:5], v[14:15], off offset:128
	global_store_dwordx2 v[4:5], v[16:17], off offset:160
	global_store_dwordx2 v[4:5], v[18:19], off offset:192
	global_store_dwordx2 v[4:5], v[2:3], off offset:224

; __device__ __forceinline__ unsigned cvt_pk_bf16(float lo, float hi) { f32x2 v = {lo, hi}; bf16x2_t b = __builtin_convertvector(v, bf16x2_t); return __builtin_bit_cast(unsigned, b); }
; __device__ __forceinline__ float bf2f(unsigned short b) { return __uint_as_float(((unsigned)b) << 16); }
; __device__ __forceinline__ void nsa_unit(int unit, const bf16_t* proj, const bf16_t* kc, const bf16_t* vc, const bf16_t* gn, const float* cs, const float* sn, ...
;     ...
;     for (int s2 = 0; s2 < 2; ++s2) {
;         const int d = 32 * s2 + 8 * kq; f32x4 c[2], sv[2];
;         c[0] = *(const f32x4*)(cs + (size_t)tc * 64 + d); c[1] = *(const f32x4*)(cs + (size_t)tc * 64 + d + 4);
;         sv[0] = *(const f32x4*)(sn + (size_t)tc * 64 + d); sv[1] = *(const f32x4*)(sn + (size_t)tc * 64 + d + 4);
;         float o1[8], o2[8];
; #pragma unroll
;         for (int j = 0; j < 8; ++j) { const float x1 = bf2f((unsigned short)qf[s2][j]), x2 = bf2f((unsigned short)qf[s2 + 2][j]), cc = c[j >> 2][j & 3], ss = sv[j >> 2][j & 3];
;             o1[j] = x1 * cc - x2 * ss; o2[j] = x2 * cc + x1 * ss; }
;         u32x4 w1, w2; w1.x = cvt_pk_bf16(o1[0], o1[1]); w1.y = cvt_pk_bf16(o1[2], o1[3]); w1.z = cvt_pk_bf16(o1[4], o1[5]); w1.w = cvt_pk_bf16(o1[6], o1[7]);
;         w2.x = cvt_pk_bf16(o2[0], o2[1]); w2.y = cvt_pk_bf16(o2[2], o2[3]); w2.z = cvt_pk_bf16(o2[4], o2[5]); w2.w = cvt_pk_bf16(o2[6], o2[7]);
;         qf[s2] = __builtin_bit_cast(bf16x8, w1); qf[s2 + 2] = __builtin_bit_cast(bf16x8, w2);
;     }
;     ...
;     i64_t q8[4];
; #pragma unroll
;     for (int s2 = 0; s2 < 4; ++s2) { f32x4 a, b;
; #pragma unroll
;         for (int j = 0; j < 4; ++j) { a[j] = bf2f((unsigned short)qf[s2][j]) * SL2; b[j] = bf2f((unsigned short)qf[s2][4 + j]) * SL2; }
;         q8[s2] = __builtin_bit_cast(i64_t, pack8_fp8(a, b)); }
.LBB0_959:
	s_or_b64 exec, exec, s[12:13]
	v_and_b32_e32 v51, 0xffff0000, v14
	v_lshlrev_b32_e32 v50, 16, v14
	v_and_b32_e32 v53, 0xffff0000, v10
	v_lshlrev_b32_e32 v52, 16, v10
	s_waitcnt vmcnt(4)
	v_pk_mul_f32 v[54:55], v[46:47], v[52:53]
	v_pk_mul_f32 v[46:47], v[46:47], v[50:51]
	v_pk_fma_f32 v[54:55], v[42:43], v[50:51], v[54:55] neg_lo:[0,0,1] neg_hi:[0,0,1]
	v_pk_fma_f32 v[42:43], v[42:43], v[52:53], v[46:47]
	v_and_b32_e32 v47, 0xffff0000, v15
	v_lshlrev_b32_e32 v46, 16, v15
	v_and_b32_e32 v15, 0xffff0000, v11
	v_lshlrev_b32_e32 v14, 16, v11
	v_pk_mul_f32 v[10:11], v[48:49], v[14:15]
	v_cvt_pk_bf16_f32 v0, v54, v55
	v_pk_fma_f32 v[10:11], v[44:45], v[46:47], v[10:11] neg_lo:[0,0,1] neg_hi:[0,0,1]
	v_pk_mul_f32 v[46:47], v[48:49], v[46:47]
	v_mov_b32_e32 v79, v1
	v_pk_fma_f32 v[14:15], v[44:45], v[14:15], v[46:47]
	v_and_b32_e32 v45, 0xffff0000, v16
	v_lshlrev_b32_e32 v44, 16, v16
	v_and_b32_e32 v47, 0xffff0000, v12
	v_lshlrev_b32_e32 v46, 16, v12
	v_pk_mul_f32 v[48:49], v[38:39], v[46:47]
	v_pk_mul_f32 v[38:39], v[38:39], v[44:45]
	v_pk_fma_f32 v[48:49], v[34:35], v[44:45], v[48:49] neg_lo:[0,0,1] neg_hi:[0,0,1]
	v_pk_fma_f32 v[34:35], v[34:35], v[46:47], v[38:39]
	v_and_b32_e32 v39, 0xffff0000, v17
	v_lshlrev_b32_e32 v38, 16, v17
	v_and_b32_e32 v17, 0xffff0000, v13
	v_lshlrev_b32_e32 v16, 16, v13
	v_pk_mul_f32 v[12:13], v[40:41], v[16:17]
	v_cvt_pk_bf16_f32 v34, v34, v35
	v_pk_fma_f32 v[12:13], v[36:37], v[38:39], v[12:13] neg_lo:[0,0,1] neg_hi:[0,0,1]
	v_pk_mul_f32 v[38:39], v[40:41], v[38:39]
	v_cvt_pk_bf16_f32 v40, v14, v15
	v_pk_fma_f32 v[16:17], v[36:37], v[16:17], v[38:39]
	v_cvt_pk_bf16_f32 v38, v12, v13
	v_and_b32_e32 v13, 0xffff0000, v2
	v_lshlrev_b32_e32 v12, 16, v2
	v_cvt_pk_bf16_f32 v36, v10, v11
	v_and_b32_e32 v11, 0xffff0000, v6
	v_lshlrev_b32_e32 v10, 16, v6
	s_waitcnt vmcnt(0)
	v_pk_mul_f32 v[14:15], v[30:31], v[12:13]
	v_lshlrev_b32_e32 v6, 16, v3
	v_pk_fma_f32 v[14:15], v[26:27], v[10:11], v[14:15] neg_lo:[0,0,1] neg_hi:[0,0,1]
	v_pk_mul_f32 v[10:11], v[30:31], v[10:11]
	v_cvt_pk_bf16_f32 v35, v16, v17
	v_pk_fma_f32 v[10:11], v[26:27], v[12:13], v[10:11]
	v_and_b32_e32 v13, 0xffff0000, v7
	v_lshlrev_b32_e32 v12, 16, v7
	v_and_b32_e32 v7, 0xffff0000, v3
	v_pk_mul_f32 v[2:3], v[32:33], v[6:7]
	v_and_b32_e32 v17, 0xffff0000, v4
	v_pk_fma_f32 v[2:3], v[28:29], v[12:13], v[2:3] neg_lo:[0,0,1] neg_hi:[0,0,1]
	v_pk_mul_f32 v[12:13], v[32:33], v[12:13]
	v_lshlrev_b32_e32 v16, 16, v4
	v_pk_fma_f32 v[6:7], v[28:29], v[6:7], v[12:13]
	v_and_b32_e32 v13, 0xffff0000, v8
	v_lshlrev_b32_e32 v12, 16, v8
	v_pk_mul_f32 v[26:27], v[22:23], v[16:17]
	v_lshlrev_b32_e32 v8, 16, v5
	v_pk_fma_f32 v[26:27], v[18:19], v[12:13], v[26:27] neg_lo:[0,0,1] neg_hi:[0,0,1]
	v_pk_mul_f32 v[12:13], v[22:23], v[12:13]
	v_cvt_pk_bf16_f32 v37, v48, v49
	v_pk_fma_f32 v[12:13], v[18:19], v[16:17], v[12:13]
	v_and_b32_e32 v17, 0xffff0000, v9
	v_lshlrev_b32_e32 v16, 16, v9
	v_and_b32_e32 v9, 0xffff0000, v5
	v_pk_mul_f32 v[4:5], v[24:25], v[8:9]
	v_mov_b32_e32 v78, v1
	v_pk_fma_f32 v[4:5], v[20:21], v[16:17], v[4:5] neg_lo:[0,0,1] neg_hi:[0,0,1]
	v_pk_mul_f32 v[16:17], v[24:25], v[16:17]
	v_cvt_pk_bf16_f32 v4, v4, v5
	v_cvt_pk_bf16_f32 v5, v10, v11
	v_lshlrev_b32_e32 v10, 16, v37
	v_and_b32_e32 v11, 0xffff0000, v37
	v_pk_fma_f32 v[8:9], v[20:21], v[8:9], v[16:17]
	v_mul_f32_e32 v10, 0x3e0293ee, v10
	v_mul_f32_e32 v11, 0x3e0293ee, v11
	v_cvt_pk_bf16_f32 v8, v8, v9
	v_lshlrev_b32_e32 v9, 16, v0
	v_and_b32_e32 v0, 0xffff0000, v0
	v_cvt_pk_fp8_f32 v79, v10, v11
	v_mul_f32_e32 v9, 0x3e0293ee, v9
	v_mul_f32_e32 v0, 0x3e0293ee, v0
	v_cvt_pk_bf16_f32 v6, v6, v7
	v_cvt_pk_bf16_f32 v7, v12, v13
	v_lshlrev_b32_e32 v13, 16, v38
	v_cvt_pk_fp8_f32 v78, v9, v0
	v_and_b32_e32 v0, 0xffff0000, v38
	v_cvt_pk_bf16_f32 v14, v14, v15
	v_mul_f32_e32 v13, 0x3e0293ee, v13
	v_mul_f32_e32 v0, 0x3e0293ee, v0
	v_cvt_pk_fp8_f32 v79, v13, v0 op_sel:[0,0,1]
	v_lshlrev_b32_e32 v0, 16, v14
	v_and_b32_e32 v10, 0xffff0000, v14
	v_cvt_pk_bf16_f32 v2, v2, v3
	v_cvt_pk_bf16_f32 v3, v26, v27
	v_mul_f32_e32 v0, 0x3e0293ee, v0
	v_mul_f32_e32 v10, 0x3e0293ee, v10
	v_mov_b32_e32 v80, v1
	v_lshlrev_b32_e32 v9, 16, v3
	v_and_b32_e32 v3, 0xffff0000, v3
	v_cvt_pk_fp8_f32 v80, v0, v10
	v_mul_f32_e32 v9, 0x3e0293ee, v9
	v_mul_f32_e32 v3, 0x3e0293ee, v3
	v_mov_b32_e32 v81, v1
	v_lshlrev_b32_e32 v12, 16, v36
	v_and_b32_e32 v15, 0xffff0000, v36
	v_lshlrev_b32_e32 v11, 16, v2
	v_and_b32_e32 v2, 0xffff0000, v2
	v_cvt_pk_fp8_f32 v81, v9, v3
	v_mul_f32_e32 v12, 0x3e0293ee, v12
	v_mul_f32_e32 v15, 0x3e0293ee, v15
	v_mul_f32_e32 v11, 0x3e0293ee, v11
	v_mul_f32_e32 v2, 0x3e0293ee, v2
	v_cvt_pk_fp8_f32 v78, v12, v15 op_sel:[0,0,1]
	v_lshlrev_b32_e32 v12, 16, v4
	v_and_b32_e32 v0, 0xffff0000, v4
	v_cvt_pk_fp8_f32 v80, v11, v2 op_sel:[0,0,1]
	v_lshlrev_b32_e32 v2, 16, v34
	v_and_b32_e32 v4, 0xffff0000, v34
	v_cvt_pk_bf16_f32 v39, v42, v43
	v_mul_f32_e32 v12, 0x3e0293ee, v12
	v_mul_f32_e32 v0, 0x3e0293ee, v0
	v_mul_f32_e32 v2, 0x3e0293ee, v2
	v_mul_f32_e32 v4, 0x3e0293ee, v4
	v_mov_b32_e32 v83, v1
	v_cvt_pk_fp8_f32 v81, v12, v0 op_sel:[0,0,1]
	v_lshlrev_b32_e32 v0, 16, v39
	v_and_b32_e32 v3, 0xffff0000, v39
	v_cvt_pk_fp8_f32 v83, v2, v4
	v_mul_f32_e32 v0, 0x3e0293ee, v0
	v_mul_f32_e32 v3, 0x3e0293ee, v3
	v_mov_b32_e32 v82, v1
	v_lshlrev_b32_e32 v10, 16, v35
	v_cvt_pk_fp8_f32 v82, v0, v3
	v_and_b32_e32 v0, 0xffff0000, v35
	v_mul_f32_e32 v10, 0x3e0293ee, v10
	v_mul_f32_e32 v0, 0x3e0293ee, v0
	v_cvt_pk_fp8_f32 v83, v10, v0 op_sel:[0,0,1]
	v_lshlrev_b32_e32 v0, 16, v5
	v_lshlrev_b32_e32 v2, 16, v7
	v_and_b32_e32 v3, 0xffff0000, v5
	v_and_b32_e32 v4, 0xffff0000, v7
	v_mul_f32_e32 v0, 0x3e0293ee, v0
	v_mul_f32_e32 v2, 0x3e0293ee, v2
	v_mul_f32_e32 v3, 0x3e0293ee, v3
	v_mul_f32_e32 v4, 0x3e0293ee, v4
	v_mov_b32_e32 v84, v1
	v_mov_b32_e32 v85, v1
	v_cvt_pk_fp8_f32 v84, v0, v3
	v_cvt_pk_fp8_f32 v85, v2, v4
	v_lshlrev_b32_e32 v9, 16, v40
	v_and_b32_e32 v11, 0xffff0000, v40
	v_lshlrev_b32_e32 v5, 16, v6
	v_lshlrev_b32_e32 v7, 16, v8
	v_and_b32_e32 v6, 0xffff0000, v6
	v_and_b32_e32 v0, 0xffff0000, v8
	v_mul_f32_e32 v9, 0x3e0293ee, v9
	v_mul_f32_e32 v11, 0x3e0293ee, v11
	v_mul_f32_e32 v5, 0x3e0293ee, v5
	v_mul_f32_e32 v7, 0x3e0293ee, v7
	v_mul_f32_e32 v6, 0x3e0293ee, v6
	v_mul_f32_e32 v0, 0x3e0293ee, v0
	v_cvt_pk_fp8_f32 v82, v9, v11 op_sel:[0,0,1]
	v_cvt_pk_fp8_f32 v84, v5, v6 op_sel:[0,0,1]
	v_cvt_pk_fp8_f32 v85, v7, v0 op_sel:[0,0,1]
	s_waitcnt lgkmcnt(0)
	s_mov_b64 s[10:11], s[52:53]
	s_cmp_eq_u64 vcc, 0
	s_cbranch_scc1 .LBB0_991
; __device__ __forceinline__ void load_frag8(Frag8& f, const unsigned char* __restrict__ KF, const unsigned char* __restrict__ VF, int pos0, int lane) {
;     const unsigned char* kp = KF + ((size_t)(pos0 >> 4) * 256 + lane) * 8; const unsigned char* vp = VF + ((size_t)(pos0 >> 5) * 512 + lane) * 8;
; #pragma unroll
;     for (int T = 0; T < 2; ++T)
; #pragma unroll
;         for (int s2 = 0; s2 < 4; ++s2) f.k[T][s2] = *(const i64_t*)(kp + (T * 4 + s2) * 512);
; #pragma unroll
;     for (int db = 0; db < 8; ++db) f.v[db] = *(const i64_t*)(vp + db * 512);
; }
; template <bool SLC, class Desc>
; __device__ __forceinline__ void attn_run_frag8(const i64_t (&qf)[4], const unsigned char* __restrict__ KF, const unsigned char* __restrict__ VF, const Desc& desc, int n,
;                                                int lo_in, int hi, int qi, AState& st, int lane) {
;     if (n <= 0) return;
;     Frag8 fa, fb, fc;
;     constexpr int NM = ~(1 << 30);
;     int d0 = desc(0), d1 = desc(n > 1 ? 1 : 0);
;     load_frag8(fa, KF, VF, SLC ? (d0 & 0xfffff) : (d0 & NM), lane);
;     load_frag8(fb, KF, VF, SLC ? (d1 & 0xfffff) : (d1 & NM), lane);
	v_mov_b32_e32 v0, s3
	ds_read_b64 v[2:3], v0 offset:13632
	s_bcnt1_i32_b64 s12, vcc
	s_lshl_b32 s54, s12, 1
	s_add_u32 s12, s69, s10
	s_addc_u32 s13, s70, s11
	s_add_u32 s10, s67, s10
	s_waitcnt lgkmcnt(0)
	v_readfirstlane_b32 s57, v2
	s_addc_u32 s11, s68, s11
	s_lshl_b32 s16, s57, 7
	s_and_b32 s14, s16, 0x7fff800
	s_add_u32 s14, s10, s14
	s_addc_u32 s15, s11, 0
	v_readfirstlane_b32 s92, v3
	v_lshl_add_u64 v[2:3], s[14:15], 0, v[120:121]
	s_and_b32 s14, s16, 0x7fff000
	s_add_u32 s14, s12, s14
	s_addc_u32 s15, s13, 0
	s_lshl_b32 s16, s92, 7
	v_lshl_add_u64 v[246:247], v[2:3], 0, v[120:121]
	global_load_dwordx4 v[138:141], v[246:247], off
	global_load_dwordx4 v[142:145], v[246:247], off offset:1024
	global_load_dwordx4 v[146:149], v[246:247], off offset:2048
	global_load_dwordx4 v[150:153], v[246:247], off offset:3072
	v_lshl_add_u64 v[2:3], s[14:15], 0, v[120:121]
	s_and_b32 s14, s16, 0x7fff800
	s_add_u32 s14, s10, s14
	s_addc_u32 s15, s11, 0
	v_lshl_add_u64 v[244:245], v[2:3], 0, v[120:121]
	global_load_dwordx4 v[90:93], v[244:245], off
	global_load_dwordx4 v[94:97], v[244:245], off offset:1024
	global_load_dwordx4 v[98:101], v[244:245], off offset:2048
	global_load_dwordx4 v[102:105], v[244:245], off offset:3072
	v_lshl_add_u64 v[2:3], s[14:15], 0, v[120:121]
	s_and_b32 s14, s16, 0x7fff000
	s_add_u32 s14, s12, s14
	s_addc_u32 s15, s13, 0
	v_lshl_add_u64 v[246:247], v[2:3], 0, v[120:121]
	global_load_dwordx4 v[154:157], v[246:247], off
	global_load_dwordx4 v[158:161], v[246:247], off offset:1024
	global_load_dwordx4 v[162:165], v[246:247], off offset:2048
	global_load_dwordx4 v[166:169], v[246:247], off offset:3072
	v_lshl_add_u64 v[2:3], s[14:15], 0, v[120:121]
	v_lshl_add_u64 v[244:245], v[2:3], 0, v[120:121]
	global_load_dwordx4 v[106:109], v[244:245], off
	global_load_dwordx4 v[110:113], v[244:245], off offset:1024
	global_load_dwordx4 v[114:117], v[244:245], off offset:2048
	global_load_dwordx4 v[134:137], v[244:245], off offset:3072
	v_mov_b32_e32 v2, v1
	v_mov_b32_e32 v3, v1
	v_mov_b32_e32 v0, v1
	v_mov_b64_e32 v[38:39], v[2:3]
	v_mov_b64_e32 v[42:43], v[2:3]
	v_mov_b64_e32 v[46:47], v[2:3]
	v_mov_b64_e32 v[50:51], v[2:3]
	v_mov_b64_e32 v[54:55], v[2:3]
	v_mov_b64_e32 v[58:59], v[2:3]
	v_mov_b64_e32 v[62:63], v[2:3]
	v_mov_b64_e32 v[66:67], v[2:3]
	v_lshl_add_u64 v[86:87], s[10:11], 0, v[120:121]
	v_lshl_add_u64 v[88:89], s[12:13], 0, v[120:121]
	s_add_i32 s55, s54, -1
	v_mov_b32_e32 v202, 0xf149f2ca
	v_mov_b32_e32 v203, 0
	s_mov_b32 s56, 4
	v_mov_b64_e32 v[36:37], v[0:1]
	v_mov_b64_e32 v[40:41], v[0:1]
	v_mov_b64_e32 v[44:45], v[0:1]
	v_mov_b64_e32 v[48:49], v[0:1]
	v_mov_b64_e32 v[52:53], v[0:1]
	v_mov_b64_e32 v[56:57], v[0:1]
	v_mov_b64_e32 v[60:61], v[0:1]
	v_mov_b64_e32 v[64:65], v[0:1]
	s_branch .LBB0_963

; template <bool SLC, bool NOMASK> ...
;     const int kq = lane >> 4;
;     const int pos0 = SLC ? (dcur & 0xfffff) : dcur;
;     const int lo = SLC ? ((((dcur >> 20) == qi) | ((dcur >> 20) == 4)) ? 0 : (1 << 30)) : lo_in;
;     load_frag8(nxt, KF, VF, SLC ? (dnext & 0xfffff) : dnext, lane);
;     f32x4 sa[2] = {(f32x4){0.f, 0.f, 0.f, 0.f}, (f32x4){0.f, 0.f, 0.f, 0.f}};
; #pragma unroll
;     for (int T = 0; T < 2; ++T)
; #pragma unroll
;         for (int s2 = 0; s2 < 4; ++s2) sa[T] = __builtin_amdgcn_mfma_f32_16x16x32_fp8_fp8(cur.k[T][s2], qf[s2], sa[T], 0, 0, 0);
;     float sc[8]; bool vd[8]; float mx = -1e30f;
;     const bool act = lo == 0 || !SLC;
;     if (NOMASK) {
; #pragma unroll
;         for (int j = 0; j < 8; ++j) { sc[j] = sa[j >> 2][j & 3]; vd[j] = act; }
;         mx = fmaxf(fmaxf(fmaxf(sc[0], sc[1]), fmaxf(sc[2], sc[3])), fmaxf(fmaxf(sc[4], sc[5]), fmaxf(sc[6], sc[7])));
;         mx = act ? mx : -1e30f;
;     } else {
; #pragma unroll
;         for (int T = 0; T < 2; ++T)
; #pragma unroll
;             for (int r = 0; r < 4; ++r) { const int p = pos0 + 16 * T + 4 * kq + r; const bool v = (p >= lo) & (p <= hi); const float x = sa[T][r];
;                 sc[4 * T + r] = x; vd[4 * T + r] = v; mx = v ? fmaxf(mx, x) : mx; }
;     }
;     if (__builtin_amdgcn_ballot_w64(mx > st.m + 4.f) != 0ull) {
;         mx = fmaxf(mx, __shfl_xor(mx, 16)); mx = fmaxf(mx, __shfl_xor(mx, 32));
;         const float mn = fmaxf(st.m, mx), alpha = __builtin_amdgcn_exp2f(st.m - mn); st.m = mn; st.l *= alpha;
; #pragma unroll
;         for (int j = 0; j < 8; ++j) st.o[j] = st.o[j] * alpha;
;     }
;     f32x4 pa, pb; float ps = 0.f;
;     const float mref = st.m - 4.f;
;     if (NOMASK) {
; #pragma unroll
;         for (int j = 0; j < 4; ++j) { pa[j] = __builtin_amdgcn_exp2f(sc[j] - mref); pb[j] = __builtin_amdgcn_exp2f(sc[4 + j] - mref); }
;         if (SLC) {
; #pragma unroll
;             for (int j = 0; j < 4; ++j) { pa[j] = act ? pa[j] : 0.f; pb[j] = act ? pb[j] : 0.f; }
;         }
; #pragma unroll
;         for (int j = 0; j < 4; ++j) ps += pa[j] + pb[j];
;     } else {
; #pragma unroll
;         for (int j = 0; j < 4; ++j) { pa[j] = vd[j] ? __builtin_amdgcn_exp2f(sc[j] - mref) : 0.f; pb[j] = vd[4 + j] ? __builtin_amdgcn_exp2f(sc[4 + j] - mref) : 0.f; ps += pa[j] + pb[j]; }
;     }
;     st.l += ps;
;     const u32x2 pw = pack8_fp8(pa, pb);
.LBB0_969:
	s_and_b32 s13, s12, 0xfffffbff
	s_cmp_eq_u32 s13, 4
	s_cselect_b64 s[10:11], -1, 0
	s_lshl_b32 s14, s66, 7
	s_and_b32 s50, s14, 0x7fff800
	v_lshl_add_u64 v[10:11], v[86:87], 0, s[50:51]
	s_and_b32 s50, s14, 0x7fff000
	v_lshl_add_u64 v[246:247], v[10:11], 0, v[120:121]
	global_load_dwordx4 v[186:189], v[246:247], off
	global_load_dwordx4 v[190:193], v[246:247], off offset:1024
	global_load_dwordx4 v[194:197], v[246:247], off offset:2048
	global_load_dwordx4 v[198:201], v[246:247], off offset:3072
	v_lshl_add_u64 v[10:11], v[88:89], 0, s[50:51]
	v_lshl_add_u64 v[244:245], v[10:11], 0, v[120:121]
	global_load_dwordx4 v[170:173], v[244:245], off
	global_load_dwordx4 v[174:177], v[244:245], off offset:1024
	global_load_dwordx4 v[178:181], v[244:245], off offset:2048
	global_load_dwordx4 v[182:185], v[244:245], off offset:3072
	s_waitcnt vmcnt(20)
	v_mfma_f32_16x16x32_fp8_fp8 v[2:5], v[138:139], v[78:79], 0
	v_cmp_eq_u32_e32 vcc, s13, v209
	s_or_b64 s[10:11], s[10:11], vcc
	v_mov_b64_e32 v[74:75], v[38:39]
	v_mfma_f32_16x16x32_fp8_fp8 v[6:9], v[146:147], v[78:79], 0
	v_mov_b64_e32 v[70:71], v[42:43]
	v_mov_b64_e32 v[30:31], v[44:45]
	v_mov_b64_e32 v[26:27], v[48:49]
	v_mfma_f32_16x16x32_fp8_fp8 v[2:5], v[140:141], v[80:81], v[2:5]
	v_mov_b64_e32 v[22:23], v[52:53]
	v_mov_b64_e32 v[18:19], v[56:57]
	v_mov_b64_e32 v[14:15], v[60:61]
	v_mfma_f32_16x16x32_fp8_fp8 v[6:9], v[148:149], v[80:81], v[6:9]
	v_mov_b64_e32 v[72:73], v[36:37]
	v_mov_b64_e32 v[68:69], v[40:41]
	v_mov_b64_e32 v[32:33], v[46:47]
	v_mfma_f32_16x16x32_fp8_fp8 v[2:5], v[142:143], v[82:83], v[2:5]
	v_mov_b64_e32 v[28:29], v[50:51]
	v_mov_b64_e32 v[24:25], v[54:55]
	v_mov_b64_e32 v[20:21], v[58:59]
	v_mfma_f32_16x16x32_fp8_fp8 v[6:9], v[150:151], v[82:83], v[6:9]
	v_mov_b64_e32 v[16:17], v[62:63]
	v_mov_b32_e32 v133, v203
	v_mfma_f32_16x16x32_fp8_fp8 v[2:5], v[144:145], v[84:85], v[2:5]
	v_mfma_f32_16x16x32_fp8_fp8 v[6:9], v[152:153], v[84:85], v[6:9]
	s_nop 5
	v_max_f32_e32 v0, v3, v3
	v_max_f32_e32 v10, v2, v2
	v_max_f32_e32 v0, v10, v0
	v_max_f32_e32 v10, v5, v5
	v_max_f32_e32 v11, v4, v4
	v_max_f32_e32 v10, v11, v10
	v_max_f32_e32 v11, v9, v9
	v_max_f32_e32 v12, v8, v8
	v_max_f32_e32 v11, v12, v11
	v_max3_f32 v11, v6, v7, v11
	v_max3_f32 v0, v0, v10, v11
	v_cndmask_b32_e64 v34, v220, v0, s[10:11]
	v_mov_b64_e32 v[10:11], v[64:65]
	v_cmp_gt_f32_e32 vcc, v34, v204
	v_mov_b32_e32 v0, v202
	v_mov_b64_e32 v[12:13], v[66:67]
	s_cbranch_vccz .LBB0_971
	ds_bpermute_b32 v0, v225, v34
	v_max_f32_e32 v10, v34, v34
	s_waitcnt lgkmcnt(0)
	v_max_f32_e32 v0, v0, v0
	v_max_f32_e32 v0, v10, v0
	ds_bpermute_b32 v10, v224, v0
	s_waitcnt lgkmcnt(0)
	v_max3_f32 v0, v202, v0, v10
	v_sub_f32_e32 v10, v202, v0
	v_exp_f32_e32 v34, v10
	s_nop 0
	v_mul_f32_e32 v133, v203, v34
	v_pk_mul_f32 v[12:13], v[66:67], v[34:35] op_sel_hi:[1,0]
	v_pk_mul_f32 v[10:11], v[64:65], v[34:35] op_sel_hi:[1,0]
	v_pk_mul_f32 v[16:17], v[62:63], v[34:35] op_sel_hi:[1,0]
	v_pk_mul_f32 v[14:15], v[60:61], v[34:35] op_sel_hi:[1,0]
	v_pk_mul_f32 v[20:21], v[58:59], v[34:35] op_sel_hi:[1,0]
	v_pk_mul_f32 v[18:19], v[56:57], v[34:35] op_sel_hi:[1,0]
	v_pk_mul_f32 v[24:25], v[54:55], v[34:35] op_sel_hi:[1,0]
	v_pk_mul_f32 v[22:23], v[52:53], v[34:35] op_sel_hi:[1,0]
	v_pk_mul_f32 v[28:29], v[50:51], v[34:35] op_sel_hi:[1,0]
	v_pk_mul_f32 v[26:27], v[48:49], v[34:35] op_sel_hi:[1,0]
	v_pk_mul_f32 v[32:33], v[46:47], v[34:35] op_sel_hi:[1,0]
	v_pk_mul_f32 v[30:31], v[44:45], v[34:35] op_sel_hi:[1,0]
	v_pk_mul_f32 v[70:71], v[42:43], v[34:35] op_sel_hi:[1,0]
	v_pk_mul_f32 v[68:69], v[40:41], v[34:35] op_sel_hi:[1,0]
	v_pk_mul_f32 v[74:75], v[38:39], v[34:35] op_sel_hi:[1,0]
	v_pk_mul_f32 v[72:73], v[36:37], v[34:35] op_sel_hi:[1,0]
.LBB0_971:
	v_add_f32_e32 v34, -4.0, v0
	v_sub_f32_e32 v2, v2, v34
	v_sub_f32_e32 v6, v6, v34
	v_sub_f32_e32 v3, v3, v34
	v_sub_f32_e32 v7, v7, v34
	v_exp_f32_e32 v2, v2
	v_exp_f32_e32 v6, v6
	v_exp_f32_e32 v3, v3
	v_exp_f32_e32 v7, v7
	v_sub_f32_e32 v4, v4, v34
	v_sub_f32_e32 v8, v8, v34
	v_sub_f32_e32 v5, v5, v34
	v_sub_f32_e32 v9, v9, v34
	v_exp_f32_e32 v4, v4
	v_exp_f32_e32 v8, v8
	v_exp_f32_e32 v5, v5
	v_exp_f32_e32 v9, v9
	v_cndmask_b32_e64 v34, 0, v2, s[10:11]
	v_cndmask_b32_e64 v6, 0, v6, s[10:11]
	v_cndmask_b32_e64 v35, 0, v3, s[10:11]
	v_cndmask_b32_e64 v7, 0, v7, s[10:11]
	v_mov_b32_e32 v2, v1
	v_mov_b32_e32 v3, v1
	v_cvt_pk_fp8_f32 v2, v34, v35
	v_cvt_pk_fp8_f32 v3, v6, v7
	v_cndmask_b32_e64 v4, 0, v4, s[10:11]
	v_cndmask_b32_e64 v205, 0, v8, s[10:11]
	v_cndmask_b32_e64 v5, 0, v5, s[10:11]
	v_cndmask_b32_e64 v227, 0, v9, s[10:11]
	v_add_f32_e32 v6, v34, v6
	v_cvt_pk_fp8_f32 v2, v4, v5 op_sel:[0,0,1]
	v_cvt_pk_fp8_f32 v3, v205, v227 op_sel:[0,0,1]
	v_add_f32_e32 v6, 0, v6
	v_add_f32_e32 v7, v35, v7
	v_add_f32_e32 v6, v7, v6
	v_add_f32_e32 v4, v4, v205
	v_add_f32_e32 v4, v4, v6
	v_add_f32_e32 v5, v5, v227
	v_add_f32_e32 v4, v5, v4
	s_waitcnt vmcnt(19)
	v_mfma_f32_16x16x32_fp8_fp8 v[8:11], v[90:91], v[2:3], v[10:13]
	v_add_f32_e32 v133, v133, v4
	v_mfma_f32_16x16x32_fp8_fp8 v[12:15], v[92:93], v[2:3], v[14:17]
	s_waitcnt vmcnt(18)
	v_mfma_f32_16x16x32_fp8_fp8 v[16:19], v[94:95], v[2:3], v[18:21]
	v_mfma_f32_16x16x32_fp8_fp8 v[20:23], v[96:97], v[2:3], v[22:25]
	s_waitcnt vmcnt(17)
	v_mfma_f32_16x16x32_fp8_fp8 v[24:27], v[98:99], v[2:3], v[26:29]
	v_mfma_f32_16x16x32_fp8_fp8 v[32:35], v[100:101], v[2:3], v[30:33]
	s_waitcnt vmcnt(16)
	v_mfma_f32_16x16x32_fp8_fp8 v[28:31], v[102:103], v[2:3], v[68:71]
	v_mfma_f32_16x16x32_fp8_fp8 v[4:7], v[104:105], v[2:3], v[72:75]
	s_branch .LBB0_965
; template <bool SLC, bool NOMASK> ...
;     const int kq = lane >> 4;
;     const int pos0 = SLC ? (dcur & 0xfffff) : dcur;
;     const int lo = SLC ? ((((dcur >> 20) == qi) | ((dcur >> 20) == 4)) ? 0 : (1 << 30)) : lo_in;
;     load_frag8(nxt, KF, VF, SLC ? (dnext & 0xfffff) : dnext, lane);
;     f32x4 sa[2] = {(f32x4){0.f, 0.f, 0.f, 0.f}, (f32x4){0.f, 0.f, 0.f, 0.f}};
; #pragma unroll
;     for (int T = 0; T < 2; ++T)
; #pragma unroll
;         for (int s2 = 0; s2 < 4; ++s2) sa[T] = __builtin_amdgcn_mfma_f32_16x16x32_fp8_fp8(cur.k[T][s2], qf[s2], sa[T], 0, 0, 0);
;     float sc[8]; bool vd[8]; float mx = -1e30f;
;     const bool act = lo == 0 || !SLC;
;     if (NOMASK) {
; #pragma unroll
;         for (int j = 0; j < 8; ++j) { sc[j] = sa[j >> 2][j & 3]; vd[j] = act; }
;         mx = fmaxf(fmaxf(fmaxf(sc[0], sc[1]), fmaxf(sc[2], sc[3])), fmaxf(fmaxf(sc[4], sc[5]), fmaxf(sc[6], sc[7])));
;         mx = act ? mx : -1e30f;
;     } else {
; #pragma unroll
;         for (int T = 0; T < 2; ++T)
; #pragma unroll
;             for (int r = 0; r < 4; ++r) { const int p = pos0 + 16 * T + 4 * kq + r; const bool v = (p >= lo) & (p <= hi); const float x = sa[T][r];
;                 sc[4 * T + r] = x; vd[4 * T + r] = v; mx = v ? fmaxf(mx, x) : mx; }
;     }
;     if (__builtin_amdgcn_ballot_w64(mx > st.m + 4.f) != 0ull) {
;         mx = fmaxf(mx, __shfl_xor(mx, 16)); mx = fmaxf(mx, __shfl_xor(mx, 32));
;         const float mn = fmaxf(st.m, mx), alpha = __builtin_amdgcn_exp2f(st.m - mn); st.m = mn; st.l *= alpha;
; #pragma unroll
;         for (int j = 0; j < 8; ++j) st.o[j] = st.o[j] * alpha;
;     }
;     f32x4 pa, pb; float ps = 0.f;
;     const float mref = st.m - 4.f;
;     if (NOMASK) {
; #pragma unroll
;         for (int j = 0; j < 4; ++j) { pa[j] = __builtin_amdgcn_exp2f(sc[j] - mref); pb[j] = __builtin_amdgcn_exp2f(sc[4 + j] - mref); }
;         if (SLC) {
; #pragma unroll
;             for (int j = 0; j < 4; ++j) { pa[j] = act ? pa[j] : 0.f; pb[j] = act ? pb[j] : 0.f; }
;         }
; #pragma unroll
;         for (int j = 0; j < 4; ++j) ps += pa[j] + pb[j];
;     } else {
; #pragma unroll
;         for (int j = 0; j < 4; ++j) { pa[j] = vd[j] ? __builtin_amdgcn_exp2f(sc[j] - mref) : 0.f; pb[j] = vd[4 + j] ? __builtin_amdgcn_exp2f(sc[4 + j] - mref) : 0.f; ps += pa[j] + pb[j]; }
;     }
;     st.l += ps;
;     const u32x2 pw = pack8_fp8(pa, pb);
.LBB0_972:
	s_cmp_eq_u32 s12, 4
	s_cselect_b64 s[10:11], -1, 0
	s_lshl_b32 s13, s66, 7
	s_and_b32 s50, s13, 0x7fff800
	v_lshl_add_u64 v[10:11], v[86:87], 0, s[50:51]
	s_and_b32 s50, s13, 0x7fff000
	v_lshl_add_u64 v[246:247], v[10:11], 0, v[120:121]
	global_load_dwordx4 v[186:189], v[246:247], off
	global_load_dwordx4 v[190:193], v[246:247], off offset:1024
	global_load_dwordx4 v[194:197], v[246:247], off offset:2048
	global_load_dwordx4 v[198:201], v[246:247], off offset:3072
	v_lshl_add_u64 v[10:11], v[88:89], 0, s[50:51]
	v_lshl_add_u64 v[244:245], v[10:11], 0, v[120:121]
	global_load_dwordx4 v[170:173], v[244:245], off
	global_load_dwordx4 v[174:177], v[244:245], off offset:1024
	global_load_dwordx4 v[178:181], v[244:245], off offset:2048
	global_load_dwordx4 v[182:185], v[244:245], off offset:3072
	s_waitcnt vmcnt(20)
	v_mfma_f32_16x16x32_fp8_fp8 v[2:5], v[138:139], v[78:79], 0
	s_and_b32 s13, s57, 0xfffff
	v_cmp_eq_u32_e32 vcc, s12, v209
	v_add_u32_e32 v0, s13, v210
	v_mfma_f32_16x16x32_fp8_fp8 v[2:5], v[140:141], v[80:81], v[2:5]
	s_or_b64 s[18:19], s[10:11], vcc
	v_cmp_le_i32_e32 vcc, v0, v132
	s_and_b64 s[16:17], s[18:19], vcc
	v_mfma_f32_16x16x32_fp8_fp8 v[2:5], v[142:143], v[82:83], v[2:5]
	v_cmp_lt_i32_e32 vcc, v0, v132
	s_and_b64 s[12:13], s[18:19], vcc
	v_mfma_f32_16x16x32_fp8_fp8 v[6:9], v[146:147], v[78:79], 0
	v_mfma_f32_16x16x32_fp8_fp8 v[2:5], v[144:145], v[84:85], v[2:5]
	v_mfma_f32_16x16x32_fp8_fp8 v[6:9], v[148:149], v[80:81], v[6:9]
	v_mfma_f32_16x16x32_fp8_fp8 v[6:9], v[150:151], v[82:83], v[6:9]
	s_nop 3
	v_max_f32_e32 v10, v2, v2
	v_max_f32_e32 v10, 0xf149f2ca, v10
	v_cndmask_b32_e64 v10, v220, v10, s[16:17]
	v_max_f32_e32 v11, v3, v3
	v_max_f32_e32 v11, v10, v11
	v_cndmask_b32_e64 v10, v10, v11, s[12:13]
	v_add_u32_e32 v11, 2, v0
	v_cmp_le_i32_e32 vcc, v11, v132
	v_max_f32_e32 v11, v4, v4
	v_max_f32_e32 v11, v10, v11
	s_and_b64 s[14:15], s[18:19], vcc
	v_mfma_f32_16x16x32_fp8_fp8 v[6:9], v[152:153], v[84:85], v[6:9]
	v_cndmask_b32_e64 v10, v10, v11, s[14:15]
	v_add_u32_e32 v11, 3, v0
	v_cmp_le_i32_e32 vcc, v11, v132
	v_max_f32_e32 v11, v5, v5
	v_max_f32_e32 v11, v10, v11
	s_and_b64 s[10:11], s[18:19], vcc
	v_cndmask_b32_e64 v10, v10, v11, s[10:11]
	v_add_u32_e32 v11, 16, v0
	v_cmp_le_i32_e32 vcc, v11, v132
	v_max_f32_e32 v11, v6, v6
	v_max_f32_e32 v11, v10, v11
	s_and_b64 s[24:25], s[18:19], vcc
	v_cndmask_b32_e64 v10, v10, v11, s[24:25]
	v_add_u32_e32 v11, 17, v0
	v_cmp_le_i32_e32 vcc, v11, v132
	v_max_f32_e32 v11, v10, v10
	v_max_f32_e32 v12, v7, v7
	v_max_f32_e32 v11, v11, v12
	s_and_b64 s[20:21], s[18:19], vcc
	v_cndmask_b32_e64 v10, v10, v11, s[20:21]
	v_add_u32_e32 v11, 18, v0
	v_cmp_le_i32_e32 vcc, v11, v132
	v_max_f32_e32 v11, v10, v10
	v_max_f32_e32 v12, v8, v8
	v_max_f32_e32 v11, v11, v12
	s_and_b64 s[22:23], s[18:19], vcc
	v_cndmask_b32_e64 v10, v10, v11, s[22:23]
	v_add_u32_e32 v0, 19, v0
	v_cmp_le_i32_e32 vcc, v0, v132
	v_max_f32_e32 v0, v10, v10
	v_max_f32_e32 v11, v9, v9
	v_max_f32_e32 v0, v0, v11
	s_and_b64 s[18:19], s[18:19], vcc
	v_cndmask_b32_e64 v0, v10, v0, s[18:19]
	v_cmp_gt_f32_e32 vcc, v0, v204
	s_cbranch_vccz .LBB0_974
	ds_bpermute_b32 v10, v225, v0
	v_max_f32_e32 v0, v0, v0
	s_waitcnt lgkmcnt(0)
	v_max_f32_e32 v10, v10, v10
	v_max_f32_e32 v0, v0, v10
	ds_bpermute_b32 v10, v224, v0
	s_waitcnt lgkmcnt(0)
	v_max3_f32 v10, v202, v0, v10
	v_sub_f32_e32 v0, v202, v10
	v_exp_f32_e32 v0, v0
	v_mov_b32_e32 v202, v10
	v_mul_f32_e32 v203, v203, v0
	v_pk_mul_f32 v[66:67], v[66:67], v[0:1] op_sel_hi:[1,0]
	v_pk_mul_f32 v[64:65], v[64:65], v[0:1] op_sel_hi:[1,0]
	v_pk_mul_f32 v[62:63], v[62:63], v[0:1] op_sel_hi:[1,0]
	v_pk_mul_f32 v[60:61], v[60:61], v[0:1] op_sel_hi:[1,0]
	v_pk_mul_f32 v[58:59], v[58:59], v[0:1] op_sel_hi:[1,0]
	v_pk_mul_f32 v[56:57], v[56:57], v[0:1] op_sel_hi:[1,0]
	v_pk_mul_f32 v[54:55], v[54:55], v[0:1] op_sel_hi:[1,0]
	v_pk_mul_f32 v[52:53], v[52:53], v[0:1] op_sel_hi:[1,0]
	v_pk_mul_f32 v[50:51], v[50:51], v[0:1] op_sel_hi:[1,0]
	v_pk_mul_f32 v[48:49], v[48:49], v[0:1] op_sel_hi:[1,0]
	v_pk_mul_f32 v[46:47], v[46:47], v[0:1] op_sel_hi:[1,0]
	v_pk_mul_f32 v[44:45], v[44:45], v[0:1] op_sel_hi:[1,0]
	v_pk_mul_f32 v[42:43], v[42:43], v[0:1] op_sel_hi:[1,0]
	v_pk_mul_f32 v[40:41], v[40:41], v[0:1] op_sel_hi:[1,0]
	v_pk_mul_f32 v[38:39], v[38:39], v[0:1] op_sel_hi:[1,0]
	v_pk_mul_f32 v[36:37], v[36:37], v[0:1] op_sel_hi:[1,0]
.LBB0_974:
	v_add_f32_e32 v0, -4.0, v202
	v_sub_f32_e32 v2, v2, v0
	v_exp_f32_e32 v2, v2
	v_sub_f32_e32 v6, v6, v0
	v_exp_f32_e32 v6, v6
	v_sub_f32_e32 v4, v4, v0
	v_cndmask_b32_e64 v28, 0, v2, s[16:17]
	v_sub_f32_e32 v2, v3, v0
	v_exp_f32_e32 v2, v2
	v_sub_f32_e32 v3, v7, v0
	v_exp_f32_e32 v3, v3
	v_sub_f32_e32 v7, v8, v0
	v_cndmask_b32_e64 v29, 0, v2, s[12:13]
	v_sub_f32_e32 v2, v5, v0
	v_sub_f32_e32 v0, v9, v0
	v_cndmask_b32_e64 v6, 0, v6, s[24:25]
	v_exp_f32_e32 v4, v4
	v_exp_f32_e32 v7, v7
	v_cndmask_b32_e64 v30, 0, v3, s[20:21]
	v_exp_f32_e32 v5, v2
	v_exp_f32_e32 v0, v0
	v_mov_b32_e32 v2, v1
	v_mov_b32_e32 v3, v1
	v_cvt_pk_fp8_f32 v2, v28, v29
	v_cvt_pk_fp8_f32 v3, v6, v30
	v_cndmask_b32_e64 v4, 0, v4, s[14:15]
	v_cndmask_b32_e64 v7, 0, v7, s[22:23]
	v_cndmask_b32_e64 v5, 0, v5, s[10:11]
	v_cndmask_b32_e64 v0, 0, v0, s[18:19]
	v_cvt_pk_fp8_f32 v2, v4, v5 op_sel:[0,0,1]
	v_cvt_pk_fp8_f32 v3, v7, v0 op_sel:[0,0,1]
	v_add_f32_e32 v6, v28, v6
	v_add_f32_e32 v6, 0, v6
	v_add_f32_e32 v28, v29, v30
	v_add_f32_e32 v6, v28, v6
	v_add_f32_e32 v4, v4, v7
	v_add_f32_e32 v4, v4, v6
	v_add_f32_e32 v0, v5, v0
	s_waitcnt vmcnt(19)
	v_mfma_f32_16x16x32_fp8_fp8 v[8:11], v[90:91], v[2:3], v[64:67]
	v_add_f32_e32 v0, v0, v4
	v_add_f32_e32 v133, v203, v0
	v_mov_b32_e32 v0, v202
	v_mfma_f32_16x16x32_fp8_fp8 v[12:15], v[92:93], v[2:3], v[60:63]
	s_waitcnt vmcnt(18)
	v_mfma_f32_16x16x32_fp8_fp8 v[16:19], v[94:95], v[2:3], v[56:59]
	v_mfma_f32_16x16x32_fp8_fp8 v[20:23], v[96:97], v[2:3], v[52:55]
	s_waitcnt vmcnt(17)
	v_mfma_f32_16x16x32_fp8_fp8 v[24:27], v[98:99], v[2:3], v[48:51]
	v_mfma_f32_16x16x32_fp8_fp8 v[32:35], v[100:101], v[2:3], v[44:47]
	s_waitcnt vmcnt(16)
	v_mfma_f32_16x16x32_fp8_fp8 v[28:31], v[102:103], v[2:3], v[40:43]
	v_mfma_f32_16x16x32_fp8_fp8 v[4:7], v[104:105], v[2:3], v[36:39]
	s_add_i32 s10, s56, -3
	s_cmp_ge_u32 s10, s54
	s_mov_b64 s[10:11], -1
	s_cbranch_scc0 .LBB0_966

; template <bool SLC, bool NOMASK> ...
;     const int kq = lane >> 4;
;     const int pos0 = SLC ? (dcur & 0xfffff) : dcur;
;     const int lo = SLC ? ((((dcur >> 20) == qi) | ((dcur >> 20) == 4)) ? 0 : (1 << 30)) : lo_in;
;     load_frag8(nxt, KF, VF, SLC ? (dnext & 0xfffff) : dnext, lane);
;     f32x4 sa[2] = {(f32x4){0.f, 0.f, 0.f, 0.f}, (f32x4){0.f, 0.f, 0.f, 0.f}};
; #pragma unroll
;     for (int T = 0; T < 2; ++T)
; #pragma unroll
;         for (int s2 = 0; s2 < 4; ++s2) sa[T] = __builtin_amdgcn_mfma_f32_16x16x32_fp8_fp8(cur.k[T][s2], qf[s2], sa[T], 0, 0, 0);
;     float sc[8]; bool vd[8]; float mx = -1e30f;
;     const bool act = lo == 0 || !SLC;
;     if (NOMASK) {
; #pragma unroll
;         for (int j = 0; j < 8; ++j) { sc[j] = sa[j >> 2][j & 3]; vd[j] = act; }
;         mx = fmaxf(fmaxf(fmaxf(sc[0], sc[1]), fmaxf(sc[2], sc[3])), fmaxf(fmaxf(sc[4], sc[5]), fmaxf(sc[6], sc[7])));
;         mx = act ? mx : -1e30f;
;     } else {
; #pragma unroll
;         for (int T = 0; T < 2; ++T)
; #pragma unroll
;             for (int r = 0; r < 4; ++r) { const int p = pos0 + 16 * T + 4 * kq + r; const bool v = (p >= lo) & (p <= hi); const float x = sa[T][r];
;                 sc[4 * T + r] = x; vd[4 * T + r] = v; mx = v ? fmaxf(mx, x) : mx; }
;     }
;     if (__builtin_amdgcn_ballot_w64(mx > st.m + 4.f) != 0ull) {
;         mx = fmaxf(mx, __shfl_xor(mx, 16)); mx = fmaxf(mx, __shfl_xor(mx, 32));
;         const float mn = fmaxf(st.m, mx), alpha = __builtin_amdgcn_exp2f(st.m - mn); st.m = mn; st.l *= alpha;
; #pragma unroll
;         for (int j = 0; j < 8; ++j) st.o[j] = st.o[j] * alpha;
;     }
;     f32x4 pa, pb; float ps = 0.f;
;     const float mref = st.m - 4.f;
;     if (NOMASK) {
; #pragma unroll
;         for (int j = 0; j < 4; ++j) { pa[j] = __builtin_amdgcn_exp2f(sc[j] - mref); pb[j] = __builtin_amdgcn_exp2f(sc[4 + j] - mref); }
;         if (SLC) {
; #pragma unroll
;             for (int j = 0; j < 4; ++j) { pa[j] = act ? pa[j] : 0.f; pb[j] = act ? pb[j] : 0.f; }
;         }
; #pragma unroll
;         for (int j = 0; j < 4; ++j) ps += pa[j] + pb[j];
;     } else {
; #pragma unroll
;         for (int j = 0; j < 4; ++j) { pa[j] = vd[j] ? __builtin_amdgcn_exp2f(sc[j] - mref) : 0.f; pb[j] = vd[4 + j] ? __builtin_amdgcn_exp2f(sc[4 + j] - mref) : 0.f; ps += pa[j] + pb[j]; }
;     }
;     st.l += ps;
;     const u32x2 pw = pack8_fp8(pa, pb);
.LBB0_976:
	s_and_b32 s13, s12, 0xfffffbff
	s_cmp_eq_u32 s13, 4
	s_cselect_b64 s[10:11], -1, 0
	s_lshl_b32 s14, s57, 7
	s_and_b32 s50, s14, 0x7fff800
	v_lshl_add_u64 v[44:45], v[86:87], 0, s[50:51]
	s_and_b32 s50, s14, 0x7fff000
	v_lshl_add_u64 v[246:247], v[44:45], 0, v[120:121]
	global_load_dwordx4 v[138:141], v[246:247], off
	global_load_dwordx4 v[142:145], v[246:247], off offset:1024
	global_load_dwordx4 v[146:149], v[246:247], off offset:2048
	global_load_dwordx4 v[150:153], v[246:247], off offset:3072
	v_lshl_add_u64 v[44:45], v[88:89], 0, s[50:51]
	v_lshl_add_u64 v[244:245], v[44:45], 0, v[120:121]
	global_load_dwordx4 v[90:93], v[244:245], off
	global_load_dwordx4 v[94:97], v[244:245], off offset:1024
	global_load_dwordx4 v[98:101], v[244:245], off offset:2048
	global_load_dwordx4 v[102:105], v[244:245], off offset:3072
	s_waitcnt vmcnt(20)
	v_mfma_f32_16x16x32_fp8_fp8 v[36:39], v[154:155], v[78:79], 0
	v_cmp_eq_u32_e32 vcc, s13, v209
	s_or_b64 s[10:11], s[10:11], vcc
	v_mov_b64_e32 v[74:75], v[6:7]
	v_mfma_f32_16x16x32_fp8_fp8 v[40:43], v[162:163], v[78:79], 0
	v_mov_b64_e32 v[70:71], v[30:31]
	v_mov_b64_e32 v[66:67], v[34:35]
	v_mov_b64_e32 v[62:63], v[26:27]
	v_mfma_f32_16x16x32_fp8_fp8 v[36:39], v[156:157], v[80:81], v[36:39]
	v_mov_b64_e32 v[58:59], v[22:23]
	v_mov_b64_e32 v[54:55], v[18:19]
	v_mov_b64_e32 v[50:51], v[14:15]
	v_mfma_f32_16x16x32_fp8_fp8 v[40:43], v[164:165], v[80:81], v[40:43]
	v_mov_b32_e32 v203, v0
	v_mov_b64_e32 v[72:73], v[4:5]
	v_mov_b64_e32 v[68:69], v[28:29]
	v_mfma_f32_16x16x32_fp8_fp8 v[36:39], v[158:159], v[82:83], v[36:39]
	v_mov_b64_e32 v[64:65], v[32:33]
	v_mov_b64_e32 v[60:61], v[24:25]
	v_mov_b64_e32 v[56:57], v[20:21]
	v_mfma_f32_16x16x32_fp8_fp8 v[40:43], v[166:167], v[82:83], v[40:43]
	v_mov_b64_e32 v[52:53], v[16:17]
	v_mov_b64_e32 v[48:49], v[12:13]
	v_mfma_f32_16x16x32_fp8_fp8 v[36:39], v[160:161], v[84:85], v[36:39]
	v_mfma_f32_16x16x32_fp8_fp8 v[40:43], v[168:169], v[84:85], v[40:43]
	s_nop 5
	v_max_f32_e32 v3, v37, v37
	v_max_f32_e32 v44, v36, v36
	v_max_f32_e32 v3, v44, v3
	v_max_f32_e32 v44, v39, v39
	v_max_f32_e32 v45, v38, v38
	v_max_f32_e32 v44, v45, v44
	v_max_f32_e32 v45, v43, v43
	v_max_f32_e32 v46, v42, v42
	v_max_f32_e32 v45, v46, v45
	v_max3_f32 v45, v40, v41, v45
	v_max3_f32 v3, v3, v44, v45
	v_cndmask_b32_e64 v202, v220, v3, s[10:11]
	v_mov_b64_e32 v[46:47], v[10:11]
	v_cmp_gt_f32_e32 vcc, v202, v2
	v_mov_b64_e32 v[44:45], v[8:9]
	v_mov_b32_e32 v3, v133
	s_cbranch_vccz .LBB0_978
	ds_bpermute_b32 v3, v225, v202
	v_max_f32_e32 v44, v202, v202
	s_waitcnt lgkmcnt(0)
	v_max_f32_e32 v3, v3, v3
	v_max_f32_e32 v3, v44, v3
	ds_bpermute_b32 v44, v224, v3
	s_waitcnt lgkmcnt(0)
	v_max3_f32 v203, v0, v3, v44
	v_sub_f32_e32 v3, v0, v203
	v_exp_f32_e32 v72, v3
	s_nop 0
	v_mul_f32_e32 v3, v133, v72
	v_pk_mul_f32 v[46:47], v[10:11], v[72:73] op_sel_hi:[1,0]
	v_pk_mul_f32 v[44:45], v[8:9], v[72:73] op_sel_hi:[1,0]
	v_pk_mul_f32 v[50:51], v[14:15], v[72:73] op_sel_hi:[1,0]
	v_pk_mul_f32 v[48:49], v[12:13], v[72:73] op_sel_hi:[1,0]
	v_pk_mul_f32 v[54:55], v[18:19], v[72:73] op_sel_hi:[1,0]
	v_pk_mul_f32 v[52:53], v[16:17], v[72:73] op_sel_hi:[1,0]
	v_pk_mul_f32 v[58:59], v[22:23], v[72:73] op_sel_hi:[1,0]
	v_pk_mul_f32 v[56:57], v[20:21], v[72:73] op_sel_hi:[1,0]
	v_pk_mul_f32 v[62:63], v[26:27], v[72:73] op_sel_hi:[1,0]
	v_pk_mul_f32 v[60:61], v[24:25], v[72:73] op_sel_hi:[1,0]
	v_pk_mul_f32 v[66:67], v[34:35], v[72:73] op_sel_hi:[1,0]
	v_pk_mul_f32 v[64:65], v[32:33], v[72:73] op_sel_hi:[1,0]
	v_pk_mul_f32 v[70:71], v[30:31], v[72:73] op_sel_hi:[1,0]
	v_pk_mul_f32 v[68:69], v[28:29], v[72:73] op_sel_hi:[1,0]
	v_pk_mul_f32 v[74:75], v[6:7], v[72:73] op_sel_hi:[1,0]
	v_pk_mul_f32 v[72:73], v[4:5], v[72:73] op_sel_hi:[1,0]
.LBB0_978:
	v_add_f32_e32 v202, -4.0, v203
	v_sub_f32_e32 v36, v36, v202
	v_sub_f32_e32 v40, v40, v202
	v_sub_f32_e32 v37, v37, v202
	v_sub_f32_e32 v41, v41, v202
	v_exp_f32_e32 v36, v36
	v_exp_f32_e32 v40, v40
	v_exp_f32_e32 v37, v37
	v_exp_f32_e32 v41, v41
	v_sub_f32_e32 v38, v38, v202
	v_sub_f32_e32 v42, v42, v202
	v_sub_f32_e32 v39, v39, v202
	v_sub_f32_e32 v43, v43, v202
	v_exp_f32_e32 v38, v38
	v_exp_f32_e32 v42, v42
	v_exp_f32_e32 v39, v39
	v_exp_f32_e32 v43, v43
	v_cndmask_b32_e64 v202, 0, v36, s[10:11]
	v_cndmask_b32_e64 v204, 0, v40, s[10:11]
	v_cndmask_b32_e64 v205, 0, v37, s[10:11]
	v_cndmask_b32_e64 v227, 0, v41, s[10:11]
	v_mov_b32_e32 v228, v1
	v_mov_b32_e32 v229, v1
	v_cvt_pk_fp8_f32 v228, v202, v205
	v_cvt_pk_fp8_f32 v229, v204, v227
	v_cndmask_b32_e64 v230, 0, v38, s[10:11]
	v_cndmask_b32_e64 v231, 0, v42, s[10:11]
	v_cndmask_b32_e64 v232, 0, v39, s[10:11]
	v_cndmask_b32_e64 v233, 0, v43, s[10:11]
	v_cvt_pk_fp8_f32 v228, v230, v232 op_sel:[0,0,1]
	v_cvt_pk_fp8_f32 v229, v231, v233 op_sel:[0,0,1]
	s_nop 0
	s_waitcnt vmcnt(19)
	v_mfma_f32_16x16x32_fp8_fp8 v[40:43], v[108:109], v[228:229], v[48:51]
	v_mfma_f32_16x16x32_fp8_fp8 v[48:51], v[112:113], v[228:229], v[56:59]
	s_nop 2
	v_add_f32_e32 v56, v202, v204
	s_waitcnt vmcnt(18)
	v_mfma_f32_16x16x32_fp8_fp8 v[36:39], v[106:107], v[228:229], v[44:47]
	v_mfma_f32_16x16x32_fp8_fp8 v[44:47], v[110:111], v[228:229], v[52:55]
	s_waitcnt vmcnt(17)
	v_mfma_f32_16x16x32_fp8_fp8 v[52:55], v[114:115], v[228:229], v[60:63]
	s_nop 2
	v_add_f32_e32 v60, 0, v56
	v_add_f32_e32 v61, v205, v227
	v_add_f32_e32 v60, v61, v60
	v_add_f32_e32 v61, v230, v231
	v_mfma_f32_16x16x32_fp8_fp8 v[56:59], v[116:117], v[228:229], v[64:67]
	s_nop 2
	v_add_f32_e32 v64, v61, v60
	v_add_f32_e32 v65, v232, v233
	v_add_f32_e32 v64, v65, v64
	s_waitcnt vmcnt(16)
	v_mfma_f32_16x16x32_fp8_fp8 v[60:63], v[134:135], v[228:229], v[68:71]
	v_add_f32_e32 v204, v3, v64
	v_mfma_f32_16x16x32_fp8_fp8 v[64:67], v[136:137], v[228:229], v[72:75]
	s_branch .LBB0_968
; template <bool SLC, bool NOMASK> ...
;     const int kq = lane >> 4;
;     const int pos0 = SLC ? (dcur & 0xfffff) : dcur;
;     const int lo = SLC ? ((((dcur >> 20) == qi) | ((dcur >> 20) == 4)) ? 0 : (1 << 30)) : lo_in;
;     load_frag8(nxt, KF, VF, SLC ? (dnext & 0xfffff) : dnext, lane);
;     f32x4 sa[2] = {(f32x4){0.f, 0.f, 0.f, 0.f}, (f32x4){0.f, 0.f, 0.f, 0.f}};
; #pragma unroll
;     for (int T = 0; T < 2; ++T)
; #pragma unroll
;         for (int s2 = 0; s2 < 4; ++s2) sa[T] = __builtin_amdgcn_mfma_f32_16x16x32_fp8_fp8(cur.k[T][s2], qf[s2], sa[T], 0, 0, 0);
;     float sc[8]; bool vd[8]; float mx = -1e30f;
;     const bool act = lo == 0 || !SLC;
;     if (NOMASK) {
; #pragma unroll
;         for (int j = 0; j < 8; ++j) { sc[j] = sa[j >> 2][j & 3]; vd[j] = act; }
;         mx = fmaxf(fmaxf(fmaxf(sc[0], sc[1]), fmaxf(sc[2], sc[3])), fmaxf(fmaxf(sc[4], sc[5]), fmaxf(sc[6], sc[7])));
;         mx = act ? mx : -1e30f;
;     } else {
; #pragma unroll
;         for (int T = 0; T < 2; ++T)
; #pragma unroll
;             for (int r = 0; r < 4; ++r) { const int p = pos0 + 16 * T + 4 * kq + r; const bool v = (p >= lo) & (p <= hi); const float x = sa[T][r];
;                 sc[4 * T + r] = x; vd[4 * T + r] = v; mx = v ? fmaxf(mx, x) : mx; }
;     }
;     if (__builtin_amdgcn_ballot_w64(mx > st.m + 4.f) != 0ull) {
;         mx = fmaxf(mx, __shfl_xor(mx, 16)); mx = fmaxf(mx, __shfl_xor(mx, 32));
;         const float mn = fmaxf(st.m, mx), alpha = __builtin_amdgcn_exp2f(st.m - mn); st.m = mn; st.l *= alpha;
; #pragma unroll
;         for (int j = 0; j < 8; ++j) st.o[j] = st.o[j] * alpha;
;     }
;     f32x4 pa, pb; float ps = 0.f;
;     const float mref = st.m - 4.f;
;     if (NOMASK) {
; #pragma unroll
;         for (int j = 0; j < 4; ++j) { pa[j] = __builtin_amdgcn_exp2f(sc[j] - mref); pb[j] = __builtin_amdgcn_exp2f(sc[4 + j] - mref); }
;         if (SLC) {
; #pragma unroll
;             for (int j = 0; j < 4; ++j) { pa[j] = act ? pa[j] : 0.f; pb[j] = act ? pb[j] : 0.f; }
;         }
; #pragma unroll
;         for (int j = 0; j < 4; ++j) ps += pa[j] + pb[j];
;     } else {
; #pragma unroll
;         for (int j = 0; j < 4; ++j) { pa[j] = vd[j] ? __builtin_amdgcn_exp2f(sc[j] - mref) : 0.f; pb[j] = vd[4 + j] ? __builtin_amdgcn_exp2f(sc[4 + j] - mref) : 0.f; ps += pa[j] + pb[j]; }
;     }
;     st.l += ps;
;     const u32x2 pw = pack8_fp8(pa, pb);
.LBB0_979:
	s_cmp_eq_u32 s12, 4
	s_cselect_b64 s[10:11], -1, 0
	s_lshl_b32 s13, s57, 7
	s_and_b32 s50, s13, 0x7fff800
	v_lshl_add_u64 v[44:45], v[86:87], 0, s[50:51]
	s_and_b32 s50, s13, 0x7fff000
	v_lshl_add_u64 v[246:247], v[44:45], 0, v[120:121]
	global_load_dwordx4 v[138:141], v[246:247], off
	global_load_dwordx4 v[142:145], v[246:247], off offset:1024
	global_load_dwordx4 v[146:149], v[246:247], off offset:2048
	global_load_dwordx4 v[150:153], v[246:247], off offset:3072
	v_lshl_add_u64 v[44:45], v[88:89], 0, s[50:51]
	v_lshl_add_u64 v[244:245], v[44:45], 0, v[120:121]
	global_load_dwordx4 v[90:93], v[244:245], off
	global_load_dwordx4 v[94:97], v[244:245], off offset:1024
	global_load_dwordx4 v[98:101], v[244:245], off offset:2048
	global_load_dwordx4 v[102:105], v[244:245], off offset:3072
	s_waitcnt vmcnt(20)
	v_mfma_f32_16x16x32_fp8_fp8 v[36:39], v[154:155], v[78:79], 0
	s_and_b32 s13, s92, 0xfffff
	v_cmp_eq_u32_e32 vcc, s12, v209
	v_add_u32_e32 v3, s13, v210
	v_mfma_f32_16x16x32_fp8_fp8 v[36:39], v[156:157], v[80:81], v[36:39]
	s_or_b64 s[18:19], s[10:11], vcc
	v_cmp_le_i32_e32 vcc, v3, v132
	s_and_b64 s[16:17], s[18:19], vcc
	v_mfma_f32_16x16x32_fp8_fp8 v[36:39], v[158:159], v[82:83], v[36:39]
	v_cmp_lt_i32_e32 vcc, v3, v132
	s_and_b64 s[12:13], s[18:19], vcc
	v_mfma_f32_16x16x32_fp8_fp8 v[40:43], v[162:163], v[78:79], 0
	v_mfma_f32_16x16x32_fp8_fp8 v[36:39], v[160:161], v[84:85], v[36:39]
	v_mfma_f32_16x16x32_fp8_fp8 v[40:43], v[164:165], v[80:81], v[40:43]
	v_mfma_f32_16x16x32_fp8_fp8 v[40:43], v[166:167], v[82:83], v[40:43]
	s_nop 3
	v_max_f32_e32 v44, v36, v36
	v_max_f32_e32 v44, 0xf149f2ca, v44
	v_cndmask_b32_e64 v44, v220, v44, s[16:17]
	v_max_f32_e32 v45, v37, v37
	v_max_f32_e32 v45, v44, v45
	v_cndmask_b32_e64 v44, v44, v45, s[12:13]
	v_add_u32_e32 v45, 2, v3
	v_cmp_le_i32_e32 vcc, v45, v132
	v_max_f32_e32 v45, v38, v38
	v_max_f32_e32 v45, v44, v45
	s_and_b64 s[14:15], s[18:19], vcc
	v_mfma_f32_16x16x32_fp8_fp8 v[40:43], v[168:169], v[84:85], v[40:43]
	v_cndmask_b32_e64 v44, v44, v45, s[14:15]
	v_add_u32_e32 v45, 3, v3
	v_cmp_le_i32_e32 vcc, v45, v132
	v_max_f32_e32 v45, v39, v39
	v_max_f32_e32 v45, v44, v45
	s_and_b64 s[10:11], s[18:19], vcc
	v_cndmask_b32_e64 v44, v44, v45, s[10:11]
	v_add_u32_e32 v45, 16, v3
	v_cmp_le_i32_e32 vcc, v45, v132
	v_max_f32_e32 v45, v40, v40
	v_max_f32_e32 v45, v44, v45
	s_and_b64 s[24:25], s[18:19], vcc
	v_cndmask_b32_e64 v44, v44, v45, s[24:25]
	v_add_u32_e32 v45, 17, v3
	v_cmp_le_i32_e32 vcc, v45, v132
	v_max_f32_e32 v45, v44, v44
	v_max_f32_e32 v46, v41, v41
	v_max_f32_e32 v45, v45, v46
	s_and_b64 s[20:21], s[18:19], vcc
	v_cndmask_b32_e64 v44, v44, v45, s[20:21]
	v_add_u32_e32 v45, 18, v3
	v_cmp_le_i32_e32 vcc, v45, v132
	v_max_f32_e32 v45, v44, v44
	v_max_f32_e32 v46, v42, v42
	v_max_f32_e32 v45, v45, v46
	s_and_b64 s[22:23], s[18:19], vcc
	v_cndmask_b32_e64 v44, v44, v45, s[22:23]
	v_add_u32_e32 v3, 19, v3
	v_cmp_le_i32_e32 vcc, v3, v132
	v_max_f32_e32 v3, v44, v44
	v_max_f32_e32 v45, v43, v43
	v_max_f32_e32 v3, v3, v45
	s_and_b64 s[18:19], s[18:19], vcc
	v_cndmask_b32_e64 v3, v44, v3, s[18:19]
	v_cmp_gt_f32_e32 vcc, v3, v2
	s_cbranch_vccz .LBB0_981
	ds_bpermute_b32 v2, v225, v3
	v_max_f32_e32 v3, v3, v3
	s_waitcnt lgkmcnt(0)
	v_max_f32_e32 v2, v2, v2
	v_max_f32_e32 v2, v3, v2
	ds_bpermute_b32 v3, v224, v2
	s_waitcnt lgkmcnt(0)
	v_max3_f32 v2, v0, v2, v3
	v_sub_f32_e32 v0, v0, v2
	v_exp_f32_e32 v0, v0
	s_nop 0
	v_mul_f32_e32 v133, v133, v0
	v_pk_mul_f32 v[10:11], v[10:11], v[0:1] op_sel_hi:[1,0]
	v_pk_mul_f32 v[8:9], v[8:9], v[0:1] op_sel_hi:[1,0]
	v_pk_mul_f32 v[14:15], v[14:15], v[0:1] op_sel_hi:[1,0]
	v_pk_mul_f32 v[12:13], v[12:13], v[0:1] op_sel_hi:[1,0]
	v_pk_mul_f32 v[18:19], v[18:19], v[0:1] op_sel_hi:[1,0]
	v_pk_mul_f32 v[16:17], v[16:17], v[0:1] op_sel_hi:[1,0]
	v_pk_mul_f32 v[22:23], v[22:23], v[0:1] op_sel_hi:[1,0]
	v_pk_mul_f32 v[20:21], v[20:21], v[0:1] op_sel_hi:[1,0]
	v_pk_mul_f32 v[26:27], v[26:27], v[0:1] op_sel_hi:[1,0]
	v_pk_mul_f32 v[24:25], v[24:25], v[0:1] op_sel_hi:[1,0]
	v_pk_mul_f32 v[34:35], v[34:35], v[0:1] op_sel_hi:[1,0]
	v_pk_mul_f32 v[32:33], v[32:33], v[0:1] op_sel_hi:[1,0]
	v_pk_mul_f32 v[30:31], v[30:31], v[0:1] op_sel_hi:[1,0]
	v_pk_mul_f32 v[28:29], v[28:29], v[0:1] op_sel_hi:[1,0]
	v_pk_mul_f32 v[6:7], v[6:7], v[0:1] op_sel_hi:[1,0]
	v_pk_mul_f32 v[4:5], v[4:5], v[0:1] op_sel_hi:[1,0]
	v_mov_b32_e32 v0, v2
.LBB0_981:
	v_add_f32_e32 v2, -4.0, v0
	v_sub_f32_e32 v3, v36, v2
	v_exp_f32_e32 v3, v3
	v_sub_f32_e32 v36, v40, v2
	v_exp_f32_e32 v36, v36
	v_mov_b32_e32 v203, v0
	v_cndmask_b32_e64 v56, 0, v3, s[16:17]
	v_sub_f32_e32 v3, v37, v2
	v_cndmask_b32_e64 v57, 0, v36, s[24:25]
	v_exp_f32_e32 v3, v3
	v_sub_f32_e32 v36, v41, v2
	v_sub_f32_e32 v37, v38, v2
	v_exp_f32_e32 v36, v36
	v_exp_f32_e32 v37, v37
	v_sub_f32_e32 v38, v42, v2
	v_cndmask_b32_e64 v58, 0, v3, s[12:13]
	v_sub_f32_e32 v3, v39, v2
	v_sub_f32_e32 v2, v43, v2
	v_exp_f32_e32 v38, v38
	v_cndmask_b32_e64 v59, 0, v36, s[20:21]
	v_cndmask_b32_e64 v60, 0, v37, s[14:15]
	v_exp_f32_e32 v36, v3
	v_exp_f32_e32 v37, v2
	v_mov_b32_e32 v2, v1
	v_mov_b32_e32 v3, v1
	v_cvt_pk_fp8_f32 v2, v56, v58
	v_cvt_pk_fp8_f32 v3, v57, v59
	v_cndmask_b32_e64 v61, 0, v38, s[22:23]
	v_cndmask_b32_e64 v64, 0, v36, s[10:11]
	v_cndmask_b32_e64 v65, 0, v37, s[18:19]
	v_cvt_pk_fp8_f32 v2, v60, v64 op_sel:[0,0,1]
	v_cvt_pk_fp8_f32 v3, v61, v65 op_sel:[0,0,1]
	s_nop 0
	s_waitcnt vmcnt(19)
	v_mfma_f32_16x16x32_fp8_fp8 v[36:39], v[106:107], v[2:3], v[8:11]
	s_nop 2
	v_add_f32_e32 v8, v56, v57
	v_add_f32_e32 v8, 0, v8
	v_add_f32_e32 v9, v58, v59
	v_add_f32_e32 v8, v9, v8
	v_add_f32_e32 v9, v60, v61
	v_mfma_f32_16x16x32_fp8_fp8 v[40:43], v[108:109], v[2:3], v[12:15]
	v_add_f32_e32 v8, v9, v8
	v_add_f32_e32 v9, v64, v65
	v_add_f32_e32 v8, v9, v8
	s_waitcnt vmcnt(18)
	v_mfma_f32_16x16x32_fp8_fp8 v[44:47], v[110:111], v[2:3], v[16:19]
	v_add_f32_e32 v204, v133, v8
	v_mfma_f32_16x16x32_fp8_fp8 v[48:51], v[112:113], v[2:3], v[20:23]
	s_waitcnt vmcnt(17)
	v_mfma_f32_16x16x32_fp8_fp8 v[52:55], v[114:115], v[2:3], v[24:27]
	v_mfma_f32_16x16x32_fp8_fp8 v[56:59], v[116:117], v[2:3], v[32:35]
	s_waitcnt vmcnt(16)
	v_mfma_f32_16x16x32_fp8_fp8 v[60:63], v[134:135], v[2:3], v[28:31]
	v_mfma_f32_16x16x32_fp8_fp8 v[64:67], v[136:137], v[2:3], v[4:7]
	s_andn2_b64 vcc, exec, s[26:27]
	s_mov_b64 s[10:11], -1
	s_cbranch_vccnz .LBB0_961
; template <bool SLC, bool NOMASK> ...
;     const int kq = lane >> 4;
;     const int pos0 = SLC ? (dcur & 0xfffff) : dcur;
;     const int lo = SLC ? ((((dcur >> 20) == qi) | ((dcur >> 20) == 4)) ? 0 : (1 << 30)) : lo_in;
;     load_frag8(nxt, KF, VF, SLC ? (dnext & 0xfffff) : dnext, lane);
;     f32x4 sa[2] = {(f32x4){0.f, 0.f, 0.f, 0.f}, (f32x4){0.f, 0.f, 0.f, 0.f}};
; #pragma unroll
;     for (int T = 0; T < 2; ++T)
; #pragma unroll
;         for (int s2 = 0; s2 < 4; ++s2) sa[T] = __builtin_amdgcn_mfma_f32_16x16x32_fp8_fp8(cur.k[T][s2], qf[s2], sa[T], 0, 0, 0);
;     float sc[8]; bool vd[8]; float mx = -1e30f;
;     const bool act = lo == 0 || !SLC;
;     if (NOMASK) {
; #pragma unroll
;         for (int j = 0; j < 8; ++j) { sc[j] = sa[j >> 2][j & 3]; vd[j] = act; }
;         mx = fmaxf(fmaxf(fmaxf(sc[0], sc[1]), fmaxf(sc[2], sc[3])), fmaxf(fmaxf(sc[4], sc[5]), fmaxf(sc[6], sc[7])));
;         mx = act ? mx : -1e30f;
;     } else {
; #pragma unroll
;         for (int T = 0; T < 2; ++T)
; #pragma unroll
;             for (int r = 0; r < 4; ++r) { const int p = pos0 + 16 * T + 4 * kq + r; const bool v = (p >= lo) & (p <= hi); const float x = sa[T][r];
;                 sc[4 * T + r] = x; vd[4 * T + r] = v; mx = v ? fmaxf(mx, x) : mx; }
;     }
;     if (__builtin_amdgcn_ballot_w64(mx > st.m + 4.f) != 0ull) {
;         mx = fmaxf(mx, __shfl_xor(mx, 16)); mx = fmaxf(mx, __shfl_xor(mx, 32));
;         const float mn = fmaxf(st.m, mx), alpha = __builtin_amdgcn_exp2f(st.m - mn); st.m = mn; st.l *= alpha;
; #pragma unroll
;         for (int j = 0; j < 8; ++j) st.o[j] = st.o[j] * alpha;
;     }
;     f32x4 pa, pb; float ps = 0.f;
;     const float mref = st.m - 4.f;
;     if (NOMASK) {
; #pragma unroll
;         for (int j = 0; j < 4; ++j) { pa[j] = __builtin_amdgcn_exp2f(sc[j] - mref); pb[j] = __builtin_amdgcn_exp2f(sc[4 + j] - mref); }
;         if (SLC) {
; #pragma unroll
;             for (int j = 0; j < 4; ++j) { pa[j] = act ? pa[j] : 0.f; pb[j] = act ? pb[j] : 0.f; }
;         }
; #pragma unroll
;         for (int j = 0; j < 4; ++j) ps += pa[j] + pb[j];
;     } else {
; #pragma unroll
;         for (int j = 0; j < 4; ++j) { pa[j] = vd[j] ? __builtin_amdgcn_exp2f(sc[j] - mref) : 0.f; pb[j] = vd[4 + j] ? __builtin_amdgcn_exp2f(sc[4 + j] - mref) : 0.f; ps += pa[j] + pb[j]; }
;     }
;     st.l += ps;
;     const u32x2 pw = pack8_fp8(pa, pb);
.LBB0_982:
	s_cmp_lt_u32 s56, s54
	s_cselect_b32 s10, s56, s55
	s_lshl_b32 s10, s10, 2
	s_add_i32 s10, s3, s10
	v_mov_b32_e32 v0, s10
	ds_read_b32 v0, v0 offset:13632
	s_and_b32 s13, s66, 2.0
	s_ashr_i32 s12, s66, 20
	s_mov_b64 s[10:11], -1
	s_cmp_eq_u32 s13, 0
	s_waitcnt lgkmcnt(0)
	v_readfirstlane_b32 s92, v0
	v_add_f32_e32 v0, 4.0, v203
	s_cbranch_scc1 .LBB0_986
	s_and_b32 s13, s12, 0xfffffbff
	s_cmp_eq_u32 s13, 4
	s_cselect_b64 s[10:11], -1, 0
	s_lshl_b32 s14, s92, 7
	s_and_b32 s50, s14, 0x7fff800
	v_lshl_add_u64 v[10:11], v[86:87], 0, s[50:51]
	s_and_b32 s50, s14, 0x7fff000
	v_lshl_add_u64 v[246:247], v[10:11], 0, v[120:121]
	global_load_dwordx4 v[154:157], v[246:247], off
	global_load_dwordx4 v[158:161], v[246:247], off offset:1024
	global_load_dwordx4 v[162:165], v[246:247], off offset:2048
	global_load_dwordx4 v[166:169], v[246:247], off offset:3072
	v_lshl_add_u64 v[10:11], v[88:89], 0, s[50:51]
	v_lshl_add_u64 v[244:245], v[10:11], 0, v[120:121]
	global_load_dwordx4 v[106:109], v[244:245], off
	global_load_dwordx4 v[110:113], v[244:245], off offset:1024
	global_load_dwordx4 v[114:117], v[244:245], off offset:2048
	global_load_dwordx4 v[134:137], v[244:245], off offset:3072
	s_waitcnt vmcnt(20)
	v_mfma_f32_16x16x32_fp8_fp8 v[2:5], v[186:187], v[78:79], 0
	v_cmp_eq_u32_e32 vcc, s13, v209
	s_or_b64 s[10:11], s[10:11], vcc
	v_mov_b64_e32 v[74:75], v[66:67]
	v_mfma_f32_16x16x32_fp8_fp8 v[6:9], v[194:195], v[78:79], 0
	v_mov_b64_e32 v[70:71], v[62:63]
	v_mov_b64_e32 v[30:31], v[56:57]
	v_mov_b64_e32 v[26:27], v[52:53]
	v_mfma_f32_16x16x32_fp8_fp8 v[2:5], v[188:189], v[80:81], v[2:5]
	v_mov_b64_e32 v[22:23], v[48:49]
	v_mov_b64_e32 v[18:19], v[44:45]
	v_mov_b64_e32 v[14:15], v[40:41]
	v_mfma_f32_16x16x32_fp8_fp8 v[6:9], v[196:197], v[80:81], v[6:9]
	v_mov_b32_e32 v202, v203
	v_mov_b64_e32 v[72:73], v[64:65]
	v_mov_b64_e32 v[68:69], v[60:61]
	v_mfma_f32_16x16x32_fp8_fp8 v[2:5], v[190:191], v[82:83], v[2:5]
	v_mov_b64_e32 v[32:33], v[58:59]
	v_mov_b64_e32 v[28:29], v[54:55]
	v_mov_b64_e32 v[24:25], v[50:51]
	v_mfma_f32_16x16x32_fp8_fp8 v[6:9], v[198:199], v[82:83], v[6:9]
	v_mov_b64_e32 v[20:21], v[46:47]
	v_mov_b64_e32 v[16:17], v[42:43]
	v_mov_b32_e32 v133, v204
	v_mfma_f32_16x16x32_fp8_fp8 v[2:5], v[192:193], v[84:85], v[2:5]
	v_mfma_f32_16x16x32_fp8_fp8 v[6:9], v[200:201], v[84:85], v[6:9]
	s_nop 5
	v_max_f32_e32 v10, v3, v3
	v_max_f32_e32 v11, v2, v2
	v_max_f32_e32 v10, v11, v10
	v_max_f32_e32 v11, v5, v5
	v_max_f32_e32 v12, v4, v4
	v_max_f32_e32 v11, v12, v11
	v_max_f32_e32 v12, v9, v9
	v_max_f32_e32 v13, v8, v8
	v_max_f32_e32 v12, v13, v12
	v_max3_f32 v12, v6, v7, v12
	v_max3_f32 v10, v10, v11, v12
	v_cndmask_b32_e64 v34, v220, v10, s[10:11]
	v_mov_b64_e32 v[10:11], v[36:37]
	v_cmp_gt_f32_e32 vcc, v34, v0
	v_mov_b64_e32 v[12:13], v[38:39]
	s_cbranch_vccz .LBB0_985
	ds_bpermute_b32 v10, v225, v34
	v_max_f32_e32 v11, v34, v34
	s_waitcnt lgkmcnt(0)
	v_max_f32_e32 v10, v10, v10
	v_max_f32_e32 v10, v11, v10
	ds_bpermute_b32 v11, v224, v10
	s_waitcnt lgkmcnt(0)
	v_max3_f32 v202, v203, v10, v11
	v_sub_f32_e32 v10, v203, v202
	v_exp_f32_e32 v34, v10
	s_nop 0
	v_mul_f32_e32 v133, v204, v34
	v_pk_mul_f32 v[12:13], v[38:39], v[34:35] op_sel_hi:[1,0]
	v_pk_mul_f32 v[10:11], v[36:37], v[34:35] op_sel_hi:[1,0]
	v_pk_mul_f32 v[16:17], v[42:43], v[34:35] op_sel_hi:[1,0]
	v_pk_mul_f32 v[14:15], v[40:41], v[34:35] op_sel_hi:[1,0]
	v_pk_mul_f32 v[20:21], v[46:47], v[34:35] op_sel_hi:[1,0]
	v_pk_mul_f32 v[18:19], v[44:45], v[34:35] op_sel_hi:[1,0]
	v_pk_mul_f32 v[24:25], v[50:51], v[34:35] op_sel_hi:[1,0]
	v_pk_mul_f32 v[22:23], v[48:49], v[34:35] op_sel_hi:[1,0]
	v_pk_mul_f32 v[28:29], v[54:55], v[34:35] op_sel_hi:[1,0]
	v_pk_mul_f32 v[26:27], v[52:53], v[34:35] op_sel_hi:[1,0]
	v_pk_mul_f32 v[32:33], v[58:59], v[34:35] op_sel_hi:[1,0]
	v_pk_mul_f32 v[30:31], v[56:57], v[34:35] op_sel_hi:[1,0]
	v_pk_mul_f32 v[70:71], v[62:63], v[34:35] op_sel_hi:[1,0]
	v_pk_mul_f32 v[68:69], v[60:61], v[34:35] op_sel_hi:[1,0]
	v_pk_mul_f32 v[74:75], v[66:67], v[34:35] op_sel_hi:[1,0]
	v_pk_mul_f32 v[72:73], v[64:65], v[34:35] op_sel_hi:[1,0]
.LBB0_985:
	v_add_f32_e32 v34, -4.0, v202
	v_sub_f32_e32 v2, v2, v34
	v_sub_f32_e32 v6, v6, v34
	v_sub_f32_e32 v3, v3, v34
	v_sub_f32_e32 v7, v7, v34
	v_exp_f32_e32 v2, v2
	v_exp_f32_e32 v6, v6
	v_exp_f32_e32 v3, v3
	v_exp_f32_e32 v7, v7
	v_sub_f32_e32 v4, v4, v34
	v_sub_f32_e32 v8, v8, v34
	v_sub_f32_e32 v5, v5, v34
	v_sub_f32_e32 v9, v9, v34
	v_exp_f32_e32 v4, v4
	v_exp_f32_e32 v8, v8
	v_exp_f32_e32 v5, v5
	v_exp_f32_e32 v9, v9
	v_cndmask_b32_e64 v34, 0, v2, s[10:11]
	v_cndmask_b32_e64 v6, 0, v6, s[10:11]
	v_cndmask_b32_e64 v35, 0, v3, s[10:11]
	v_cndmask_b32_e64 v7, 0, v7, s[10:11]
	v_mov_b32_e32 v2, v1
	v_mov_b32_e32 v3, v1
	v_cvt_pk_fp8_f32 v2, v34, v35
	v_cvt_pk_fp8_f32 v3, v6, v7
	v_cndmask_b32_e64 v4, 0, v4, s[10:11]
	v_cndmask_b32_e64 v205, 0, v8, s[10:11]
	v_cndmask_b32_e64 v5, 0, v5, s[10:11]
	v_cndmask_b32_e64 v227, 0, v9, s[10:11]
	v_add_f32_e32 v6, v34, v6
	v_cvt_pk_fp8_f32 v2, v4, v5 op_sel:[0,0,1]
	v_cvt_pk_fp8_f32 v3, v205, v227 op_sel:[0,0,1]
	v_add_f32_e32 v6, 0, v6
	v_add_f32_e32 v7, v35, v7
	v_add_f32_e32 v6, v7, v6
	v_add_f32_e32 v4, v4, v205
	v_add_f32_e32 v4, v4, v6
	v_add_f32_e32 v5, v5, v227
	v_add_f32_e32 v4, v5, v4
	s_waitcnt vmcnt(19)
	v_mfma_f32_16x16x32_fp8_fp8 v[8:11], v[170:171], v[2:3], v[10:13]
	v_add_f32_e32 v133, v133, v4
	s_mov_b64 s[10:11], 0
	v_mfma_f32_16x16x32_fp8_fp8 v[12:15], v[172:173], v[2:3], v[14:17]
	s_waitcnt vmcnt(18)
	v_mfma_f32_16x16x32_fp8_fp8 v[16:19], v[174:175], v[2:3], v[18:21]
	v_mfma_f32_16x16x32_fp8_fp8 v[20:23], v[176:177], v[2:3], v[22:25]
	s_waitcnt vmcnt(17)
	v_mfma_f32_16x16x32_fp8_fp8 v[24:27], v[178:179], v[2:3], v[26:29]
	v_mfma_f32_16x16x32_fp8_fp8 v[32:35], v[180:181], v[2:3], v[30:33]
	s_waitcnt vmcnt(16)
	v_mfma_f32_16x16x32_fp8_fp8 v[28:31], v[182:183], v[2:3], v[68:71]
	v_mfma_f32_16x16x32_fp8_fp8 v[4:7], v[184:185], v[2:3], v[72:75]
; template <bool SLC, bool NOMASK> ...
;     const int kq = lane >> 4;
;     const int pos0 = SLC ? (dcur & 0xfffff) : dcur;
;     const int lo = SLC ? ((((dcur >> 20) == qi) | ((dcur >> 20) == 4)) ? 0 : (1 << 30)) : lo_in;
;     load_frag8(nxt, KF, VF, SLC ? (dnext & 0xfffff) : dnext, lane);
;     f32x4 sa[2] = {(f32x4){0.f, 0.f, 0.f, 0.f}, (f32x4){0.f, 0.f, 0.f, 0.f}};
; #pragma unroll
;     for (int T = 0; T < 2; ++T)
; #pragma unroll
;         for (int s2 = 0; s2 < 4; ++s2) sa[T] = __builtin_amdgcn_mfma_f32_16x16x32_fp8_fp8(cur.k[T][s2], qf[s2], sa[T], 0, 0, 0);
;     float sc[8]; bool vd[8]; float mx = -1e30f;
;     const bool act = lo == 0 || !SLC;
;     if (NOMASK) {
; #pragma unroll
;         for (int j = 0; j < 8; ++j) { sc[j] = sa[j >> 2][j & 3]; vd[j] = act; }
;         mx = fmaxf(fmaxf(fmaxf(sc[0], sc[1]), fmaxf(sc[2], sc[3])), fmaxf(fmaxf(sc[4], sc[5]), fmaxf(sc[6], sc[7])));
;         mx = act ? mx : -1e30f;
;     } else {
; #pragma unroll
;         for (int T = 0; T < 2; ++T)
; #pragma unroll
;             for (int r = 0; r < 4; ++r) { const int p = pos0 + 16 * T + 4 * kq + r; const bool v = (p >= lo) & (p <= hi); const float x = sa[T][r];
;                 sc[4 * T + r] = x; vd[4 * T + r] = v; mx = v ? fmaxf(mx, x) : mx; }
;     }
;     if (__builtin_amdgcn_ballot_w64(mx > st.m + 4.f) != 0ull) {
;         mx = fmaxf(mx, __shfl_xor(mx, 16)); mx = fmaxf(mx, __shfl_xor(mx, 32));
;         const float mn = fmaxf(st.m, mx), alpha = __builtin_amdgcn_exp2f(st.m - mn); st.m = mn; st.l *= alpha;
; #pragma unroll
;         for (int j = 0; j < 8; ++j) st.o[j] = st.o[j] * alpha;
;     }
;     f32x4 pa, pb; float ps = 0.f;
;     const float mref = st.m - 4.f;
;     if (NOMASK) {
; #pragma unroll
;         for (int j = 0; j < 4; ++j) { pa[j] = __builtin_amdgcn_exp2f(sc[j] - mref); pb[j] = __builtin_amdgcn_exp2f(sc[4 + j] - mref); }
;         if (SLC) {
; #pragma unroll
;             for (int j = 0; j < 4; ++j) { pa[j] = act ? pa[j] : 0.f; pb[j] = act ? pb[j] : 0.f; }
;         }
; #pragma unroll
;         for (int j = 0; j < 4; ++j) ps += pa[j] + pb[j];
;     } else {
; #pragma unroll
;         for (int j = 0; j < 4; ++j) { pa[j] = vd[j] ? __builtin_amdgcn_exp2f(sc[j] - mref) : 0.f; pb[j] = vd[4 + j] ? __builtin_amdgcn_exp2f(sc[4 + j] - mref) : 0.f; ps += pa[j] + pb[j]; }
;     }
;     st.l += ps;
;     const u32x2 pw = pack8_fp8(pa, pb);
.LBB0_986:
	s_and_b64 vcc, exec, s[10:11]
	s_cbranch_vccz .LBB0_990
	s_cmp_eq_u32 s12, 4
	s_cselect_b64 s[10:11], -1, 0
	s_lshl_b32 s13, s92, 7
	s_and_b32 s50, s13, 0x7fff800
	v_lshl_add_u64 v[10:11], v[86:87], 0, s[50:51]
	s_and_b32 s50, s13, 0x7fff000
	v_lshl_add_u64 v[246:247], v[10:11], 0, v[120:121]
	global_load_dwordx4 v[154:157], v[246:247], off
	global_load_dwordx4 v[158:161], v[246:247], off offset:1024
	global_load_dwordx4 v[162:165], v[246:247], off offset:2048
	global_load_dwordx4 v[166:169], v[246:247], off offset:3072
	v_lshl_add_u64 v[10:11], v[88:89], 0, s[50:51]
	v_lshl_add_u64 v[244:245], v[10:11], 0, v[120:121]
	global_load_dwordx4 v[106:109], v[244:245], off
	global_load_dwordx4 v[110:113], v[244:245], off offset:1024
	global_load_dwordx4 v[114:117], v[244:245], off offset:2048
	global_load_dwordx4 v[134:137], v[244:245], off offset:3072
	s_waitcnt vmcnt(20)
	v_mfma_f32_16x16x32_fp8_fp8 v[2:5], v[186:187], v[78:79], 0
	s_and_b32 s13, s66, 0xfffff
	v_cmp_eq_u32_e32 vcc, s12, v209
	v_add_u32_e32 v10, s13, v210
	v_mfma_f32_16x16x32_fp8_fp8 v[2:5], v[188:189], v[80:81], v[2:5]
	s_or_b64 s[18:19], s[10:11], vcc
	v_cmp_le_i32_e32 vcc, v10, v132
	s_and_b64 s[16:17], s[18:19], vcc
	v_mfma_f32_16x16x32_fp8_fp8 v[2:5], v[190:191], v[82:83], v[2:5]
	v_cmp_lt_i32_e32 vcc, v10, v132
	s_and_b64 s[12:13], s[18:19], vcc
	v_mfma_f32_16x16x32_fp8_fp8 v[6:9], v[194:195], v[78:79], 0
	v_mfma_f32_16x16x32_fp8_fp8 v[2:5], v[192:193], v[84:85], v[2:5]
	v_mfma_f32_16x16x32_fp8_fp8 v[6:9], v[196:197], v[80:81], v[6:9]
	v_mfma_f32_16x16x32_fp8_fp8 v[6:9], v[198:199], v[82:83], v[6:9]
	s_nop 3
	v_max_f32_e32 v11, v2, v2
	v_max_f32_e32 v11, 0xf149f2ca, v11
	v_cndmask_b32_e64 v11, v220, v11, s[16:17]
	v_max_f32_e32 v12, v3, v3
	v_max_f32_e32 v12, v11, v12
	v_cndmask_b32_e64 v11, v11, v12, s[12:13]
	v_add_u32_e32 v12, 2, v10
	v_cmp_le_i32_e32 vcc, v12, v132
	v_max_f32_e32 v12, v4, v4
	v_max_f32_e32 v12, v11, v12
	s_and_b64 s[14:15], s[18:19], vcc
	v_mfma_f32_16x16x32_fp8_fp8 v[6:9], v[200:201], v[84:85], v[6:9]
	v_cndmask_b32_e64 v11, v11, v12, s[14:15]
	v_add_u32_e32 v12, 3, v10
	v_cmp_le_i32_e32 vcc, v12, v132
	v_max_f32_e32 v12, v5, v5
	v_max_f32_e32 v12, v11, v12
	s_and_b64 s[10:11], s[18:19], vcc
	v_cndmask_b32_e64 v11, v11, v12, s[10:11]
	v_add_u32_e32 v12, 16, v10
	v_cmp_le_i32_e32 vcc, v12, v132
	v_max_f32_e32 v12, v6, v6
	v_max_f32_e32 v12, v11, v12
	s_and_b64 s[24:25], s[18:19], vcc
	v_cndmask_b32_e64 v11, v11, v12, s[24:25]
	v_add_u32_e32 v12, 17, v10
	v_cmp_le_i32_e32 vcc, v12, v132
	v_max_f32_e32 v12, v11, v11
	v_max_f32_e32 v13, v7, v7
	v_max_f32_e32 v12, v12, v13
	s_and_b64 s[20:21], s[18:19], vcc
	v_cndmask_b32_e64 v11, v11, v12, s[20:21]
	v_add_u32_e32 v12, 18, v10
	v_cmp_le_i32_e32 vcc, v12, v132
	v_max_f32_e32 v12, v11, v11
	v_max_f32_e32 v13, v8, v8
	v_max_f32_e32 v12, v12, v13
	s_and_b64 s[22:23], s[18:19], vcc
	v_cndmask_b32_e64 v11, v11, v12, s[22:23]
	v_add_u32_e32 v10, 19, v10
	v_cmp_le_i32_e32 vcc, v10, v132
	v_max_f32_e32 v10, v11, v11
	v_max_f32_e32 v12, v9, v9
	v_max_f32_e32 v10, v10, v12
	s_and_b64 s[18:19], s[18:19], vcc
	v_cndmask_b32_e64 v10, v11, v10, s[18:19]
	v_cmp_gt_f32_e32 vcc, v10, v0
	s_cbranch_vccz .LBB0_989
	ds_bpermute_b32 v0, v225, v10
	v_max_f32_e32 v10, v10, v10
	s_waitcnt lgkmcnt(0)
	v_max_f32_e32 v0, v0, v0
	v_max_f32_e32 v0, v10, v0
	ds_bpermute_b32 v10, v224, v0
	s_waitcnt lgkmcnt(0)
	v_max3_f32 v10, v203, v0, v10
	v_sub_f32_e32 v0, v203, v10
	v_exp_f32_e32 v0, v0
	v_mov_b32_e32 v203, v10
	v_mul_f32_e32 v204, v204, v0
	v_pk_mul_f32 v[38:39], v[38:39], v[0:1] op_sel_hi:[1,0]
	v_pk_mul_f32 v[36:37], v[36:37], v[0:1] op_sel_hi:[1,0]
	v_pk_mul_f32 v[42:43], v[42:43], v[0:1] op_sel_hi:[1,0]
	v_pk_mul_f32 v[40:41], v[40:41], v[0:1] op_sel_hi:[1,0]
	v_pk_mul_f32 v[46:47], v[46:47], v[0:1] op_sel_hi:[1,0]
	v_pk_mul_f32 v[44:45], v[44:45], v[0:1] op_sel_hi:[1,0]
	v_pk_mul_f32 v[50:51], v[50:51], v[0:1] op_sel_hi:[1,0]
	v_pk_mul_f32 v[48:49], v[48:49], v[0:1] op_sel_hi:[1,0]
	v_pk_mul_f32 v[54:55], v[54:55], v[0:1] op_sel_hi:[1,0]
	v_pk_mul_f32 v[52:53], v[52:53], v[0:1] op_sel_hi:[1,0]
	v_pk_mul_f32 v[58:59], v[58:59], v[0:1] op_sel_hi:[1,0]
	v_pk_mul_f32 v[56:57], v[56:57], v[0:1] op_sel_hi:[1,0]
	v_pk_mul_f32 v[62:63], v[62:63], v[0:1] op_sel_hi:[1,0]
	v_pk_mul_f32 v[60:61], v[60:61], v[0:1] op_sel_hi:[1,0]
	v_pk_mul_f32 v[66:67], v[66:67], v[0:1] op_sel_hi:[1,0]
	v_pk_mul_f32 v[64:65], v[64:65], v[0:1] op_sel_hi:[1,0]
.LBB0_989:
	v_add_f32_e32 v0, -4.0, v203
	v_sub_f32_e32 v2, v2, v0
	v_exp_f32_e32 v2, v2
	v_sub_f32_e32 v6, v6, v0
	v_exp_f32_e32 v6, v6
	v_sub_f32_e32 v4, v4, v0
	v_cndmask_b32_e64 v28, 0, v2, s[16:17]
	v_sub_f32_e32 v2, v3, v0
	v_exp_f32_e32 v2, v2
	v_sub_f32_e32 v3, v7, v0
	v_exp_f32_e32 v3, v3
	v_sub_f32_e32 v7, v8, v0
	v_cndmask_b32_e64 v29, 0, v2, s[12:13]
	v_sub_f32_e32 v2, v5, v0
	v_sub_f32_e32 v0, v9, v0
	v_cndmask_b32_e64 v6, 0, v6, s[24:25]
	v_exp_f32_e32 v4, v4
	v_exp_f32_e32 v7, v7
	v_cndmask_b32_e64 v30, 0, v3, s[20:21]
	v_exp_f32_e32 v5, v2
	v_exp_f32_e32 v0, v0
	v_mov_b32_e32 v2, v1
	v_mov_b32_e32 v3, v1
	v_cvt_pk_fp8_f32 v2, v28, v29
	v_cvt_pk_fp8_f32 v3, v6, v30
	v_cndmask_b32_e64 v4, 0, v4, s[14:15]
	v_cndmask_b32_e64 v7, 0, v7, s[22:23]
	v_cndmask_b32_e64 v5, 0, v5, s[10:11]
	v_cndmask_b32_e64 v0, 0, v0, s[18:19]
	v_cvt_pk_fp8_f32 v2, v4, v5 op_sel:[0,0,1]
	v_cvt_pk_fp8_f32 v3, v7, v0 op_sel:[0,0,1]
	v_add_f32_e32 v6, v28, v6
	v_add_f32_e32 v6, 0, v6
	v_add_f32_e32 v28, v29, v30
	v_add_f32_e32 v6, v28, v6
	v_add_f32_e32 v4, v4, v7
	v_add_f32_e32 v4, v4, v6
	v_add_f32_e32 v0, v5, v0
	s_waitcnt vmcnt(19)
	v_mfma_f32_16x16x32_fp8_fp8 v[8:11], v[170:171], v[2:3], v[36:39]
	v_add_f32_e32 v0, v0, v4
	v_add_f32_e32 v133, v204, v0
	v_mov_b32_e32 v202, v203
	v_mfma_f32_16x16x32_fp8_fp8 v[12:15], v[172:173], v[2:3], v[40:43]
	s_waitcnt vmcnt(18)
	v_mfma_f32_16x16x32_fp8_fp8 v[16:19], v[174:175], v[2:3], v[44:47]
	v_mfma_f32_16x16x32_fp8_fp8 v[20:23], v[176:177], v[2:3], v[48:51]
	s_waitcnt vmcnt(17)
	v_mfma_f32_16x16x32_fp8_fp8 v[24:27], v[178:179], v[2:3], v[52:55]
	v_mfma_f32_16x16x32_fp8_fp8 v[32:35], v[180:181], v[2:3], v[56:59]
	s_waitcnt vmcnt(16)
	v_mfma_f32_16x16x32_fp8_fp8 v[28:31], v[182:183], v[2:3], v[60:63]
	v_mfma_f32_16x16x32_fp8_fp8 v[4:7], v[184:185], v[2:3], v[64:67]

; __device__ __forceinline__ unsigned cvt_pk_bf16(float lo, float hi) { f32x2 v = {lo, hi}; bf16x2_t b = __builtin_convertvector(v, bf16x2_t); return __builtin_bit_cast(unsigned, b); }
; __device__ __forceinline__ float bf2f(unsigned short b) { return __uint_as_float(((unsigned)b) << 16); }
; __device__ __forceinline__ float bflo(unsigned w) { return __uint_as_float(w << 16); }
; __device__ __forceinline__ float bfhi(unsigned w) { return __uint_as_float(w & 0xffff0000u); }
; __device__ __forceinline__ float quad_total(float v) { v += __shfl_xor(v, 16); v += __shfl_xor(v, 32); return v; }
; __device__ __forceinline__ void nsa_unit(int unit, const bf16_t* proj, const bf16_t* kc, const bf16_t* vc, const bf16_t* gn, const float* cs, const float* sn, ...
;     ...
;     { const float g1 = bf2f(gn[(size_t)tc * 32 + head * 3 + 1]); const float lt = quad_total(st.l), inv = (lt > 0.f ? 1.f / lt : 0.f) * g1;
; #pragma unroll
;         for (int i = 0; i < 8; ++i) { const f32x4 o = st.o[i] * inv; u32x2 w = outl[64 * i]; w.x = cvt_pk_bf16(bflo(w.x) + o[0], bfhi(w.x) + o[1]); w.y = cvt_pk_bf16(bflo(w.y) + o[2], bfhi(w.y) + o[3]); outl[64 * i] = w; } }
;     astate_init(st);
;     { const int lo = tc - 511 < 0 ? 0 : tc - 511; const int first = t0 < 511 ? 0 : (t0 - 511) >> 5, last = (t0 + 3) >> 5;
;       auto desc = [&](int i) { const int p0 = 32 * (first + i); return p0 | ((p0 >= t0 + 3 - 511 && p0 + 31 <= t0) ? (1 << 30) : 0); };
;       unsigned long long goff = (unsigned long long)g * S * 128; asm volatile("" : "+s"(goff));
;       attn_run_frag8<false>(q8, (const unsigned char*)kslf + ((size_t)16 << 20) + goff, (const unsigned char*)kslf + ((size_t)24 << 20) + goff, desc, last - first + 1, lo, tc, 0, st, lane); }
.LBB0_992:
	s_waitcnt vmcnt(8)
	global_load_ushort v0, v[76:77], off offset:2
	ds_bpermute_b32 v2, v225, v133
	ds_read2st64_b64 v[36:39], v226 offset0:27 offset1:28
	ds_read2st64_b64 v[40:43], v226 offset0:29 offset1:30
	ds_read2st64_b64 v[44:47], v226 offset0:31 offset1:32
	ds_read2st64_b64 v[48:51], v226 offset0:33 offset1:34
	s_mov_b32 s56, 0
	s_waitcnt lgkmcnt(3)
	v_and_b32_e32 v3, 0xffff0000, v36
	v_lshlrev_b32_e32 v52, 16, v38
	v_add_f32_e32 v64, v133, v2
	ds_bpermute_b32 v65, v224, v64
	v_lshlrev_b32_e32 v2, 16, v36
	v_lshlrev_b32_e32 v36, 16, v37
	v_and_b32_e32 v37, 0xffff0000, v37
	v_and_b32_e32 v53, 0xffff0000, v38
	s_waitcnt lgkmcnt(0)
	v_add_f32_e32 v64, v64, v65
	v_div_scale_f32 v65, s[10:11], v64, v64, 1.0
	v_rcp_f32_e32 v66, v65
	v_div_scale_f32 v67, vcc, 1.0, v64, 1.0
	v_lshlrev_b32_e32 v38, 16, v39
	v_fma_f32 v68, -v65, v66, 1.0
	v_fmac_f32_e32 v66, v68, v66
	v_mul_f32_e32 v68, v67, v66
	v_fma_f32 v69, -v65, v68, v67
	v_fmac_f32_e32 v68, v69, v66
	v_fma_f32 v65, -v65, v68, v67
	v_div_fmas_f32 v65, v65, v66, v68
	v_div_fixup_f32 v65, v65, v64, 1.0
	v_cmp_lt_f32_e32 vcc, 0, v64
	v_and_b32_e32 v39, 0xffff0000, v39
	v_lshlrev_b32_e32 v54, 16, v40
	v_cndmask_b32_e32 v64, 0, v65, vcc
	v_and_b32_e32 v55, 0xffff0000, v40
	v_lshlrev_b32_e32 v40, 16, v41
	v_and_b32_e32 v41, 0xffff0000, v41
	v_lshlrev_b32_e32 v56, 16, v42
	v_and_b32_e32 v57, 0xffff0000, v42
	v_lshlrev_b32_e32 v42, 16, v43
	v_and_b32_e32 v43, 0xffff0000, v43
	v_lshlrev_b32_e32 v58, 16, v44
	v_and_b32_e32 v59, 0xffff0000, v44
	v_lshlrev_b32_e32 v44, 16, v45
	v_and_b32_e32 v45, 0xffff0000, v45
	v_lshlrev_b32_e32 v60, 16, v46
	v_and_b32_e32 v61, 0xffff0000, v46
	v_lshlrev_b32_e32 v46, 16, v47
	v_and_b32_e32 v47, 0xffff0000, v47
	v_lshlrev_b32_e32 v62, 16, v48
	v_and_b32_e32 v63, 0xffff0000, v48
	v_lshlrev_b32_e32 v48, 16, v49
	v_and_b32_e32 v49, 0xffff0000, v49
	s_add_i32 s10, s90, 0xfffffe01
	s_lshr_b32 s10, s10, 5
	s_cmpk_gt_i32 s90, 0x1fe
	s_cselect_b32 s26, s10, 0
	s_ashr_i32 s15, s91, 3
	s_sub_i32 s27, s15, s26
	s_mov_b64 s[12:13], s[52:53]
	s_cmp_lt_i32 s27, 0
	s_waitcnt vmcnt(0)
	v_lshlrev_b32_e32 v0, 16, v0
	v_mul_f32_e32 v0, v64, v0
	v_pk_fma_f32 v[2:3], v[8:9], v[0:1], v[2:3] op_sel_hi:[1,0,1]
	v_pk_fma_f32 v[8:9], v[10:11], v[0:1], v[36:37] op_sel_hi:[1,0,1]
	v_pk_fma_f32 v[10:11], v[12:13], v[0:1], v[52:53] op_sel_hi:[1,0,1]
	v_pk_fma_f32 v[12:13], v[14:15], v[0:1], v[38:39] op_sel_hi:[1,0,1]
	v_pk_fma_f32 v[14:15], v[16:17], v[0:1], v[54:55] op_sel_hi:[1,0,1]
	v_pk_fma_f32 v[16:17], v[18:19], v[0:1], v[40:41] op_sel_hi:[1,0,1]
	v_pk_fma_f32 v[18:19], v[20:21], v[0:1], v[56:57] op_sel_hi:[1,0,1]
	v_pk_fma_f32 v[20:21], v[22:23], v[0:1], v[42:43] op_sel_hi:[1,0,1]
	v_pk_fma_f32 v[22:23], v[24:25], v[0:1], v[58:59] op_sel_hi:[1,0,1]
	v_pk_fma_f32 v[24:25], v[26:27], v[0:1], v[44:45] op_sel_hi:[1,0,1]
	v_pk_fma_f32 v[26:27], v[32:33], v[0:1], v[60:61] op_sel_hi:[1,0,1]
	v_pk_fma_f32 v[32:33], v[34:35], v[0:1], v[46:47] op_sel_hi:[1,0,1]
	v_cvt_pk_bf16_f32 v2, v2, v3
	v_cvt_pk_bf16_f32 v3, v8, v9
	v_cvt_pk_bf16_f32 v8, v10, v11
	v_cvt_pk_bf16_f32 v9, v12, v13
	v_cvt_pk_bf16_f32 v10, v14, v15
	v_cvt_pk_bf16_f32 v11, v16, v17
	v_cvt_pk_bf16_f32 v12, v18, v19
	v_cvt_pk_bf16_f32 v13, v20, v21
	v_cvt_pk_bf16_f32 v14, v22, v23
	v_cvt_pk_bf16_f32 v15, v24, v25
	v_cvt_pk_bf16_f32 v16, v26, v27
	v_cvt_pk_bf16_f32 v17, v32, v33
	ds_write2st64_b64 v226, v[2:3], v[8:9] offset0:27 offset1:28
	ds_write2st64_b64 v226, v[10:11], v[12:13] offset0:29 offset1:30
	ds_write2st64_b64 v226, v[14:15], v[16:17] offset0:31 offset1:32
	v_pk_fma_f32 v[2:3], v[30:31], v[0:1], v[48:49] op_sel_hi:[1,0,1]
	v_pk_fma_f32 v[28:29], v[28:29], v[0:1], v[62:63] op_sel_hi:[1,0,1]
	v_cvt_pk_bf16_f32 v19, v2, v3
	v_lshlrev_b32_e32 v2, 16, v50
	v_and_b32_e32 v3, 0xffff0000, v50
	v_pk_fma_f32 v[2:3], v[4:5], v[0:1], v[2:3] op_sel_hi:[1,0,1]
	v_lshlrev_b32_e32 v4, 16, v51
	v_and_b32_e32 v5, 0xffff0000, v51
	v_pk_fma_f32 v[4:5], v[6:7], v[0:1], v[4:5] op_sel_hi:[1,0,1]
	v_cvt_pk_bf16_f32 v18, v28, v29
	v_cvt_pk_bf16_f32 v2, v2, v3
	v_cvt_pk_bf16_f32 v3, v4, v5
	ds_write2st64_b64 v226, v[18:19], v[2:3] offset0:33 offset1:34
	s_cbranch_scc1 .LBB0_925
; template <bool SLC, class Desc>
; __device__ __forceinline__ void attn_run_frag8(const i64_t (&qf)[4], const unsigned char* __restrict__ KF, const unsigned char* __restrict__ VF, const Desc& desc, int n,
;                                                int lo_in, int hi, int qi, AState& st, int lane) {
;     if (n <= 0) return;
;     Frag8 fa, fb, fc;
;     constexpr int NM = ~(1 << 30);
;     int d0 = desc(0), d1 = desc(n > 1 ? 1 : 0);
;     load_frag8(fa, KF, VF, SLC ? (d0 & 0xfffff) : (d0 & NM), lane);
;     load_frag8(fb, KF, VF, SLC ? (d1 & 0xfffff) : (d1 & NM), lane);
; __device__ __forceinline__ void nsa_unit(int unit, const bf16_t* proj, const bf16_t* kc, const bf16_t* vc, const bf16_t* gn, const float* cs, const float* sn, ...
;     ...
;     astate_init(st);
;     { const int lo = tc - 511 < 0 ? 0 : tc - 511; const int first = t0 < 511 ? 0 : (t0 - 511) >> 5, last = (t0 + 3) >> 5;
;       auto desc = [&](int i) { const int p0 = 32 * (first + i); return p0 | ((p0 >= t0 + 3 - 511 && p0 + 31 <= t0) ? (1 << 30) : 0); };
;       unsigned long long goff = (unsigned long long)g * S * 128; asm volatile("" : "+s"(goff));
;       attn_run_frag8<false>(q8, (const unsigned char*)kslf + ((size_t)16 << 20) + goff, (const unsigned char*)kslf + ((size_t)24 << 20) + goff, desc, last - first + 1, lo, tc, 0, st, lane); }
	s_add_u32 s10, s71, s12
	s_addc_u32 s11, s72, s13
	s_add_u32 s12, s73, s12
	s_addc_u32 s13, s74, s13
	s_lshl_b32 s20, s26, 5
	s_add_i32 s54, s90, 0xfffffe04
	s_cmp_lt_i32 s20, s54
	s_cselect_b64 s[16:17], -1, 0
	s_or_b32 s14, s20, 31
	s_cmp_gt_i32 s14, s90
	s_cselect_b64 s[18:19], -1, 0
	s_or_b64 s[16:17], s[16:17], s[18:19]
	s_and_b64 s[16:17], s[16:17], exec
	s_cselect_b32 s14, 0, 2.0
	s_or_b32 s14, s14, s20
	s_cmp_lg_u32 s15, s26
	s_cselect_b64 s[16:17], -1, 0
	v_cndmask_b32_e64 v0, 0, 1, s[16:17]
	v_lshl_add_u64 v[86:87], s[12:13], 0, v[120:121]
	v_readfirstlane_b32 s15, v0
	s_add_i32 s15, s26, s15
	s_lshl_b32 s21, s15, 5
	s_cmp_lt_i32 s21, s54
	s_cselect_b64 s[16:17], -1, 0
	s_or_b32 s18, s21, 31
	s_cmp_gt_i32 s18, s90
	s_cselect_b64 s[18:19], -1, 0
	s_or_b64 s[16:17], s[16:17], s[18:19]
	s_and_b64 s[16:17], s[16:17], exec
	s_cselect_b32 s16, 0, 2.0
	s_or_b32 s66, s16, s21
	s_and_b32 s16, s20, 0x3fffffe0
	s_lshr_b32 s50, s16, 4
	s_lshl_b64 s[16:17], s[50:51], 11
	s_add_u32 s16, s12, s16
	s_addc_u32 s17, s13, s17
	s_and_b32 s50, s26, 0x1ffffff
	v_lshl_add_u64 v[2:3], s[16:17], 0, v[120:121]
	s_lshl_b64 s[16:17], s[50:51], 12
	s_add_u32 s16, s10, s16
	s_addc_u32 s17, s11, s17
	v_lshl_add_u64 v[246:247], v[2:3], 0, v[120:121]
	global_load_dwordx4 v[138:141], v[246:247], off
	global_load_dwordx4 v[142:145], v[246:247], off offset:1024
	global_load_dwordx4 v[146:149], v[246:247], off offset:2048
	global_load_dwordx4 v[150:153], v[246:247], off offset:3072
	v_lshl_add_u64 v[2:3], s[16:17], 0, v[120:121]
	s_and_b32 s16, s21, 0x3fffffe0
	s_lshr_b32 s50, s16, 4
	s_lshl_b64 s[16:17], s[50:51], 11
	s_add_u32 s16, s12, s16
	s_addc_u32 s17, s13, s17
	s_and_b32 s50, s15, 0x1ffffff
	v_lshl_add_u64 v[244:245], v[2:3], 0, v[120:121]
	global_load_dwordx4 v[90:93], v[244:245], off
	global_load_dwordx4 v[94:97], v[244:245], off offset:1024
	global_load_dwordx4 v[98:101], v[244:245], off offset:2048
	global_load_dwordx4 v[102:105], v[244:245], off offset:3072
	v_lshl_add_u64 v[2:3], s[16:17], 0, v[120:121]
	s_lshl_b64 s[16:17], s[50:51], 12
	s_add_u32 s16, s10, s16
	s_addc_u32 s17, s11, s17
	v_lshl_add_u64 v[246:247], v[2:3], 0, v[120:121]
	global_load_dwordx4 v[154:157], v[246:247], off
	global_load_dwordx4 v[158:161], v[246:247], off offset:1024
	global_load_dwordx4 v[162:165], v[246:247], off offset:2048
	global_load_dwordx4 v[166:169], v[246:247], off offset:3072
	v_lshl_add_u64 v[2:3], s[16:17], 0, v[120:121]
	v_lshl_add_u64 v[244:245], v[2:3], 0, v[120:121]
	global_load_dwordx4 v[106:109], v[244:245], off
	global_load_dwordx4 v[110:113], v[244:245], off offset:1024
	global_load_dwordx4 v[114:117], v[244:245], off offset:2048
	global_load_dwordx4 v[134:137], v[244:245], off offset:3072
	v_max_i32_e32 v0, 0x1ff, v132
	v_mov_b32_e32 v2, v1
	v_mov_b32_e32 v3, v1
	v_add_u32_e32 v35, 0xfffffe01, v0
	v_mov_b32_e32 v0, v1
	v_mov_b64_e32 v[38:39], v[2:3]
	v_mov_b64_e32 v[42:43], v[2:3]
	v_mov_b64_e32 v[46:47], v[2:3]
	v_mov_b64_e32 v[50:51], v[2:3]
	v_mov_b64_e32 v[54:55], v[2:3]
	v_mov_b64_e32 v[58:59], v[2:3]
	v_mov_b64_e32 v[62:63], v[2:3]
	v_mov_b64_e32 v[66:67], v[2:3]
	v_lshl_add_u64 v[88:89], s[10:11], 0, v[120:121]
	v_mov_b32_e32 v133, 0xf149f2ca
	v_mov_b32_e32 v227, 0
	v_mov_b64_e32 v[36:37], v[0:1]
	v_mov_b64_e32 v[40:41], v[0:1]
	v_mov_b64_e32 v[44:45], v[0:1]
	v_mov_b64_e32 v[48:49], v[0:1]
	v_mov_b64_e32 v[52:53], v[0:1]
	v_mov_b64_e32 v[56:57], v[0:1]
	v_mov_b64_e32 v[60:61], v[0:1]
	v_mov_b64_e32 v[64:65], v[0:1]
	s_branch .LBB0_996

; template <bool SLC, bool NOMASK> ...
;     const int kq = lane >> 4;
;     const int pos0 = SLC ? (dcur & 0xfffff) : dcur;
;     const int lo = SLC ? ((((dcur >> 20) == qi) | ((dcur >> 20) == 4)) ? 0 : (1 << 30)) : lo_in;
;     load_frag8(nxt, KF, VF, SLC ? (dnext & 0xfffff) : dnext, lane);
;     f32x4 sa[2] = {(f32x4){0.f, 0.f, 0.f, 0.f}, (f32x4){0.f, 0.f, 0.f, 0.f}};
; #pragma unroll
;     for (int T = 0; T < 2; ++T)
; #pragma unroll
;         for (int s2 = 0; s2 < 4; ++s2) sa[T] = __builtin_amdgcn_mfma_f32_16x16x32_fp8_fp8(cur.k[T][s2], qf[s2], sa[T], 0, 0, 0);
;     float sc[8]; bool vd[8]; float mx = -1e30f;
;     const bool act = lo == 0 || !SLC;
;     if (NOMASK) {
; #pragma unroll
;         for (int j = 0; j < 8; ++j) { sc[j] = sa[j >> 2][j & 3]; vd[j] = act; }
;         mx = fmaxf(fmaxf(fmaxf(sc[0], sc[1]), fmaxf(sc[2], sc[3])), fmaxf(fmaxf(sc[4], sc[5]), fmaxf(sc[6], sc[7])));
;         mx = act ? mx : -1e30f;
;     } else {
; #pragma unroll
;         for (int T = 0; T < 2; ++T)
; #pragma unroll
;             for (int r = 0; r < 4; ++r) { const int p = pos0 + 16 * T + 4 * kq + r; const bool v = (p >= lo) & (p <= hi); const float x = sa[T][r];
;                 sc[4 * T + r] = x; vd[4 * T + r] = v; mx = v ? fmaxf(mx, x) : mx; }
;     }
;     if (__builtin_amdgcn_ballot_w64(mx > st.m + 4.f) != 0ull) {
;         mx = fmaxf(mx, __shfl_xor(mx, 16)); mx = fmaxf(mx, __shfl_xor(mx, 32));
;         const float mn = fmaxf(st.m, mx), alpha = __builtin_amdgcn_exp2f(st.m - mn); st.m = mn; st.l *= alpha;
; #pragma unroll
;         for (int j = 0; j < 8; ++j) st.o[j] = st.o[j] * alpha;
;     }
;     f32x4 pa, pb; float ps = 0.f;
;     const float mref = st.m - 4.f;
;     if (NOMASK) {
; #pragma unroll
;         for (int j = 0; j < 4; ++j) { pa[j] = __builtin_amdgcn_exp2f(sc[j] - mref); pb[j] = __builtin_amdgcn_exp2f(sc[4 + j] - mref); }
;         if (SLC) {
; #pragma unroll
;             for (int j = 0; j < 4; ++j) { pa[j] = act ? pa[j] : 0.f; pb[j] = act ? pb[j] : 0.f; }
;         }
; #pragma unroll
;         for (int j = 0; j < 4; ++j) ps += pa[j] + pb[j];
;     } else {
; #pragma unroll
;         for (int j = 0; j < 4; ++j) { pa[j] = vd[j] ? __builtin_amdgcn_exp2f(sc[j] - mref) : 0.f; pb[j] = vd[4 + j] ? __builtin_amdgcn_exp2f(sc[4 + j] - mref) : 0.f; ps += pa[j] + pb[j]; }
;     }
;     st.l += ps;
;     const u32x2 pw = pack8_fp8(pa, pb);
.LBB0_1002:
	v_lshl_add_u64 v[246:247], v[204:205], 0, v[120:121]
	global_load_dwordx4 v[186:189], v[246:247], off
	global_load_dwordx4 v[190:193], v[246:247], off offset:1024
	global_load_dwordx4 v[194:197], v[246:247], off offset:2048
	global_load_dwordx4 v[198:201], v[246:247], off offset:3072
	v_lshl_add_u64 v[244:245], v[202:203], 0, v[120:121]
	global_load_dwordx4 v[170:173], v[244:245], off
	global_load_dwordx4 v[174:177], v[244:245], off offset:1024
	global_load_dwordx4 v[178:181], v[244:245], off offset:2048
	global_load_dwordx4 v[182:185], v[244:245], off offset:3072
	s_waitcnt vmcnt(20)
	v_mfma_f32_16x16x32_fp8_fp8 v[2:5], v[138:139], v[78:79], 0
	v_mov_b64_e32 v[74:75], v[38:39]
	v_mov_b64_e32 v[70:71], v[42:43]
	v_mov_b64_e32 v[30:31], v[44:45]
	v_mfma_f32_16x16x32_fp8_fp8 v[6:9], v[146:147], v[78:79], 0
	v_mov_b64_e32 v[26:27], v[48:49]
	v_mov_b64_e32 v[22:23], v[52:53]
	v_mov_b64_e32 v[18:19], v[56:57]
	v_mfma_f32_16x16x32_fp8_fp8 v[2:5], v[140:141], v[80:81], v[2:5]
	v_mov_b64_e32 v[14:15], v[60:61]
	v_mov_b32_e32 v228, v133
	v_mov_b64_e32 v[72:73], v[36:37]
	v_mfma_f32_16x16x32_fp8_fp8 v[6:9], v[148:149], v[80:81], v[6:9]
	v_mov_b64_e32 v[68:69], v[40:41]
	v_mov_b64_e32 v[32:33], v[46:47]
	v_mov_b64_e32 v[28:29], v[50:51]
	v_mfma_f32_16x16x32_fp8_fp8 v[2:5], v[142:143], v[82:83], v[2:5]
	v_mov_b64_e32 v[24:25], v[54:55]
	v_mov_b64_e32 v[20:21], v[58:59]
	v_mov_b64_e32 v[16:17], v[62:63]
	v_mfma_f32_16x16x32_fp8_fp8 v[6:9], v[150:151], v[82:83], v[6:9]
	v_mov_b32_e32 v34, v227
	v_mfma_f32_16x16x32_fp8_fp8 v[2:5], v[144:145], v[84:85], v[2:5]
	v_mfma_f32_16x16x32_fp8_fp8 v[6:9], v[152:153], v[84:85], v[6:9]
	s_nop 5
	v_max_f32_e32 v0, v3, v3
	v_max_f32_e32 v10, v2, v2
	v_max_f32_e32 v0, v10, v0
	v_max_f32_e32 v10, v5, v5
	v_max_f32_e32 v11, v4, v4
	v_max_f32_e32 v10, v11, v10
	v_max_f32_e32 v11, v9, v9
	v_max_f32_e32 v12, v8, v8
	v_max_f32_e32 v11, v12, v11
	v_max3_f32 v11, v6, v7, v11
	v_max3_f32 v0, v0, v10, v11
	v_add_f32_e32 v10, 4.0, v133
	v_cmp_gt_f32_e32 vcc, v0, v10
	v_mov_b64_e32 v[10:11], v[64:65]
	v_mov_b64_e32 v[12:13], v[66:67]
	s_cbranch_vccz .LBB0_1004
	ds_bpermute_b32 v10, v225, v0
	v_max_f32_e32 v0, v0, v0
	s_waitcnt lgkmcnt(0)
	v_max_f32_e32 v10, v10, v10
	v_max_f32_e32 v0, v0, v10
	ds_bpermute_b32 v10, v224, v0
	s_waitcnt lgkmcnt(0)
	v_max3_f32 v228, v133, v0, v10
	v_sub_f32_e32 v0, v133, v228
	v_exp_f32_e32 v0, v0
	s_nop 0
	v_mul_f32_e32 v34, v227, v0
	v_pk_mul_f32 v[12:13], v[66:67], v[0:1] op_sel_hi:[1,0]
	v_pk_mul_f32 v[10:11], v[64:65], v[0:1] op_sel_hi:[1,0]
	v_pk_mul_f32 v[16:17], v[62:63], v[0:1] op_sel_hi:[1,0]
	v_pk_mul_f32 v[14:15], v[60:61], v[0:1] op_sel_hi:[1,0]
	v_pk_mul_f32 v[20:21], v[58:59], v[0:1] op_sel_hi:[1,0]
	v_pk_mul_f32 v[18:19], v[56:57], v[0:1] op_sel_hi:[1,0]
	v_pk_mul_f32 v[24:25], v[54:55], v[0:1] op_sel_hi:[1,0]
	v_pk_mul_f32 v[22:23], v[52:53], v[0:1] op_sel_hi:[1,0]
	v_pk_mul_f32 v[28:29], v[50:51], v[0:1] op_sel_hi:[1,0]
	v_pk_mul_f32 v[26:27], v[48:49], v[0:1] op_sel_hi:[1,0]
	v_pk_mul_f32 v[32:33], v[46:47], v[0:1] op_sel_hi:[1,0]
	v_pk_mul_f32 v[30:31], v[44:45], v[0:1] op_sel_hi:[1,0]
	v_pk_mul_f32 v[70:71], v[42:43], v[0:1] op_sel_hi:[1,0]
	v_pk_mul_f32 v[68:69], v[40:41], v[0:1] op_sel_hi:[1,0]
	v_pk_mul_f32 v[74:75], v[38:39], v[0:1] op_sel_hi:[1,0]
	v_pk_mul_f32 v[72:73], v[36:37], v[0:1] op_sel_hi:[1,0]
.LBB0_1004:
	v_add_f32_e32 v229, -4.0, v228
	v_sub_f32_e32 v0, v2, v229
	v_exp_f32_e32 v231, v0
	v_sub_f32_e32 v0, v6, v229
	v_exp_f32_e32 v234, v0
	v_sub_f32_e32 v0, v3, v229
	v_exp_f32_e32 v2, v0
	v_sub_f32_e32 v0, v7, v229
	v_exp_f32_e32 v0, v0
	v_sub_f32_e32 v3, v4, v229
	v_exp_f32_e32 v235, v3
	v_sub_f32_e32 v3, v8, v229
	v_exp_f32_e32 v236, v3
	v_sub_f32_e32 v3, v5, v229
	v_exp_f32_e32 v4, v3
	v_sub_f32_e32 v3, v9, v229
	v_mov_b32_e32 v232, v1
	v_mov_b32_e32 v233, v1
	v_exp_f32_e32 v230, v3
	v_cvt_pk_fp8_f32 v232, v231, v2
	v_cvt_pk_fp8_f32 v233, v234, v0
	v_add_f32_e32 v3, v231, v234
	v_pk_add_f32 v[2:3], v[2:3], v[0:1]
	v_cvt_pk_fp8_f32 v232, v235, v4 op_sel:[0,0,1]
	v_cvt_pk_fp8_f32 v233, v236, v230 op_sel:[0,0,1]
	v_pk_add_f32 v[2:3], v[2:3], v[2:3] op_sel_hi:[0,1]
	v_add_f32_e32 v5, v235, v236
	v_mov_b32_e32 v231, v3
	v_pk_add_f32 v[2:3], v[4:5], v[230:231]
	s_waitcnt vmcnt(19)
	v_mfma_f32_16x16x32_fp8_fp8 v[6:9], v[90:91], v[232:233], v[10:13]
	v_add_f32_e32 v0, v2, v3
	v_add_f32_e32 v34, v0, v34
	v_mfma_f32_16x16x32_fp8_fp8 v[10:13], v[92:93], v[232:233], v[14:17]
	s_waitcnt vmcnt(18)
	v_mfma_f32_16x16x32_fp8_fp8 v[14:17], v[94:95], v[232:233], v[18:21]
	v_mfma_f32_16x16x32_fp8_fp8 v[18:21], v[96:97], v[232:233], v[22:25]
	s_waitcnt vmcnt(17)
	v_mfma_f32_16x16x32_fp8_fp8 v[22:25], v[98:99], v[232:233], v[26:29]
	v_mfma_f32_16x16x32_fp8_fp8 v[26:29], v[100:101], v[232:233], v[30:33]
	s_waitcnt vmcnt(16)
	v_mfma_f32_16x16x32_fp8_fp8 v[30:33], v[102:103], v[232:233], v[68:71]
	v_mfma_f32_16x16x32_fp8_fp8 v[2:5], v[104:105], v[232:233], v[72:75]
	s_branch .LBB0_998
; template <bool SLC, bool NOMASK> ...
;     const int kq = lane >> 4;
;     const int pos0 = SLC ? (dcur & 0xfffff) : dcur;
;     const int lo = SLC ? ((((dcur >> 20) == qi) | ((dcur >> 20) == 4)) ? 0 : (1 << 30)) : lo_in;
;     load_frag8(nxt, KF, VF, SLC ? (dnext & 0xfffff) : dnext, lane);
;     f32x4 sa[2] = {(f32x4){0.f, 0.f, 0.f, 0.f}, (f32x4){0.f, 0.f, 0.f, 0.f}};
; #pragma unroll
;     for (int T = 0; T < 2; ++T)
; #pragma unroll
;         for (int s2 = 0; s2 < 4; ++s2) sa[T] = __builtin_amdgcn_mfma_f32_16x16x32_fp8_fp8(cur.k[T][s2], qf[s2], sa[T], 0, 0, 0);
;     float sc[8]; bool vd[8]; float mx = -1e30f;
;     const bool act = lo == 0 || !SLC;
;     if (NOMASK) {
; #pragma unroll
;         for (int j = 0; j < 8; ++j) { sc[j] = sa[j >> 2][j & 3]; vd[j] = act; }
;         mx = fmaxf(fmaxf(fmaxf(sc[0], sc[1]), fmaxf(sc[2], sc[3])), fmaxf(fmaxf(sc[4], sc[5]), fmaxf(sc[6], sc[7])));
;         mx = act ? mx : -1e30f;
;     } else {
; #pragma unroll
;         for (int T = 0; T < 2; ++T)
; #pragma unroll
;             for (int r = 0; r < 4; ++r) { const int p = pos0 + 16 * T + 4 * kq + r; const bool v = (p >= lo) & (p <= hi); const float x = sa[T][r];
;                 sc[4 * T + r] = x; vd[4 * T + r] = v; mx = v ? fmaxf(mx, x) : mx; }
;     }
;     if (__builtin_amdgcn_ballot_w64(mx > st.m + 4.f) != 0ull) {
;         mx = fmaxf(mx, __shfl_xor(mx, 16)); mx = fmaxf(mx, __shfl_xor(mx, 32));
;         const float mn = fmaxf(st.m, mx), alpha = __builtin_amdgcn_exp2f(st.m - mn); st.m = mn; st.l *= alpha;
; #pragma unroll
;         for (int j = 0; j < 8; ++j) st.o[j] = st.o[j] * alpha;
;     }
;     f32x4 pa, pb; float ps = 0.f;
;     const float mref = st.m - 4.f;
;     if (NOMASK) {
; #pragma unroll
;         for (int j = 0; j < 4; ++j) { pa[j] = __builtin_amdgcn_exp2f(sc[j] - mref); pb[j] = __builtin_amdgcn_exp2f(sc[4 + j] - mref); }
;         if (SLC) {
; #pragma unroll
;             for (int j = 0; j < 4; ++j) { pa[j] = act ? pa[j] : 0.f; pb[j] = act ? pb[j] : 0.f; }
;         }
; #pragma unroll
;         for (int j = 0; j < 4; ++j) ps += pa[j] + pb[j];
;     } else {
; #pragma unroll
;         for (int j = 0; j < 4; ++j) { pa[j] = vd[j] ? __builtin_amdgcn_exp2f(sc[j] - mref) : 0.f; pb[j] = vd[4 + j] ? __builtin_amdgcn_exp2f(sc[4 + j] - mref) : 0.f; ps += pa[j] + pb[j]; }
;     }
;     st.l += ps;
;     const u32x2 pw = pack8_fp8(pa, pb);
.LBB0_1005:
	v_lshl_add_u64 v[246:247], v[204:205], 0, v[120:121]
	global_load_dwordx4 v[186:189], v[246:247], off
	global_load_dwordx4 v[190:193], v[246:247], off offset:1024
	global_load_dwordx4 v[194:197], v[246:247], off offset:2048
	global_load_dwordx4 v[198:201], v[246:247], off offset:3072
	v_lshl_add_u64 v[244:245], v[202:203], 0, v[120:121]
	global_load_dwordx4 v[170:173], v[244:245], off
	global_load_dwordx4 v[174:177], v[244:245], off offset:1024
	global_load_dwordx4 v[178:181], v[244:245], off offset:2048
	global_load_dwordx4 v[182:185], v[244:245], off offset:3072
	s_waitcnt vmcnt(20)
	v_mfma_f32_16x16x32_fp8_fp8 v[2:5], v[138:139], v[78:79], 0
	v_add_u32_e32 v0, s14, v210
	v_cmp_ge_i32_e32 vcc, v0, v35
	v_cmp_le_i32_e64 s[10:11], v0, v132
	v_mfma_f32_16x16x32_fp8_fp8 v[2:5], v[140:141], v[80:81], v[2:5]
	s_and_b64 s[16:17], vcc, s[10:11]
	v_add_u32_e32 v11, 1, v0
	v_cmp_ge_i32_e32 vcc, v11, v35
	v_mfma_f32_16x16x32_fp8_fp8 v[2:5], v[142:143], v[82:83], v[2:5]
	v_cmp_lt_i32_e64 s[10:11], v0, v132
	s_and_b64 s[12:13], s[10:11], vcc
	v_mfma_f32_16x16x32_fp8_fp8 v[6:9], v[146:147], v[78:79], 0
	v_mfma_f32_16x16x32_fp8_fp8 v[2:5], v[144:145], v[84:85], v[2:5]
	v_mfma_f32_16x16x32_fp8_fp8 v[6:9], v[148:149], v[80:81], v[6:9]
	v_mfma_f32_16x16x32_fp8_fp8 v[6:9], v[150:151], v[82:83], v[6:9]
	s_nop 3
	v_max_f32_e32 v10, v2, v2
	v_max_f32_e32 v10, 0xf149f2ca, v10
	v_cndmask_b32_e64 v10, v220, v10, s[16:17]
	v_max_f32_e32 v11, v3, v3
	v_max_f32_e32 v11, v10, v11
	v_cndmask_b32_e64 v10, v10, v11, s[12:13]
	v_add_u32_e32 v11, 2, v0
	v_cmp_ge_i32_e32 vcc, v11, v35
	v_cmp_le_i32_e64 s[10:11], v11, v132
	v_max_f32_e32 v11, v4, v4
	v_max_f32_e32 v11, v10, v11
	s_and_b64 s[14:15], vcc, s[10:11]
	v_mfma_f32_16x16x32_fp8_fp8 v[6:9], v[152:153], v[84:85], v[6:9]
	v_cndmask_b32_e64 v10, v10, v11, s[14:15]
	v_add_u32_e32 v11, 3, v0
	v_cmp_ge_i32_e32 vcc, v11, v35
	v_cmp_le_i32_e64 s[10:11], v11, v132
	v_max_f32_e32 v11, v5, v5
	v_max_f32_e32 v11, v10, v11
	s_and_b64 s[10:11], vcc, s[10:11]
	v_cndmask_b32_e64 v10, v10, v11, s[10:11]
	v_add_u32_e32 v11, 16, v0
	v_cmp_ge_i32_e32 vcc, v11, v35
	v_cmp_le_i32_e64 s[18:19], v11, v132
	v_max_f32_e32 v11, v6, v6
	v_max_f32_e32 v11, v10, v11
	s_and_b64 s[24:25], vcc, s[18:19]
	v_cndmask_b32_e64 v10, v10, v11, s[24:25]
	v_add_u32_e32 v11, 17, v0
	v_cmp_ge_i32_e32 vcc, v11, v35
	v_cmp_le_i32_e64 s[18:19], v11, v132
	v_max_f32_e32 v11, v10, v10
	v_max_f32_e32 v12, v7, v7
	v_max_f32_e32 v11, v11, v12
	s_and_b64 s[20:21], vcc, s[18:19]
	v_cndmask_b32_e64 v10, v10, v11, s[20:21]
	v_add_u32_e32 v11, 18, v0
	v_cmp_ge_i32_e32 vcc, v11, v35
	v_cmp_le_i32_e64 s[18:19], v11, v132
	v_max_f32_e32 v11, v10, v10
	v_max_f32_e32 v12, v8, v8
	v_max_f32_e32 v11, v11, v12
	s_and_b64 s[22:23], vcc, s[18:19]
	v_cndmask_b32_e64 v10, v10, v11, s[22:23]
	v_add_u32_e32 v0, 19, v0
	v_cmp_ge_i32_e32 vcc, v0, v35
	v_cmp_le_i32_e64 s[18:19], v0, v132
	v_max_f32_e32 v0, v10, v10
	v_max_f32_e32 v11, v9, v9
	v_max_f32_e32 v0, v0, v11
	s_and_b64 s[18:19], vcc, s[18:19]
	v_cndmask_b32_e64 v0, v10, v0, s[18:19]
	v_add_f32_e32 v10, 4.0, v133
	v_cmp_gt_f32_e32 vcc, v0, v10
	s_cbranch_vccz .LBB0_1007
	ds_bpermute_b32 v10, v225, v0
	v_max_f32_e32 v0, v0, v0
	s_waitcnt lgkmcnt(0)
	v_max_f32_e32 v10, v10, v10
	v_max_f32_e32 v0, v0, v10
	ds_bpermute_b32 v10, v224, v0
	s_waitcnt lgkmcnt(0)
	v_max3_f32 v10, v133, v0, v10
	v_sub_f32_e32 v0, v133, v10
	v_exp_f32_e32 v0, v0
	v_mov_b32_e32 v133, v10
	v_mul_f32_e32 v227, v227, v0
	v_pk_mul_f32 v[66:67], v[66:67], v[0:1] op_sel_hi:[1,0]
	v_pk_mul_f32 v[64:65], v[64:65], v[0:1] op_sel_hi:[1,0]
	v_pk_mul_f32 v[62:63], v[62:63], v[0:1] op_sel_hi:[1,0]
	v_pk_mul_f32 v[60:61], v[60:61], v[0:1] op_sel_hi:[1,0]
	v_pk_mul_f32 v[58:59], v[58:59], v[0:1] op_sel_hi:[1,0]
	v_pk_mul_f32 v[56:57], v[56:57], v[0:1] op_sel_hi:[1,0]
	v_pk_mul_f32 v[54:55], v[54:55], v[0:1] op_sel_hi:[1,0]
	v_pk_mul_f32 v[52:53], v[52:53], v[0:1] op_sel_hi:[1,0]
	v_pk_mul_f32 v[50:51], v[50:51], v[0:1] op_sel_hi:[1,0]
	v_pk_mul_f32 v[48:49], v[48:49], v[0:1] op_sel_hi:[1,0]
	v_pk_mul_f32 v[46:47], v[46:47], v[0:1] op_sel_hi:[1,0]
	v_pk_mul_f32 v[44:45], v[44:45], v[0:1] op_sel_hi:[1,0]
	v_pk_mul_f32 v[42:43], v[42:43], v[0:1] op_sel_hi:[1,0]
	v_pk_mul_f32 v[40:41], v[40:41], v[0:1] op_sel_hi:[1,0]
	v_pk_mul_f32 v[38:39], v[38:39], v[0:1] op_sel_hi:[1,0]
	v_pk_mul_f32 v[36:37], v[36:37], v[0:1] op_sel_hi:[1,0]
.LBB0_1007:
	v_add_f32_e32 v0, -4.0, v133
	v_sub_f32_e32 v2, v2, v0
	v_exp_f32_e32 v2, v2
	v_sub_f32_e32 v6, v6, v0
	v_exp_f32_e32 v6, v6
	v_sub_f32_e32 v4, v4, v0
	v_cndmask_b32_e64 v26, 0, v2, s[16:17]
	v_sub_f32_e32 v2, v3, v0
	v_exp_f32_e32 v2, v2
	v_sub_f32_e32 v3, v7, v0
	v_exp_f32_e32 v3, v3
	v_cndmask_b32_e64 v27, 0, v6, s[24:25]
	v_sub_f32_e32 v6, v8, v0
	v_cndmask_b32_e64 v28, 0, v2, s[12:13]
	v_sub_f32_e32 v2, v5, v0
	v_sub_f32_e32 v0, v9, v0
	v_exp_f32_e32 v4, v4
	v_exp_f32_e32 v6, v6
	v_cndmask_b32_e64 v29, 0, v3, s[20:21]
	v_exp_f32_e32 v5, v2
	v_exp_f32_e32 v0, v0
	v_mov_b32_e32 v2, v1
	v_mov_b32_e32 v3, v1
	v_cvt_pk_fp8_f32 v2, v26, v28
	v_cvt_pk_fp8_f32 v3, v27, v29
	v_cndmask_b32_e64 v4, 0, v4, s[14:15]
	v_cndmask_b32_e64 v30, 0, v6, s[22:23]
	v_cndmask_b32_e64 v5, 0, v5, s[10:11]
	v_cndmask_b32_e64 v0, 0, v0, s[18:19]
	v_cvt_pk_fp8_f32 v2, v4, v5 op_sel:[0,0,1]
	v_cvt_pk_fp8_f32 v3, v30, v0 op_sel:[0,0,1]
	v_add_f32_e32 v26, v26, v27
	v_add_f32_e32 v31, 0, v26
	v_add_f32_e32 v32, v28, v29
	v_add_f32_e32 v31, v32, v31
	v_add_f32_e32 v4, v4, v30
	v_add_f32_e32 v4, v4, v31
	v_add_f32_e32 v0, v5, v0
	s_waitcnt vmcnt(19)
	v_mfma_f32_16x16x32_fp8_fp8 v[6:9], v[90:91], v[2:3], v[64:67]
	v_add_f32_e32 v0, v0, v4
	v_add_f32_e32 v34, v227, v0
	v_mov_b32_e32 v228, v133
	v_mfma_f32_16x16x32_fp8_fp8 v[10:13], v[92:93], v[2:3], v[60:63]
	s_waitcnt vmcnt(18)
	v_mfma_f32_16x16x32_fp8_fp8 v[14:17], v[94:95], v[2:3], v[56:59]
	v_mfma_f32_16x16x32_fp8_fp8 v[18:21], v[96:97], v[2:3], v[52:55]
	s_waitcnt vmcnt(17)
	v_mfma_f32_16x16x32_fp8_fp8 v[22:25], v[98:99], v[2:3], v[48:51]
	v_mfma_f32_16x16x32_fp8_fp8 v[26:29], v[100:101], v[2:3], v[44:47]
	s_waitcnt vmcnt(16)
	v_mfma_f32_16x16x32_fp8_fp8 v[30:33], v[102:103], v[2:3], v[40:43]
	v_mfma_f32_16x16x32_fp8_fp8 v[2:5], v[104:105], v[2:3], v[36:39]
	s_cmp_ge_i32 s56, s27
	s_mov_b64 s[10:11], -1
	s_cbranch_scc0 .LBB0_999

; template <bool SLC, bool NOMASK> ...
;     const int kq = lane >> 4;
;     const int pos0 = SLC ? (dcur & 0xfffff) : dcur;
;     const int lo = SLC ? ((((dcur >> 20) == qi) | ((dcur >> 20) == 4)) ? 0 : (1 << 30)) : lo_in;
;     load_frag8(nxt, KF, VF, SLC ? (dnext & 0xfffff) : dnext, lane);
;     f32x4 sa[2] = {(f32x4){0.f, 0.f, 0.f, 0.f}, (f32x4){0.f, 0.f, 0.f, 0.f}};
; #pragma unroll
;     for (int T = 0; T < 2; ++T)
; #pragma unroll
;         for (int s2 = 0; s2 < 4; ++s2) sa[T] = __builtin_amdgcn_mfma_f32_16x16x32_fp8_fp8(cur.k[T][s2], qf[s2], sa[T], 0, 0, 0);
;     float sc[8]; bool vd[8]; float mx = -1e30f;
;     const bool act = lo == 0 || !SLC;
;     if (NOMASK) {
; #pragma unroll
;         for (int j = 0; j < 8; ++j) { sc[j] = sa[j >> 2][j & 3]; vd[j] = act; }
;         mx = fmaxf(fmaxf(fmaxf(sc[0], sc[1]), fmaxf(sc[2], sc[3])), fmaxf(fmaxf(sc[4], sc[5]), fmaxf(sc[6], sc[7])));
;         mx = act ? mx : -1e30f;
;     } else {
; #pragma unroll
;         for (int T = 0; T < 2; ++T)
; #pragma unroll
;             for (int r = 0; r < 4; ++r) { const int p = pos0 + 16 * T + 4 * kq + r; const bool v = (p >= lo) & (p <= hi); const float x = sa[T][r];
;                 sc[4 * T + r] = x; vd[4 * T + r] = v; mx = v ? fmaxf(mx, x) : mx; }
;     }
;     if (__builtin_amdgcn_ballot_w64(mx > st.m + 4.f) != 0ull) {
;         mx = fmaxf(mx, __shfl_xor(mx, 16)); mx = fmaxf(mx, __shfl_xor(mx, 32));
;         const float mn = fmaxf(st.m, mx), alpha = __builtin_amdgcn_exp2f(st.m - mn); st.m = mn; st.l *= alpha;
; #pragma unroll
;         for (int j = 0; j < 8; ++j) st.o[j] = st.o[j] * alpha;
;     }
;     f32x4 pa, pb; float ps = 0.f;
;     const float mref = st.m - 4.f;
;     if (NOMASK) {
; #pragma unroll
;         for (int j = 0; j < 4; ++j) { pa[j] = __builtin_amdgcn_exp2f(sc[j] - mref); pb[j] = __builtin_amdgcn_exp2f(sc[4 + j] - mref); }
;         if (SLC) {
; #pragma unroll
;             for (int j = 0; j < 4; ++j) { pa[j] = act ? pa[j] : 0.f; pb[j] = act ? pb[j] : 0.f; }
;         }
; #pragma unroll
;         for (int j = 0; j < 4; ++j) ps += pa[j] + pb[j];
;     } else {
; #pragma unroll
;         for (int j = 0; j < 4; ++j) { pa[j] = vd[j] ? __builtin_amdgcn_exp2f(sc[j] - mref) : 0.f; pb[j] = vd[4 + j] ? __builtin_amdgcn_exp2f(sc[4 + j] - mref) : 0.f; ps += pa[j] + pb[j]; }
;     }
;     st.l += ps;
;     const u32x2 pw = pack8_fp8(pa, pb);
.LBB0_1009:
	v_lshl_add_u64 v[246:247], v[204:205], 0, v[120:121]
	global_load_dwordx4 v[138:141], v[246:247], off
	global_load_dwordx4 v[142:145], v[246:247], off offset:1024
	global_load_dwordx4 v[146:149], v[246:247], off offset:2048
	global_load_dwordx4 v[150:153], v[246:247], off offset:3072
	v_lshl_add_u64 v[244:245], v[202:203], 0, v[120:121]
	global_load_dwordx4 v[90:93], v[244:245], off
	global_load_dwordx4 v[94:97], v[244:245], off offset:1024
	global_load_dwordx4 v[98:101], v[244:245], off offset:2048
	global_load_dwordx4 v[102:105], v[244:245], off offset:3072
	s_waitcnt vmcnt(20)
	v_mfma_f32_16x16x32_fp8_fp8 v[36:39], v[154:155], v[78:79], 0
	v_mov_b64_e32 v[74:75], v[4:5]
	v_mov_b64_e32 v[70:71], v[32:33]
	v_mov_b64_e32 v[66:67], v[28:29]
	v_mfma_f32_16x16x32_fp8_fp8 v[40:43], v[162:163], v[78:79], 0
	v_mov_b64_e32 v[62:63], v[24:25]
	v_mov_b64_e32 v[58:59], v[20:21]
	v_mov_b64_e32 v[54:55], v[16:17]
	v_mfma_f32_16x16x32_fp8_fp8 v[36:39], v[156:157], v[80:81], v[36:39]
	v_mov_b64_e32 v[50:51], v[12:13]
	v_mov_b32_e32 v227, v228
	v_mov_b64_e32 v[72:73], v[2:3]
	v_mfma_f32_16x16x32_fp8_fp8 v[40:43], v[164:165], v[80:81], v[40:43]
	v_mov_b64_e32 v[68:69], v[30:31]
	v_mov_b64_e32 v[64:65], v[26:27]
	v_mov_b64_e32 v[60:61], v[22:23]
	v_mfma_f32_16x16x32_fp8_fp8 v[36:39], v[158:159], v[82:83], v[36:39]
	v_mov_b64_e32 v[56:57], v[18:19]
	v_mov_b64_e32 v[52:53], v[14:15]
	v_mov_b64_e32 v[48:49], v[10:11]
	v_mfma_f32_16x16x32_fp8_fp8 v[40:43], v[166:167], v[82:83], v[40:43]
	v_mov_b32_e32 v229, v34
	v_mfma_f32_16x16x32_fp8_fp8 v[36:39], v[160:161], v[84:85], v[36:39]
	v_mfma_f32_16x16x32_fp8_fp8 v[40:43], v[168:169], v[84:85], v[40:43]
	s_nop 5
	v_max_f32_e32 v0, v37, v37
	v_max_f32_e32 v44, v36, v36
	v_max_f32_e32 v0, v44, v0
	v_max_f32_e32 v44, v39, v39
	v_max_f32_e32 v45, v38, v38
	v_max_f32_e32 v44, v45, v44
	v_max_f32_e32 v45, v43, v43
	v_max_f32_e32 v46, v42, v42
	v_max_f32_e32 v45, v46, v45
	v_max3_f32 v45, v40, v41, v45
	v_max3_f32 v0, v0, v44, v45
	v_mov_b64_e32 v[46:47], v[8:9]
	v_cmp_gt_f32_e32 vcc, v0, v133
	v_mov_b64_e32 v[44:45], v[6:7]
	s_cbranch_vccz .LBB0_1011
	ds_bpermute_b32 v44, v225, v0
	v_max_f32_e32 v0, v0, v0
	s_waitcnt lgkmcnt(0)
	v_max_f32_e32 v44, v44, v44
	v_max_f32_e32 v0, v0, v44
	ds_bpermute_b32 v44, v224, v0
	s_waitcnt lgkmcnt(0)
	v_max3_f32 v227, v228, v0, v44
	v_sub_f32_e32 v0, v228, v227
	v_exp_f32_e32 v0, v0
	s_nop 0
	v_mul_f32_e32 v229, v34, v0
	v_pk_mul_f32 v[46:47], v[8:9], v[0:1] op_sel_hi:[1,0]
	v_pk_mul_f32 v[44:45], v[6:7], v[0:1] op_sel_hi:[1,0]
	v_pk_mul_f32 v[50:51], v[12:13], v[0:1] op_sel_hi:[1,0]
	v_pk_mul_f32 v[48:49], v[10:11], v[0:1] op_sel_hi:[1,0]
	v_pk_mul_f32 v[54:55], v[16:17], v[0:1] op_sel_hi:[1,0]
	v_pk_mul_f32 v[52:53], v[14:15], v[0:1] op_sel_hi:[1,0]
	v_pk_mul_f32 v[58:59], v[20:21], v[0:1] op_sel_hi:[1,0]
	v_pk_mul_f32 v[56:57], v[18:19], v[0:1] op_sel_hi:[1,0]
	v_pk_mul_f32 v[62:63], v[24:25], v[0:1] op_sel_hi:[1,0]
	v_pk_mul_f32 v[60:61], v[22:23], v[0:1] op_sel_hi:[1,0]
	v_pk_mul_f32 v[66:67], v[28:29], v[0:1] op_sel_hi:[1,0]
	v_pk_mul_f32 v[64:65], v[26:27], v[0:1] op_sel_hi:[1,0]
	v_pk_mul_f32 v[70:71], v[32:33], v[0:1] op_sel_hi:[1,0]
	v_pk_mul_f32 v[68:69], v[30:31], v[0:1] op_sel_hi:[1,0]
	v_pk_mul_f32 v[74:75], v[4:5], v[0:1] op_sel_hi:[1,0]
	v_pk_mul_f32 v[72:73], v[2:3], v[0:1] op_sel_hi:[1,0]
.LBB0_1011:
	v_add_f32_e32 v231, -4.0, v227
	v_sub_f32_e32 v0, v36, v231
	v_exp_f32_e32 v233, v0
	v_sub_f32_e32 v0, v40, v231
	v_exp_f32_e32 v235, v0
	v_sub_f32_e32 v0, v37, v231
	v_exp_f32_e32 v230, v0
	v_sub_f32_e32 v0, v41, v231
	v_exp_f32_e32 v0, v0
	v_sub_f32_e32 v36, v38, v231
	v_exp_f32_e32 v238, v36
	v_sub_f32_e32 v36, v42, v231
	v_exp_f32_e32 v239, v36
	v_sub_f32_e32 v36, v39, v231
	v_exp_f32_e32 v232, v36
	v_sub_f32_e32 v36, v43, v231
	v_mov_b32_e32 v236, v1
	v_mov_b32_e32 v237, v1
	v_exp_f32_e32 v234, v36
	v_cvt_pk_fp8_f32 v236, v233, v230
	v_cvt_pk_fp8_f32 v237, v235, v0
	v_add_f32_e32 v231, v233, v235
	v_add_f32_e32 v233, v238, v239
	v_cvt_pk_fp8_f32 v236, v238, v232 op_sel:[0,0,1]
	v_cvt_pk_fp8_f32 v237, v239, v234 op_sel:[0,0,1]
	s_nop 0
	s_waitcnt vmcnt(19)
	v_mfma_f32_16x16x32_fp8_fp8 v[36:39], v[106:107], v[236:237], v[44:47]
	v_mfma_f32_16x16x32_fp8_fp8 v[44:47], v[110:111], v[236:237], v[52:55]
	s_waitcnt vmcnt(18)
	v_mfma_f32_16x16x32_fp8_fp8 v[52:55], v[114:115], v[236:237], v[60:63]
	s_nop 2
	v_add_f32_e64 v60, v230, v0
	v_add_f32_e64 v61, v231, v1
	v_mfma_f32_16x16x32_fp8_fp8 v[40:43], v[108:109], v[236:237], v[48:51]
	v_pk_add_f32 v[60:61], v[60:61], v[60:61] op_sel_hi:[0,1]
	v_mov_b32_e32 v235, v61
	s_waitcnt vmcnt(17)
	v_mfma_f32_16x16x32_fp8_fp8 v[48:51], v[112:113], v[236:237], v[56:59]
	v_mfma_f32_16x16x32_fp8_fp8 v[56:59], v[116:117], v[236:237], v[64:67]
	s_nop 2
	v_add_f32_e64 v64, v232, v234
	v_add_f32_e64 v65, v233, v235
	s_waitcnt vmcnt(16)
	v_mfma_f32_16x16x32_fp8_fp8 v[60:63], v[134:135], v[236:237], v[68:71]
	v_add_f32_e32 v0, v64, v65
	v_add_f32_e32 v229, v0, v229
	v_mfma_f32_16x16x32_fp8_fp8 v[64:67], v[136:137], v[236:237], v[72:75]
	s_branch .LBB0_1001
; template <bool SLC, bool NOMASK> ...
;     const int kq = lane >> 4;
;     const int pos0 = SLC ? (dcur & 0xfffff) : dcur;
;     const int lo = SLC ? ((((dcur >> 20) == qi) | ((dcur >> 20) == 4)) ? 0 : (1 << 30)) : lo_in;
;     load_frag8(nxt, KF, VF, SLC ? (dnext & 0xfffff) : dnext, lane);
;     f32x4 sa[2] = {(f32x4){0.f, 0.f, 0.f, 0.f}, (f32x4){0.f, 0.f, 0.f, 0.f}};
; #pragma unroll
;     for (int T = 0; T < 2; ++T)
; #pragma unroll
;         for (int s2 = 0; s2 < 4; ++s2) sa[T] = __builtin_amdgcn_mfma_f32_16x16x32_fp8_fp8(cur.k[T][s2], qf[s2], sa[T], 0, 0, 0);
;     float sc[8]; bool vd[8]; float mx = -1e30f;
;     const bool act = lo == 0 || !SLC;
;     if (NOMASK) {
; #pragma unroll
;         for (int j = 0; j < 8; ++j) { sc[j] = sa[j >> 2][j & 3]; vd[j] = act; }
;         mx = fmaxf(fmaxf(fmaxf(sc[0], sc[1]), fmaxf(sc[2], sc[3])), fmaxf(fmaxf(sc[4], sc[5]), fmaxf(sc[6], sc[7])));
;         mx = act ? mx : -1e30f;
;     } else {
; #pragma unroll
;         for (int T = 0; T < 2; ++T)
; #pragma unroll
;             for (int r = 0; r < 4; ++r) { const int p = pos0 + 16 * T + 4 * kq + r; const bool v = (p >= lo) & (p <= hi); const float x = sa[T][r];
;                 sc[4 * T + r] = x; vd[4 * T + r] = v; mx = v ? fmaxf(mx, x) : mx; }
;     }
;     if (__builtin_amdgcn_ballot_w64(mx > st.m + 4.f) != 0ull) {
;         mx = fmaxf(mx, __shfl_xor(mx, 16)); mx = fmaxf(mx, __shfl_xor(mx, 32));
;         const float mn = fmaxf(st.m, mx), alpha = __builtin_amdgcn_exp2f(st.m - mn); st.m = mn; st.l *= alpha;
; #pragma unroll
;         for (int j = 0; j < 8; ++j) st.o[j] = st.o[j] * alpha;
;     }
;     f32x4 pa, pb; float ps = 0.f;
;     const float mref = st.m - 4.f;
;     if (NOMASK) {
; #pragma unroll
;         for (int j = 0; j < 4; ++j) { pa[j] = __builtin_amdgcn_exp2f(sc[j] - mref); pb[j] = __builtin_amdgcn_exp2f(sc[4 + j] - mref); }
;         if (SLC) {
; #pragma unroll
;             for (int j = 0; j < 4; ++j) { pa[j] = act ? pa[j] : 0.f; pb[j] = act ? pb[j] : 0.f; }
;         }
; #pragma unroll
;         for (int j = 0; j < 4; ++j) ps += pa[j] + pb[j];
;     } else {
; #pragma unroll
;         for (int j = 0; j < 4; ++j) { pa[j] = vd[j] ? __builtin_amdgcn_exp2f(sc[j] - mref) : 0.f; pb[j] = vd[4 + j] ? __builtin_amdgcn_exp2f(sc[4 + j] - mref) : 0.f; ps += pa[j] + pb[j]; }
;     }
;     st.l += ps;
;     const u32x2 pw = pack8_fp8(pa, pb);
.LBB0_1012:
	v_lshl_add_u64 v[246:247], v[204:205], 0, v[120:121]
	global_load_dwordx4 v[138:141], v[246:247], off
	global_load_dwordx4 v[142:145], v[246:247], off offset:1024
	global_load_dwordx4 v[146:149], v[246:247], off offset:2048
	global_load_dwordx4 v[150:153], v[246:247], off offset:3072
	v_lshl_add_u64 v[244:245], v[202:203], 0, v[120:121]
	global_load_dwordx4 v[90:93], v[244:245], off
	global_load_dwordx4 v[94:97], v[244:245], off offset:1024
	global_load_dwordx4 v[98:101], v[244:245], off offset:2048
	global_load_dwordx4 v[102:105], v[244:245], off offset:3072
	s_waitcnt vmcnt(20)
	v_mfma_f32_16x16x32_fp8_fp8 v[36:39], v[154:155], v[78:79], 0
	v_add_u32_e32 v0, s66, v210
	v_cmp_ge_i32_e32 vcc, v0, v35
	v_cmp_le_i32_e64 s[10:11], v0, v132
	v_mfma_f32_16x16x32_fp8_fp8 v[36:39], v[156:157], v[80:81], v[36:39]
	s_and_b64 s[16:17], vcc, s[10:11]
	v_add_u32_e32 v45, 1, v0
	v_cmp_ge_i32_e32 vcc, v45, v35
	v_mfma_f32_16x16x32_fp8_fp8 v[36:39], v[158:159], v[82:83], v[36:39]
	v_cmp_lt_i32_e64 s[10:11], v0, v132
	s_and_b64 s[12:13], s[10:11], vcc
	v_mfma_f32_16x16x32_fp8_fp8 v[40:43], v[162:163], v[78:79], 0
	v_mfma_f32_16x16x32_fp8_fp8 v[36:39], v[160:161], v[84:85], v[36:39]
	v_mfma_f32_16x16x32_fp8_fp8 v[40:43], v[164:165], v[80:81], v[40:43]
	v_mfma_f32_16x16x32_fp8_fp8 v[40:43], v[166:167], v[82:83], v[40:43]
	s_nop 3
	v_max_f32_e32 v44, v36, v36
	v_max_f32_e32 v44, 0xf149f2ca, v44
	v_cndmask_b32_e64 v44, v220, v44, s[16:17]
	v_max_f32_e32 v45, v37, v37
	v_max_f32_e32 v45, v44, v45
	v_cndmask_b32_e64 v44, v44, v45, s[12:13]
	v_add_u32_e32 v45, 2, v0
	v_cmp_ge_i32_e32 vcc, v45, v35
	v_cmp_le_i32_e64 s[10:11], v45, v132
	v_max_f32_e32 v45, v38, v38
	v_max_f32_e32 v45, v44, v45
	s_and_b64 s[14:15], vcc, s[10:11]
	v_mfma_f32_16x16x32_fp8_fp8 v[40:43], v[168:169], v[84:85], v[40:43]
	v_cndmask_b32_e64 v44, v44, v45, s[14:15]
	v_add_u32_e32 v45, 3, v0
	v_cmp_ge_i32_e32 vcc, v45, v35
	v_cmp_le_i32_e64 s[10:11], v45, v132
	v_max_f32_e32 v45, v39, v39
	v_max_f32_e32 v45, v44, v45
	s_and_b64 s[10:11], vcc, s[10:11]
	v_cndmask_b32_e64 v44, v44, v45, s[10:11]
	v_add_u32_e32 v45, 16, v0
	v_cmp_ge_i32_e32 vcc, v45, v35
	v_cmp_le_i32_e64 s[18:19], v45, v132
	v_max_f32_e32 v45, v40, v40
	v_max_f32_e32 v45, v44, v45
	s_and_b64 s[24:25], vcc, s[18:19]
	v_cndmask_b32_e64 v44, v44, v45, s[24:25]
	v_add_u32_e32 v45, 17, v0
	v_cmp_ge_i32_e32 vcc, v45, v35
	v_cmp_le_i32_e64 s[18:19], v45, v132
	v_max_f32_e32 v45, v44, v44
	v_max_f32_e32 v46, v41, v41
	v_max_f32_e32 v45, v45, v46
	s_and_b64 s[20:21], vcc, s[18:19]
	v_cndmask_b32_e64 v44, v44, v45, s[20:21]
	v_add_u32_e32 v45, 18, v0
	v_cmp_ge_i32_e32 vcc, v45, v35
	v_cmp_le_i32_e64 s[18:19], v45, v132
	v_max_f32_e32 v45, v44, v44
	v_max_f32_e32 v46, v42, v42
	v_max_f32_e32 v45, v45, v46
	s_and_b64 s[22:23], vcc, s[18:19]
	v_cndmask_b32_e64 v44, v44, v45, s[22:23]
	v_add_u32_e32 v0, 19, v0
	v_cmp_ge_i32_e32 vcc, v0, v35
	v_cmp_le_i32_e64 s[18:19], v0, v132
	v_max_f32_e32 v0, v44, v44
	v_max_f32_e32 v45, v43, v43
	v_max_f32_e32 v0, v0, v45
	s_and_b64 s[18:19], vcc, s[18:19]
	v_cndmask_b32_e64 v0, v44, v0, s[18:19]
	v_cmp_gt_f32_e32 vcc, v0, v133
	s_cbranch_vccz .LBB0_1014
	ds_bpermute_b32 v44, v225, v0
	v_max_f32_e32 v0, v0, v0
	s_waitcnt lgkmcnt(0)
	v_max_f32_e32 v44, v44, v44
	v_max_f32_e32 v0, v0, v44
	ds_bpermute_b32 v44, v224, v0
	s_waitcnt lgkmcnt(0)
	v_max3_f32 v44, v228, v0, v44
	v_sub_f32_e32 v0, v228, v44
	v_exp_f32_e32 v0, v0
	v_mov_b32_e32 v228, v44
	v_mul_f32_e32 v34, v34, v0
	v_pk_mul_f32 v[8:9], v[8:9], v[0:1] op_sel_hi:[1,0]
	v_pk_mul_f32 v[6:7], v[6:7], v[0:1] op_sel_hi:[1,0]
	v_pk_mul_f32 v[12:13], v[12:13], v[0:1] op_sel_hi:[1,0]
	v_pk_mul_f32 v[10:11], v[10:11], v[0:1] op_sel_hi:[1,0]
	v_pk_mul_f32 v[16:17], v[16:17], v[0:1] op_sel_hi:[1,0]
	v_pk_mul_f32 v[14:15], v[14:15], v[0:1] op_sel_hi:[1,0]
	v_pk_mul_f32 v[20:21], v[20:21], v[0:1] op_sel_hi:[1,0]
	v_pk_mul_f32 v[18:19], v[18:19], v[0:1] op_sel_hi:[1,0]
	v_pk_mul_f32 v[24:25], v[24:25], v[0:1] op_sel_hi:[1,0]
	v_pk_mul_f32 v[22:23], v[22:23], v[0:1] op_sel_hi:[1,0]
	v_pk_mul_f32 v[28:29], v[28:29], v[0:1] op_sel_hi:[1,0]
	v_pk_mul_f32 v[26:27], v[26:27], v[0:1] op_sel_hi:[1,0]
	v_pk_mul_f32 v[32:33], v[32:33], v[0:1] op_sel_hi:[1,0]
	v_pk_mul_f32 v[30:31], v[30:31], v[0:1] op_sel_hi:[1,0]
	v_pk_mul_f32 v[4:5], v[4:5], v[0:1] op_sel_hi:[1,0]
	v_pk_mul_f32 v[2:3], v[2:3], v[0:1] op_sel_hi:[1,0]
.LBB0_1014:
	v_add_f32_e32 v0, -4.0, v228
	v_sub_f32_e32 v36, v36, v0
	v_exp_f32_e32 v36, v36
	v_sub_f32_e32 v40, v40, v0
	v_exp_f32_e32 v40, v40
	v_sub_f32_e32 v38, v38, v0
	v_cndmask_b32_e64 v56, 0, v36, s[16:17]
	v_sub_f32_e32 v36, v37, v0
	v_exp_f32_e32 v36, v36
	v_sub_f32_e32 v37, v41, v0
	v_exp_f32_e32 v37, v37
	v_cndmask_b32_e64 v57, 0, v40, s[24:25]
	v_sub_f32_e32 v40, v42, v0
	v_cndmask_b32_e64 v58, 0, v36, s[12:13]
	v_sub_f32_e32 v36, v39, v0
	v_sub_f32_e32 v0, v43, v0
	v_exp_f32_e32 v38, v38
	v_exp_f32_e32 v40, v40
	v_cndmask_b32_e64 v59, 0, v37, s[20:21]
	v_exp_f32_e32 v36, v36
	v_exp_f32_e32 v0, v0
	v_mov_b32_e32 v64, v1
	v_mov_b32_e32 v65, v1
	v_cvt_pk_fp8_f32 v64, v56, v58
	v_cvt_pk_fp8_f32 v65, v57, v59
	v_cndmask_b32_e64 v60, 0, v38, s[14:15]
	v_cndmask_b32_e64 v61, 0, v40, s[22:23]
	v_cndmask_b32_e64 v66, 0, v36, s[10:11]
	v_cndmask_b32_e64 v0, 0, v0, s[18:19]
	v_cvt_pk_fp8_f32 v64, v60, v66 op_sel:[0,0,1]
	v_cvt_pk_fp8_f32 v65, v61, v0 op_sel:[0,0,1]
	v_add_f32_e32 v0, v66, v0
	v_mov_b32_e32 v227, v228
	s_waitcnt vmcnt(19)
	v_mfma_f32_16x16x32_fp8_fp8 v[36:39], v[106:107], v[64:65], v[6:9]
	s_nop 2
	v_add_f32_e32 v6, v56, v57
	v_add_f32_e32 v6, 0, v6
	v_add_f32_e32 v7, v58, v59
	v_mfma_f32_16x16x32_fp8_fp8 v[40:43], v[108:109], v[64:65], v[10:13]
	v_add_f32_e32 v6, v7, v6
	v_add_f32_e32 v7, v60, v61
	v_add_f32_e32 v6, v7, v6
	s_waitcnt vmcnt(18)
	v_mfma_f32_16x16x32_fp8_fp8 v[44:47], v[110:111], v[64:65], v[14:17]
	v_add_f32_e32 v0, v0, v6
	v_add_f32_e32 v229, v34, v0
	v_mfma_f32_16x16x32_fp8_fp8 v[48:51], v[112:113], v[64:65], v[18:21]
	s_waitcnt vmcnt(17)
	v_mfma_f32_16x16x32_fp8_fp8 v[52:55], v[114:115], v[64:65], v[22:25]
	v_mfma_f32_16x16x32_fp8_fp8 v[56:59], v[116:117], v[64:65], v[26:29]
	s_waitcnt vmcnt(16)
	v_mfma_f32_16x16x32_fp8_fp8 v[60:63], v[134:135], v[64:65], v[30:33]
	v_mfma_f32_16x16x32_fp8_fp8 v[64:67], v[136:137], v[64:65], v[2:5]
	s_cmp_gt_i32 s55, s27
	s_mov_b64 s[10:11], -1
	s_cbranch_scc1 .LBB0_994
; template <bool SLC, bool NOMASK> ...
;     const int kq = lane >> 4;
;     const int pos0 = SLC ? (dcur & 0xfffff) : dcur;
;     const int lo = SLC ? ((((dcur >> 20) == qi) | ((dcur >> 20) == 4)) ? 0 : (1 << 30)) : lo_in;
;     load_frag8(nxt, KF, VF, SLC ? (dnext & 0xfffff) : dnext, lane);
;     f32x4 sa[2] = {(f32x4){0.f, 0.f, 0.f, 0.f}, (f32x4){0.f, 0.f, 0.f, 0.f}};
; #pragma unroll
;     for (int T = 0; T < 2; ++T)
; #pragma unroll
;         for (int s2 = 0; s2 < 4; ++s2) sa[T] = __builtin_amdgcn_mfma_f32_16x16x32_fp8_fp8(cur.k[T][s2], qf[s2], sa[T], 0, 0, 0);
;     float sc[8]; bool vd[8]; float mx = -1e30f;
;     const bool act = lo == 0 || !SLC;
;     if (NOMASK) {
; #pragma unroll
;         for (int j = 0; j < 8; ++j) { sc[j] = sa[j >> 2][j & 3]; vd[j] = act; }
;         mx = fmaxf(fmaxf(fmaxf(sc[0], sc[1]), fmaxf(sc[2], sc[3])), fmaxf(fmaxf(sc[4], sc[5]), fmaxf(sc[6], sc[7])));
;         mx = act ? mx : -1e30f;
;     } else {
; #pragma unroll
;         for (int T = 0; T < 2; ++T)
; #pragma unroll
;             for (int r = 0; r < 4; ++r) { const int p = pos0 + 16 * T + 4 * kq + r; const bool v = (p >= lo) & (p <= hi); const float x = sa[T][r];
;                 sc[4 * T + r] = x; vd[4 * T + r] = v; mx = v ? fmaxf(mx, x) : mx; }
;     }
;     if (__builtin_amdgcn_ballot_w64(mx > st.m + 4.f) != 0ull) {
;         mx = fmaxf(mx, __shfl_xor(mx, 16)); mx = fmaxf(mx, __shfl_xor(mx, 32));
;         const float mn = fmaxf(st.m, mx), alpha = __builtin_amdgcn_exp2f(st.m - mn); st.m = mn; st.l *= alpha;
; #pragma unroll
;         for (int j = 0; j < 8; ++j) st.o[j] = st.o[j] * alpha;
;     }
;     f32x4 pa, pb; float ps = 0.f;
;     const float mref = st.m - 4.f;
;     if (NOMASK) {
; #pragma unroll
;         for (int j = 0; j < 4; ++j) { pa[j] = __builtin_amdgcn_exp2f(sc[j] - mref); pb[j] = __builtin_amdgcn_exp2f(sc[4 + j] - mref); }
;         if (SLC) {
; #pragma unroll
;             for (int j = 0; j < 4; ++j) { pa[j] = act ? pa[j] : 0.f; pb[j] = act ? pb[j] : 0.f; }
;         }
; #pragma unroll
;         for (int j = 0; j < 4; ++j) ps += pa[j] + pb[j];
;     } else {
; #pragma unroll
;         for (int j = 0; j < 4; ++j) { pa[j] = vd[j] ? __builtin_amdgcn_exp2f(sc[j] - mref) : 0.f; pb[j] = vd[4 + j] ? __builtin_amdgcn_exp2f(sc[4 + j] - mref) : 0.f; ps += pa[j] + pb[j]; }
;     }
;     st.l += ps;
;     const u32x2 pw = pack8_fp8(pa, pb);
.LBB0_1015:
	s_cmp_lt_i32 s57, s54
	s_cselect_b64 s[10:11], -1, 0
	s_or_b32 s12, s57, 31
	s_cmp_gt_i32 s12, s90
	s_cselect_b64 s[12:13], -1, 0
	s_or_b64 s[10:11], s[10:11], s[12:13]
	s_and_b64 s[10:11], s[10:11], exec
	s_cselect_b32 s10, 0, 2.0
	s_add_i32 s56, s56, 4
	s_or_b32 s14, s10, s57
	s_min_i32 s10, s56, s27
	s_add_i32 s12, s10, s26
	s_lshl_b32 s43, s12, 5
	s_and_b32 s10, s43, 0x3fffffe0
	s_lshr_b32 s50, s10, 4
	s_lshl_b64 s[10:11], s[50:51], 11
	s_and_b32 s50, s12, 0x1ffffff
	s_lshl_b64 s[12:13], s[50:51], 12
	s_cmp_lt_u32 s14, 2.0
	v_lshl_add_u64 v[204:205], v[86:87], 0, s[10:11]
	v_lshl_add_u64 v[202:203], v[88:89], 0, s[12:13]
	s_mov_b64 s[10:11], -1
	v_add_f32_e32 v228, 4.0, v227
	s_cbranch_scc1 .LBB0_1019
	v_lshl_add_u64 v[246:247], v[204:205], 0, v[120:121]
	global_load_dwordx4 v[154:157], v[246:247], off
	global_load_dwordx4 v[158:161], v[246:247], off offset:1024
	global_load_dwordx4 v[162:165], v[246:247], off offset:2048
	global_load_dwordx4 v[166:169], v[246:247], off offset:3072
	v_lshl_add_u64 v[244:245], v[202:203], 0, v[120:121]
	global_load_dwordx4 v[106:109], v[244:245], off
	global_load_dwordx4 v[110:113], v[244:245], off offset:1024
	global_load_dwordx4 v[114:117], v[244:245], off offset:2048
	global_load_dwordx4 v[134:137], v[244:245], off offset:3072
	s_waitcnt vmcnt(20)
	v_mfma_f32_16x16x32_fp8_fp8 v[2:5], v[186:187], v[78:79], 0
	v_mov_b64_e32 v[74:75], v[66:67]
	v_mov_b64_e32 v[70:71], v[62:63]
	v_mov_b64_e32 v[30:31], v[56:57]
	v_mfma_f32_16x16x32_fp8_fp8 v[6:9], v[194:195], v[78:79], 0
	v_mov_b64_e32 v[26:27], v[52:53]
	v_mov_b64_e32 v[22:23], v[48:49]
	v_mov_b64_e32 v[18:19], v[44:45]
	v_mfma_f32_16x16x32_fp8_fp8 v[2:5], v[188:189], v[80:81], v[2:5]
	v_mov_b64_e32 v[14:15], v[40:41]
	v_mov_b32_e32 v133, v227
	v_mov_b64_e32 v[72:73], v[64:65]
	v_mfma_f32_16x16x32_fp8_fp8 v[6:9], v[196:197], v[80:81], v[6:9]
	v_mov_b64_e32 v[68:69], v[60:61]
	v_mov_b64_e32 v[32:33], v[58:59]
	v_mov_b64_e32 v[28:29], v[54:55]
	v_mfma_f32_16x16x32_fp8_fp8 v[2:5], v[190:191], v[82:83], v[2:5]
	v_mov_b64_e32 v[24:25], v[50:51]
	v_mov_b64_e32 v[20:21], v[46:47]
	v_mov_b64_e32 v[16:17], v[42:43]
	v_mfma_f32_16x16x32_fp8_fp8 v[6:9], v[198:199], v[82:83], v[6:9]
	v_mov_b32_e32 v34, v229
	v_mfma_f32_16x16x32_fp8_fp8 v[2:5], v[192:193], v[84:85], v[2:5]
	v_mfma_f32_16x16x32_fp8_fp8 v[6:9], v[200:201], v[84:85], v[6:9]
	s_nop 5
	v_max_f32_e32 v0, v3, v3
	v_max_f32_e32 v10, v2, v2
	v_max_f32_e32 v0, v10, v0
	v_max_f32_e32 v10, v5, v5
	v_max_f32_e32 v11, v4, v4
	v_max_f32_e32 v10, v11, v10
	v_max_f32_e32 v11, v9, v9
	v_max_f32_e32 v12, v8, v8
	v_max_f32_e32 v11, v12, v11
	v_max3_f32 v11, v6, v7, v11
	v_max3_f32 v0, v0, v10, v11
	v_mov_b64_e32 v[10:11], v[36:37]
	v_cmp_gt_f32_e32 vcc, v0, v228
	v_mov_b64_e32 v[12:13], v[38:39]
	s_cbranch_vccz .LBB0_1018
	ds_bpermute_b32 v10, v225, v0
	v_max_f32_e32 v0, v0, v0
	s_waitcnt lgkmcnt(0)
	v_max_f32_e32 v10, v10, v10
	v_max_f32_e32 v0, v0, v10
	ds_bpermute_b32 v10, v224, v0
	s_waitcnt lgkmcnt(0)
	v_max3_f32 v133, v227, v0, v10
	v_sub_f32_e32 v0, v227, v133
	v_exp_f32_e32 v0, v0
	s_nop 0
	v_mul_f32_e32 v34, v229, v0
	v_pk_mul_f32 v[12:13], v[38:39], v[0:1] op_sel_hi:[1,0]
	v_pk_mul_f32 v[10:11], v[36:37], v[0:1] op_sel_hi:[1,0]
	v_pk_mul_f32 v[16:17], v[42:43], v[0:1] op_sel_hi:[1,0]
	v_pk_mul_f32 v[14:15], v[40:41], v[0:1] op_sel_hi:[1,0]
	v_pk_mul_f32 v[20:21], v[46:47], v[0:1] op_sel_hi:[1,0]
	v_pk_mul_f32 v[18:19], v[44:45], v[0:1] op_sel_hi:[1,0]
	v_pk_mul_f32 v[24:25], v[50:51], v[0:1] op_sel_hi:[1,0]
	v_pk_mul_f32 v[22:23], v[48:49], v[0:1] op_sel_hi:[1,0]
	v_pk_mul_f32 v[28:29], v[54:55], v[0:1] op_sel_hi:[1,0]
	v_pk_mul_f32 v[26:27], v[52:53], v[0:1] op_sel_hi:[1,0]
	v_pk_mul_f32 v[32:33], v[58:59], v[0:1] op_sel_hi:[1,0]
	v_pk_mul_f32 v[30:31], v[56:57], v[0:1] op_sel_hi:[1,0]
	v_pk_mul_f32 v[70:71], v[62:63], v[0:1] op_sel_hi:[1,0]
	v_pk_mul_f32 v[68:69], v[60:61], v[0:1] op_sel_hi:[1,0]
	v_pk_mul_f32 v[74:75], v[66:67], v[0:1] op_sel_hi:[1,0]
	v_pk_mul_f32 v[72:73], v[64:65], v[0:1] op_sel_hi:[1,0]
.LBB0_1018:
	v_add_f32_e32 v230, -4.0, v133
	v_sub_f32_e32 v0, v2, v230
	v_exp_f32_e32 v231, v0
	v_sub_f32_e32 v0, v6, v230
	v_exp_f32_e32 v234, v0
	v_sub_f32_e32 v0, v3, v230
	v_exp_f32_e32 v2, v0
	v_sub_f32_e32 v0, v7, v230
	v_exp_f32_e32 v0, v0
	v_sub_f32_e32 v3, v4, v230
	v_exp_f32_e32 v235, v3
	v_sub_f32_e32 v3, v8, v230
	v_exp_f32_e32 v236, v3
	v_sub_f32_e32 v3, v5, v230
	v_exp_f32_e32 v4, v3
	v_sub_f32_e32 v3, v9, v230
	v_mov_b32_e32 v232, v1
	v_mov_b32_e32 v233, v1
	v_exp_f32_e32 v230, v3
	v_cvt_pk_fp8_f32 v232, v231, v2
	v_cvt_pk_fp8_f32 v233, v234, v0
	v_add_f32_e32 v3, v231, v234
	v_pk_add_f32 v[2:3], v[2:3], v[0:1]
	v_cvt_pk_fp8_f32 v232, v235, v4 op_sel:[0,0,1]
	v_cvt_pk_fp8_f32 v233, v236, v230 op_sel:[0,0,1]
	v_pk_add_f32 v[2:3], v[2:3], v[2:3] op_sel_hi:[0,1]
	v_add_f32_e32 v5, v235, v236
	v_mov_b32_e32 v231, v3
	v_pk_add_f32 v[2:3], v[4:5], v[230:231]
	s_waitcnt vmcnt(19)
	v_mfma_f32_16x16x32_fp8_fp8 v[6:9], v[170:171], v[232:233], v[10:13]
	v_add_f32_e32 v0, v2, v3
	v_add_f32_e32 v34, v0, v34
	s_mov_b64 s[10:11], 0
	v_mfma_f32_16x16x32_fp8_fp8 v[10:13], v[172:173], v[232:233], v[14:17]
	s_waitcnt vmcnt(18)
	v_mfma_f32_16x16x32_fp8_fp8 v[14:17], v[174:175], v[232:233], v[18:21]
	v_mfma_f32_16x16x32_fp8_fp8 v[18:21], v[176:177], v[232:233], v[22:25]
	s_waitcnt vmcnt(17)
	v_mfma_f32_16x16x32_fp8_fp8 v[22:25], v[178:179], v[232:233], v[26:29]
	v_mfma_f32_16x16x32_fp8_fp8 v[26:29], v[180:181], v[232:233], v[30:33]
	s_waitcnt vmcnt(16)
	v_mfma_f32_16x16x32_fp8_fp8 v[30:33], v[182:183], v[232:233], v[68:71]
	v_mfma_f32_16x16x32_fp8_fp8 v[2:5], v[184:185], v[232:233], v[72:75]
; template <bool SLC, bool NOMASK> ...
;     const int kq = lane >> 4;
;     const int pos0 = SLC ? (dcur & 0xfffff) : dcur;
;     const int lo = SLC ? ((((dcur >> 20) == qi) | ((dcur >> 20) == 4)) ? 0 : (1 << 30)) : lo_in;
;     load_frag8(nxt, KF, VF, SLC ? (dnext & 0xfffff) : dnext, lane);
;     f32x4 sa[2] = {(f32x4){0.f, 0.f, 0.f, 0.f}, (f32x4){0.f, 0.f, 0.f, 0.f}};
; #pragma unroll
;     for (int T = 0; T < 2; ++T)
; #pragma unroll
;         for (int s2 = 0; s2 < 4; ++s2) sa[T] = __builtin_amdgcn_mfma_f32_16x16x32_fp8_fp8(cur.k[T][s2], qf[s2], sa[T], 0, 0, 0);
;     float sc[8]; bool vd[8]; float mx = -1e30f;
;     const bool act = lo == 0 || !SLC;
;     if (NOMASK) {
; #pragma unroll
;         for (int j = 0; j < 8; ++j) { sc[j] = sa[j >> 2][j & 3]; vd[j] = act; }
;         mx = fmaxf(fmaxf(fmaxf(sc[0], sc[1]), fmaxf(sc[2], sc[3])), fmaxf(fmaxf(sc[4], sc[5]), fmaxf(sc[6], sc[7])));
;         mx = act ? mx : -1e30f;
;     } else {
; #pragma unroll
;         for (int T = 0; T < 2; ++T)
; #pragma unroll
;             for (int r = 0; r < 4; ++r) { const int p = pos0 + 16 * T + 4 * kq + r; const bool v = (p >= lo) & (p <= hi); const float x = sa[T][r];
;                 sc[4 * T + r] = x; vd[4 * T + r] = v; mx = v ? fmaxf(mx, x) : mx; }
;     }
;     if (__builtin_amdgcn_ballot_w64(mx > st.m + 4.f) != 0ull) {
;         mx = fmaxf(mx, __shfl_xor(mx, 16)); mx = fmaxf(mx, __shfl_xor(mx, 32));
;         const float mn = fmaxf(st.m, mx), alpha = __builtin_amdgcn_exp2f(st.m - mn); st.m = mn; st.l *= alpha;
; #pragma unroll
;         for (int j = 0; j < 8; ++j) st.o[j] = st.o[j] * alpha;
;     }
;     f32x4 pa, pb; float ps = 0.f;
;     const float mref = st.m - 4.f;
;     if (NOMASK) {
; #pragma unroll
;         for (int j = 0; j < 4; ++j) { pa[j] = __builtin_amdgcn_exp2f(sc[j] - mref); pb[j] = __builtin_amdgcn_exp2f(sc[4 + j] - mref); }
;         if (SLC) {
; #pragma unroll
;             for (int j = 0; j < 4; ++j) { pa[j] = act ? pa[j] : 0.f; pb[j] = act ? pb[j] : 0.f; }
;         }
; #pragma unroll
;         for (int j = 0; j < 4; ++j) ps += pa[j] + pb[j];
;     } else {
; #pragma unroll
;         for (int j = 0; j < 4; ++j) { pa[j] = vd[j] ? __builtin_amdgcn_exp2f(sc[j] - mref) : 0.f; pb[j] = vd[4 + j] ? __builtin_amdgcn_exp2f(sc[4 + j] - mref) : 0.f; ps += pa[j] + pb[j]; }
;     }
;     st.l += ps;
;     const u32x2 pw = pack8_fp8(pa, pb);
.LBB0_1019:
	s_and_b64 vcc, exec, s[10:11]
	s_cbranch_vccz .LBB0_1023
	v_lshl_add_u64 v[246:247], v[204:205], 0, v[120:121]
	global_load_dwordx4 v[154:157], v[246:247], off
	global_load_dwordx4 v[158:161], v[246:247], off offset:1024
	global_load_dwordx4 v[162:165], v[246:247], off offset:2048
	global_load_dwordx4 v[166:169], v[246:247], off offset:3072
	v_lshl_add_u64 v[244:245], v[202:203], 0, v[120:121]
	global_load_dwordx4 v[106:109], v[244:245], off
	global_load_dwordx4 v[110:113], v[244:245], off offset:1024
	global_load_dwordx4 v[114:117], v[244:245], off offset:2048
	global_load_dwordx4 v[134:137], v[244:245], off offset:3072
	s_waitcnt vmcnt(20)
	v_mfma_f32_16x16x32_fp8_fp8 v[2:5], v[186:187], v[78:79], 0
	v_or_b32_e32 v0, s57, v210
	v_cmp_ge_i32_e32 vcc, v0, v35
	v_cmp_le_i32_e64 s[10:11], v0, v132
	v_mfma_f32_16x16x32_fp8_fp8 v[2:5], v[188:189], v[80:81], v[2:5]
	s_and_b64 s[16:17], vcc, s[10:11]
	v_or_b32_e32 v11, 1, v0
	v_cmp_ge_i32_e32 vcc, v11, v35
	v_mfma_f32_16x16x32_fp8_fp8 v[2:5], v[190:191], v[82:83], v[2:5]
	v_cmp_lt_i32_e64 s[10:11], v0, v132
	s_and_b64 s[12:13], s[10:11], vcc
	v_mfma_f32_16x16x32_fp8_fp8 v[6:9], v[194:195], v[78:79], 0
	v_mfma_f32_16x16x32_fp8_fp8 v[2:5], v[192:193], v[84:85], v[2:5]
	v_mfma_f32_16x16x32_fp8_fp8 v[6:9], v[196:197], v[80:81], v[6:9]
	v_mfma_f32_16x16x32_fp8_fp8 v[6:9], v[198:199], v[82:83], v[6:9]
	s_nop 3
	v_max_f32_e32 v10, v2, v2
	v_max_f32_e32 v10, 0xf149f2ca, v10
	v_cndmask_b32_e64 v10, v220, v10, s[16:17]
	v_max_f32_e32 v11, v3, v3
	v_max_f32_e32 v11, v10, v11
	v_cndmask_b32_e64 v10, v10, v11, s[12:13]
	v_or_b32_e32 v11, 2, v0
	v_cmp_ge_i32_e32 vcc, v11, v35
	v_cmp_le_i32_e64 s[10:11], v11, v132
	v_max_f32_e32 v11, v4, v4
	v_max_f32_e32 v11, v10, v11
	s_and_b64 s[14:15], vcc, s[10:11]
	v_mfma_f32_16x16x32_fp8_fp8 v[6:9], v[200:201], v[84:85], v[6:9]
	v_cndmask_b32_e64 v10, v10, v11, s[14:15]
	v_or_b32_e32 v11, 3, v0
	v_cmp_ge_i32_e32 vcc, v11, v35
	v_cmp_le_i32_e64 s[10:11], v11, v132
	v_max_f32_e32 v11, v5, v5
	v_max_f32_e32 v11, v10, v11
	s_and_b64 s[10:11], vcc, s[10:11]
	v_cndmask_b32_e64 v10, v10, v11, s[10:11]
	v_or_b32_e32 v11, 16, v0
	v_cmp_ge_i32_e32 vcc, v11, v35
	v_cmp_le_i32_e64 s[18:19], v11, v132
	v_max_f32_e32 v11, v6, v6
	v_max_f32_e32 v11, v10, v11
	s_and_b64 s[24:25], vcc, s[18:19]
	v_cndmask_b32_e64 v10, v10, v11, s[24:25]
	v_or_b32_e32 v11, 17, v0
	v_cmp_ge_i32_e32 vcc, v11, v35
	v_cmp_le_i32_e64 s[18:19], v11, v132
	v_max_f32_e32 v11, v10, v10
	v_max_f32_e32 v12, v7, v7
	v_max_f32_e32 v11, v11, v12
	s_and_b64 s[20:21], vcc, s[18:19]
	v_cndmask_b32_e64 v10, v10, v11, s[20:21]
	v_or_b32_e32 v11, 18, v0
	v_cmp_ge_i32_e32 vcc, v11, v35
	v_cmp_le_i32_e64 s[18:19], v11, v132
	v_max_f32_e32 v11, v10, v10
	v_max_f32_e32 v12, v8, v8
	v_max_f32_e32 v11, v11, v12
	s_and_b64 s[22:23], vcc, s[18:19]
	v_cndmask_b32_e64 v10, v10, v11, s[22:23]
	v_or_b32_e32 v0, 19, v0
	v_cmp_ge_i32_e32 vcc, v0, v35
	v_cmp_le_i32_e64 s[18:19], v0, v132
	v_max_f32_e32 v0, v10, v10
	v_max_f32_e32 v11, v9, v9
	v_max_f32_e32 v0, v0, v11
	s_and_b64 s[18:19], vcc, s[18:19]
	v_cndmask_b32_e64 v0, v10, v0, s[18:19]
	v_cmp_gt_f32_e32 vcc, v0, v228
	s_cbranch_vccz .LBB0_1022
	ds_bpermute_b32 v10, v225, v0
	v_max_f32_e32 v0, v0, v0
	s_waitcnt lgkmcnt(0)
	v_max_f32_e32 v10, v10, v10
	v_max_f32_e32 v0, v0, v10
	ds_bpermute_b32 v10, v224, v0
	s_waitcnt lgkmcnt(0)
	v_max3_f32 v10, v227, v0, v10
	v_sub_f32_e32 v0, v227, v10
	v_exp_f32_e32 v0, v0
	v_mov_b32_e32 v227, v10
	v_mul_f32_e32 v229, v229, v0
	v_pk_mul_f32 v[38:39], v[38:39], v[0:1] op_sel_hi:[1,0]
	v_pk_mul_f32 v[36:37], v[36:37], v[0:1] op_sel_hi:[1,0]
	v_pk_mul_f32 v[42:43], v[42:43], v[0:1] op_sel_hi:[1,0]
	v_pk_mul_f32 v[40:41], v[40:41], v[0:1] op_sel_hi:[1,0]
	v_pk_mul_f32 v[46:47], v[46:47], v[0:1] op_sel_hi:[1,0]
	v_pk_mul_f32 v[44:45], v[44:45], v[0:1] op_sel_hi:[1,0]
	v_pk_mul_f32 v[50:51], v[50:51], v[0:1] op_sel_hi:[1,0]
	v_pk_mul_f32 v[48:49], v[48:49], v[0:1] op_sel_hi:[1,0]
	v_pk_mul_f32 v[54:55], v[54:55], v[0:1] op_sel_hi:[1,0]
	v_pk_mul_f32 v[52:53], v[52:53], v[0:1] op_sel_hi:[1,0]
	v_pk_mul_f32 v[58:59], v[58:59], v[0:1] op_sel_hi:[1,0]
	v_pk_mul_f32 v[56:57], v[56:57], v[0:1] op_sel_hi:[1,0]
	v_pk_mul_f32 v[62:63], v[62:63], v[0:1] op_sel_hi:[1,0]
	v_pk_mul_f32 v[60:61], v[60:61], v[0:1] op_sel_hi:[1,0]
	v_pk_mul_f32 v[66:67], v[66:67], v[0:1] op_sel_hi:[1,0]
	v_pk_mul_f32 v[64:65], v[64:65], v[0:1] op_sel_hi:[1,0]
.LBB0_1022:
	v_add_f32_e32 v0, -4.0, v227
	v_sub_f32_e32 v2, v2, v0
	v_exp_f32_e32 v2, v2
	v_sub_f32_e32 v6, v6, v0
	v_exp_f32_e32 v6, v6
	v_sub_f32_e32 v4, v4, v0
	v_cndmask_b32_e64 v26, 0, v2, s[16:17]
	v_sub_f32_e32 v2, v3, v0
	v_exp_f32_e32 v2, v2
	v_sub_f32_e32 v3, v7, v0
	v_exp_f32_e32 v3, v3
	v_cndmask_b32_e64 v27, 0, v6, s[24:25]
	v_sub_f32_e32 v6, v8, v0
	v_cndmask_b32_e64 v28, 0, v2, s[12:13]
	v_sub_f32_e32 v2, v5, v0
	v_sub_f32_e32 v0, v9, v0
	v_exp_f32_e32 v4, v4
	v_exp_f32_e32 v6, v6
	v_cndmask_b32_e64 v29, 0, v3, s[20:21]
	v_exp_f32_e32 v5, v2
	v_exp_f32_e32 v0, v0
	v_mov_b32_e32 v2, v1
	v_mov_b32_e32 v3, v1
	v_cvt_pk_fp8_f32 v2, v26, v28
	v_cvt_pk_fp8_f32 v3, v27, v29
	v_cndmask_b32_e64 v4, 0, v4, s[14:15]
	v_cndmask_b32_e64 v30, 0, v6, s[22:23]
	v_cndmask_b32_e64 v5, 0, v5, s[10:11]
	v_cndmask_b32_e64 v0, 0, v0, s[18:19]
	v_cvt_pk_fp8_f32 v2, v4, v5 op_sel:[0,0,1]
	v_cvt_pk_fp8_f32 v3, v30, v0 op_sel:[0,0,1]
	v_add_f32_e32 v26, v26, v27
	v_add_f32_e32 v31, 0, v26
	v_add_f32_e32 v32, v28, v29
	v_add_f32_e32 v31, v32, v31
	v_add_f32_e32 v4, v4, v30
	v_add_f32_e32 v4, v4, v31
	v_add_f32_e32 v0, v5, v0
	s_waitcnt vmcnt(19)
	v_mfma_f32_16x16x32_fp8_fp8 v[6:9], v[170:171], v[2:3], v[36:39]
	v_add_f32_e32 v0, v0, v4
	v_add_f32_e32 v34, v229, v0
	v_mov_b32_e32 v133, v227
	v_mfma_f32_16x16x32_fp8_fp8 v[10:13], v[172:173], v[2:3], v[40:43]
	s_waitcnt vmcnt(18)
	v_mfma_f32_16x16x32_fp8_fp8 v[14:17], v[174:175], v[2:3], v[44:47]
	v_mfma_f32_16x16x32_fp8_fp8 v[18:21], v[176:177], v[2:3], v[48:51]
	s_waitcnt vmcnt(17)
	v_mfma_f32_16x16x32_fp8_fp8 v[22:25], v[178:179], v[2:3], v[52:55]
	v_mfma_f32_16x16x32_fp8_fp8 v[26:29], v[180:181], v[2:3], v[56:59]
	s_waitcnt vmcnt(16)
	v_mfma_f32_16x16x32_fp8_fp8 v[30:33], v[182:183], v[2:3], v[60:63]
	v_mfma_f32_16x16x32_fp8_fp8 v[2:5], v[184:185], v[2:3], v[64:67]
